# RMSNorm phases rewritten by hand: modulation vectors hoisted to registers, 4-row double-buffered loads, DPP wave sums, 16-byte stores
# speedup vs baseline: 1.0172x; 1.0172x over previous
.LBB0_277:
	v_readlane_b32 s46, v254, 54
	v_readlane_b32 s40, v254, 34
	v_readlane_b32 s44, v254, 38
	v_readlane_b32 s84, v255, 4
	s_andn2_b64 vcc, exec, s[2:3]
	v_readlane_b32 s47, v254, 55
	v_readlane_b32 s42, v250, 16
	v_readlane_b32 s16, v254, 18
	v_readlane_b32 s41, v254, 35
	v_readlane_b32 s45, v254, 39
	s_mov_b64 s[48:49], 0x200
	s_mov_b64 s[50:51], 0x400
	s_mov_b64 s[56:57], 0x600
	v_readlane_b32 s85, v255, 5
	v_readlane_b32 s86, v255, 6
	v_readlane_b32 s87, v255, 7
	v_readlane_b32 s17, v254, 56
	s_cbranch_vccnz .LBB0_281
	s_cmpk_gt_i32 s52, 0x7fff
	s_mov_b32 s36, s17
	s_cbranch_scc1 .LBB0_281
	v_readlane_b32 s2, v250, 0
	s_cmpk_lg_u32 s2, 0x100
	s_cbranch_scc1 .Lnrm_A_fallback
	v_lshrrev_b32_e32 v0, 6, v222
	v_and_b32_e32 v1, 63, v222
	v_readlane_b32 s4, v254, 48
	v_readfirstlane_b32 s3, v0
	v_readlane_b32 s82, v250, 2
	v_readlane_b32 s83, v250, 3
	s_lshl_b32 s4, s4, 3
	s_add_i32 s4, s4, s3
	s_load_dwordx2 s[18:19], s[82:83], 0x38
	s_mov_b32 s12, s72
	s_mov_b32 s13, s73
	s_lshr_b32 s2, s4, 7
	s_mul_i32 s2, s2, 0x9000
	s_add_u32 s20, s74, s2
	s_addc_u32 s21, s75, 0
	s_add_u32 s88, s20, 0x4000
	s_addc_u32 s89, s21, 0
	s_add_u32 s90, s20, 0x3000
	s_addc_u32 s91, s21, 0
	v_lshlrev_b32_e32 v202, 5, v1
	v_lshlrev_b32_e32 v203, 4, v1
	s_lshl_b32 s11, s4, 16
	s_lshl_b32 s2, s4, 15
	s_add_u32 s48, s74, s2
	s_addc_u32 s49, s75, 0
	s_add_u32 s48, s48, 0x3000000
	s_addc_u32 s49, s49, 0
	s_waitcnt lgkmcnt(0)
	s_and_b32 s13, s13, 0xffff
	s_mov_b32 s14, 0x8000000
	s_mov_b32 s15, 0x20000
	global_load_dwordx4 v[64:67], v202, s[18:19]
	global_load_dwordx4 v[68:71], v202, s[18:19] offset:16
	global_load_dwordx4 v[72:75], v202, s[18:19] offset:2048
	global_load_dwordx4 v[76:79], v202, s[18:19] offset:2064
	global_load_dwordx4 v[80:83], v202, s[88:89]
	global_load_dwordx4 v[84:87], v202, s[88:89] offset:16
	global_load_dwordx4 v[88:91], v202, s[88:89] offset:2048
	global_load_dwordx4 v[92:95], v202, s[88:89] offset:2064
	global_load_dwordx4 v[162:165], v202, s[90:91]
	global_load_dwordx4 v[166:169], v202, s[90:91] offset:16
	global_load_dwordx4 v[170:173], v202, s[90:91] offset:2048
	global_load_dwordx4 v[174:177], v202, s[90:91] offset:2064
	buffer_load_dwordx4 v[0:3], v202, s[12:15], s11 offen sc1
	buffer_load_dwordx4 v[4:7], v202, s[12:15], s11 offen offset:16 sc1
	buffer_load_dwordx4 v[8:11], v202, s[12:15], s11 offen offset:2048 sc1
	buffer_load_dwordx4 v[12:15], v202, s[12:15], s11 offen offset:2064 sc1
	s_add_u32 s11, s11, 0x1000
	buffer_load_dwordx4 v[16:19], v202, s[12:15], s11 offen sc1
	buffer_load_dwordx4 v[20:23], v202, s[12:15], s11 offen offset:16 sc1
	buffer_load_dwordx4 v[24:27], v202, s[12:15], s11 offen offset:2048 sc1
	buffer_load_dwordx4 v[28:31], v202, s[12:15], s11 offen offset:2064 sc1
	s_add_u32 s11, s11, 0x1000
	buffer_load_dwordx4 v[32:35], v202, s[12:15], s11 offen sc1
	buffer_load_dwordx4 v[36:39], v202, s[12:15], s11 offen offset:16 sc1
	buffer_load_dwordx4 v[40:43], v202, s[12:15], s11 offen offset:2048 sc1
	buffer_load_dwordx4 v[44:47], v202, s[12:15], s11 offen offset:2064 sc1
	s_add_u32 s11, s11, 0x1000
	buffer_load_dwordx4 v[48:51], v202, s[12:15], s11 offen sc1
	buffer_load_dwordx4 v[52:55], v202, s[12:15], s11 offen offset:16 sc1
	buffer_load_dwordx4 v[56:59], v202, s[12:15], s11 offen offset:2048 sc1
	buffer_load_dwordx4 v[60:63], v202, s[12:15], s11 offen offset:2064 sc1
	s_add_u32 s11, s11, 0x1000
	buffer_load_dwordx4 v[98:101], v202, s[12:15], s11 offen sc1
	buffer_load_dwordx4 v[102:105], v202, s[12:15], s11 offen offset:16 sc1
	buffer_load_dwordx4 v[106:109], v202, s[12:15], s11 offen offset:2048 sc1
	buffer_load_dwordx4 v[110:113], v202, s[12:15], s11 offen offset:2064 sc1
	s_add_u32 s11, s11, 0x1000
	buffer_load_dwordx4 v[114:117], v202, s[12:15], s11 offen sc1
	buffer_load_dwordx4 v[118:121], v202, s[12:15], s11 offen offset:16 sc1
	buffer_load_dwordx4 v[122:125], v202, s[12:15], s11 offen offset:2048 sc1
	buffer_load_dwordx4 v[126:129], v202, s[12:15], s11 offen offset:2064 sc1
	s_add_u32 s11, s11, 0x1000
	buffer_load_dwordx4 v[130:133], v202, s[12:15], s11 offen sc1
	buffer_load_dwordx4 v[134:137], v202, s[12:15], s11 offen offset:16 sc1
	buffer_load_dwordx4 v[138:141], v202, s[12:15], s11 offen offset:2048 sc1
	buffer_load_dwordx4 v[142:145], v202, s[12:15], s11 offen offset:2064 sc1
	s_add_u32 s11, s11, 0x1000
	buffer_load_dwordx4 v[146:149], v202, s[12:15], s11 offen sc1
	buffer_load_dwordx4 v[150:153], v202, s[12:15], s11 offen offset:16 sc1
	buffer_load_dwordx4 v[154:157], v202, s[12:15], s11 offen offset:2048 sc1
	buffer_load_dwordx4 v[158:161], v202, s[12:15], s11 offen offset:2064 sc1
	s_add_u32 s11, s11, 0x1000
	s_waitcnt vmcnt(16)
	v_pk_add_f32 v[80:81], v[80:81], 1.0 op_sel_hi:[1,0]
	v_pk_add_f32 v[82:83], v[82:83], 1.0 op_sel_hi:[1,0]
	v_pk_add_f32 v[84:85], v[84:85], 1.0 op_sel_hi:[1,0]
	v_pk_add_f32 v[86:87], v[86:87], 1.0 op_sel_hi:[1,0]
	v_pk_add_f32 v[88:89], v[88:89], 1.0 op_sel_hi:[1,0]
	v_pk_add_f32 v[90:91], v[90:91], 1.0 op_sel_hi:[1,0]
	v_pk_add_f32 v[92:93], v[92:93], 1.0 op_sel_hi:[1,0]
	v_pk_add_f32 v[94:95], v[94:95], 1.0 op_sel_hi:[1,0]
	v_mul_f32_e32 v178, v0, v0
	v_mul_f32_e32 v179, v16, v16
	v_mul_f32_e32 v180, v32, v32
	v_mul_f32_e32 v181, v48, v48
	v_fma_f32 v178, v1, v1, v178
	v_fma_f32 v179, v17, v17, v179
	v_fma_f32 v180, v33, v33, v180
	v_fma_f32 v181, v49, v49, v181
	v_fma_f32 v178, v2, v2, v178
	v_fma_f32 v179, v18, v18, v179
	v_fma_f32 v180, v34, v34, v180
	v_fma_f32 v181, v50, v50, v181
	v_fma_f32 v178, v3, v3, v178
	v_fma_f32 v179, v19, v19, v179
	v_fma_f32 v180, v35, v35, v180
	v_fma_f32 v181, v51, v51, v181
	v_fma_f32 v178, v4, v4, v178
	v_fma_f32 v179, v20, v20, v179
	v_fma_f32 v180, v36, v36, v180
	v_fma_f32 v181, v52, v52, v181
	v_fma_f32 v178, v5, v5, v178
	v_fma_f32 v179, v21, v21, v179
	v_fma_f32 v180, v37, v37, v180
	v_fma_f32 v181, v53, v53, v181
	v_fma_f32 v178, v6, v6, v178
	v_fma_f32 v179, v22, v22, v179
	v_fma_f32 v180, v38, v38, v180
	v_fma_f32 v181, v54, v54, v181
	v_fma_f32 v178, v7, v7, v178
	v_fma_f32 v179, v23, v23, v179
	v_fma_f32 v180, v39, v39, v180
	v_fma_f32 v181, v55, v55, v181
	v_fma_f32 v178, v8, v8, v178
	v_fma_f32 v179, v24, v24, v179
	v_fma_f32 v180, v40, v40, v180
	v_fma_f32 v181, v56, v56, v181
	v_fma_f32 v178, v9, v9, v178
	v_fma_f32 v179, v25, v25, v179
	v_fma_f32 v180, v41, v41, v180
	v_fma_f32 v181, v57, v57, v181
	v_fma_f32 v178, v10, v10, v178
	v_fma_f32 v179, v26, v26, v179
	v_fma_f32 v180, v42, v42, v180
	v_fma_f32 v181, v58, v58, v181
	v_fma_f32 v178, v11, v11, v178
	v_fma_f32 v179, v27, v27, v179
	v_fma_f32 v180, v43, v43, v180
	v_fma_f32 v181, v59, v59, v181
	v_fma_f32 v178, v12, v12, v178
	v_fma_f32 v179, v28, v28, v179
	v_fma_f32 v180, v44, v44, v180
	v_fma_f32 v181, v60, v60, v181
	v_fma_f32 v178, v13, v13, v178
	v_fma_f32 v179, v29, v29, v179
	v_fma_f32 v180, v45, v45, v180
	v_fma_f32 v181, v61, v61, v181
	v_fma_f32 v178, v14, v14, v178
	v_fma_f32 v179, v30, v30, v179
	v_fma_f32 v180, v46, v46, v180
	v_fma_f32 v181, v62, v62, v181
	v_fma_f32 v178, v15, v15, v178
	v_fma_f32 v179, v31, v31, v179
	v_fma_f32 v180, v47, v47, v180
	v_fma_f32 v181, v63, v63, v181
	v_add_f32_dpp v178, v178, v178 quad_perm:[1,0,3,2] row_mask:0xf bank_mask:0xf
	v_add_f32_dpp v179, v179, v179 quad_perm:[1,0,3,2] row_mask:0xf bank_mask:0xf
	v_add_f32_dpp v180, v180, v180 quad_perm:[1,0,3,2] row_mask:0xf bank_mask:0xf
	v_add_f32_dpp v181, v181, v181 quad_perm:[1,0,3,2] row_mask:0xf bank_mask:0xf
	v_add_f32_dpp v178, v178, v178 quad_perm:[2,3,0,1] row_mask:0xf bank_mask:0xf
	v_add_f32_dpp v179, v179, v179 quad_perm:[2,3,0,1] row_mask:0xf bank_mask:0xf
	v_add_f32_dpp v180, v180, v180 quad_perm:[2,3,0,1] row_mask:0xf bank_mask:0xf
	v_add_f32_dpp v181, v181, v181 quad_perm:[2,3,0,1] row_mask:0xf bank_mask:0xf
	v_add_f32_dpp v178, v178, v178 row_half_mirror row_mask:0xf bank_mask:0xf
	v_add_f32_dpp v179, v179, v179 row_half_mirror row_mask:0xf bank_mask:0xf
	v_add_f32_dpp v180, v180, v180 row_half_mirror row_mask:0xf bank_mask:0xf
	v_add_f32_dpp v181, v181, v181 row_half_mirror row_mask:0xf bank_mask:0xf
	v_add_f32_dpp v178, v178, v178 row_ror:8 row_mask:0xf bank_mask:0xf
	v_add_f32_dpp v179, v179, v179 row_ror:8 row_mask:0xf bank_mask:0xf
	v_add_f32_dpp v180, v180, v180 row_ror:8 row_mask:0xf bank_mask:0xf
	v_add_f32_dpp v181, v181, v181 row_ror:8 row_mask:0xf bank_mask:0xf
	v_mov_b32_e32 v182, v178
	v_mov_b32_e32 v183, v179
	v_mov_b32_e32 v184, v180
	v_mov_b32_e32 v185, v181
	v_permlane16_swap_b32_e32 v182, v178
	v_permlane16_swap_b32_e32 v183, v179
	v_permlane16_swap_b32_e32 v184, v180
	v_permlane16_swap_b32_e32 v185, v181
	v_add_f32_e32 v178, v178, v182
	v_add_f32_e32 v179, v179, v183
	v_add_f32_e32 v180, v180, v184
	v_add_f32_e32 v181, v181, v185
	v_mov_b32_e32 v182, v178
	v_mov_b32_e32 v183, v179
	v_mov_b32_e32 v184, v180
	v_mov_b32_e32 v185, v181
	v_permlane32_swap_b32_e32 v182, v178
	v_permlane32_swap_b32_e32 v183, v179
	v_permlane32_swap_b32_e32 v184, v180
	v_permlane32_swap_b32_e32 v185, v181
	v_add_f32_e32 v178, v178, v182
	v_add_f32_e32 v179, v179, v183
	v_add_f32_e32 v180, v180, v184
	v_add_f32_e32 v181, v181, v185
	v_fmamk_f32 v198, v178, 0x3a800000, v225
	v_fmamk_f32 v199, v179, 0x3a800000, v225
	v_fmamk_f32 v200, v180, 0x3a800000, v225
	v_fmamk_f32 v201, v181, 0x3a800000, v225
	v_mul_f32_e32 v182, 0x4b800000, v198
	v_mul_f32_e32 v183, 0x4b800000, v199
	v_mul_f32_e32 v184, 0x4b800000, v200
	v_mul_f32_e32 v185, 0x4b800000, v201
	v_cmp_gt_f32_e64 s[2:3], s30, v198
	v_cmp_gt_f32_e64 s[50:51], s30, v199
	v_cmp_gt_f32_e64 s[88:89], s30, v200
	v_cmp_gt_f32_e64 s[90:91], s30, v201
	v_cndmask_b32_e64 v198, v198, v182, s[2:3]
	v_cndmask_b32_e64 v199, v199, v183, s[50:51]
	v_cndmask_b32_e64 v200, v200, v184, s[88:89]
	v_cndmask_b32_e64 v201, v201, v185, s[90:91]
	v_rsq_f32_e32 v198, v198
	v_rsq_f32_e32 v199, v199
	v_rsq_f32_e32 v200, v200
	v_rsq_f32_e32 v201, v201
	v_mul_f32_e32 v182, 0x45800000, v198
	v_mul_f32_e32 v183, 0x45800000, v199
	v_mul_f32_e32 v184, 0x45800000, v200
	v_mul_f32_e32 v185, 0x45800000, v201
	v_cndmask_b32_e64 v186, v198, v182, s[2:3]
	v_cndmask_b32_e64 v192, v199, v183, s[50:51]
	v_cndmask_b32_e64 v194, v200, v184, s[88:89]
	v_cndmask_b32_e64 v196, v201, v185, s[90:91]
	v_pk_mul_f32 v[0:1], v[186:187], v[0:1] op_sel_hi:[0,1]
	v_pk_mul_f32 v[2:3], v[186:187], v[2:3] op_sel_hi:[0,1]
	v_pk_mul_f32 v[4:5], v[186:187], v[4:5] op_sel_hi:[0,1]
	v_pk_mul_f32 v[6:7], v[186:187], v[6:7] op_sel_hi:[0,1]
	v_pk_mul_f32 v[8:9], v[186:187], v[8:9] op_sel_hi:[0,1]
	v_pk_mul_f32 v[10:11], v[186:187], v[10:11] op_sel_hi:[0,1]
	v_pk_mul_f32 v[12:13], v[186:187], v[12:13] op_sel_hi:[0,1]
	v_pk_mul_f32 v[14:15], v[186:187], v[14:15] op_sel_hi:[0,1]
	v_pk_mul_f32 v[0:1], v[64:65], v[0:1]
	v_pk_mul_f32 v[2:3], v[66:67], v[2:3]
	v_pk_mul_f32 v[4:5], v[68:69], v[4:5]
	v_pk_mul_f32 v[6:7], v[70:71], v[6:7]
	v_pk_mul_f32 v[8:9], v[72:73], v[8:9]
	v_pk_mul_f32 v[10:11], v[74:75], v[10:11]
	v_pk_mul_f32 v[12:13], v[76:77], v[12:13]
	v_pk_mul_f32 v[14:15], v[78:79], v[14:15]
	v_pk_fma_f32 v[0:1], v[80:81], v[0:1], v[162:163]
	v_pk_fma_f32 v[2:3], v[82:83], v[2:3], v[164:165]
	v_pk_fma_f32 v[4:5], v[84:85], v[4:5], v[166:167]
	v_pk_fma_f32 v[6:7], v[86:87], v[6:7], v[168:169]
	v_pk_fma_f32 v[8:9], v[88:89], v[8:9], v[170:171]
	v_pk_fma_f32 v[10:11], v[90:91], v[10:11], v[172:173]
	v_pk_fma_f32 v[12:13], v[92:93], v[12:13], v[174:175]
	v_pk_fma_f32 v[14:15], v[94:95], v[14:15], v[176:177]
	v_cvt_pk_bf16_f32 v204, v0, v1
	v_cvt_pk_bf16_f32 v205, v2, v3
	v_cvt_pk_bf16_f32 v206, v4, v5
	v_cvt_pk_bf16_f32 v207, v6, v7
	v_cvt_pk_bf16_f32 v208, v8, v9
	v_cvt_pk_bf16_f32 v209, v10, v11
	v_cvt_pk_bf16_f32 v210, v12, v13
	v_cvt_pk_bf16_f32 v211, v14, v15
	global_store_dwordx4 v203, v[204:207], s[48:49] sc1
	global_store_dwordx4 v203, v[208:211], s[48:49] offset:1024 sc1
	s_add_u32 s48, s48, 0x800
	s_addc_u32 s49, s49, 0
	v_pk_mul_f32 v[16:17], v[192:193], v[16:17] op_sel_hi:[0,1]
	v_pk_mul_f32 v[18:19], v[192:193], v[18:19] op_sel_hi:[0,1]
	v_pk_mul_f32 v[20:21], v[192:193], v[20:21] op_sel_hi:[0,1]
	v_pk_mul_f32 v[22:23], v[192:193], v[22:23] op_sel_hi:[0,1]
	v_pk_mul_f32 v[24:25], v[192:193], v[24:25] op_sel_hi:[0,1]
	v_pk_mul_f32 v[26:27], v[192:193], v[26:27] op_sel_hi:[0,1]
	v_pk_mul_f32 v[28:29], v[192:193], v[28:29] op_sel_hi:[0,1]
	v_pk_mul_f32 v[30:31], v[192:193], v[30:31] op_sel_hi:[0,1]
	v_pk_mul_f32 v[16:17], v[64:65], v[16:17]
	v_pk_mul_f32 v[18:19], v[66:67], v[18:19]
	v_pk_mul_f32 v[20:21], v[68:69], v[20:21]
	v_pk_mul_f32 v[22:23], v[70:71], v[22:23]
	v_pk_mul_f32 v[24:25], v[72:73], v[24:25]
	v_pk_mul_f32 v[26:27], v[74:75], v[26:27]
	v_pk_mul_f32 v[28:29], v[76:77], v[28:29]
	v_pk_mul_f32 v[30:31], v[78:79], v[30:31]
	v_pk_fma_f32 v[16:17], v[80:81], v[16:17], v[162:163]
	v_pk_fma_f32 v[18:19], v[82:83], v[18:19], v[164:165]
	v_pk_fma_f32 v[20:21], v[84:85], v[20:21], v[166:167]
	v_pk_fma_f32 v[22:23], v[86:87], v[22:23], v[168:169]
	v_pk_fma_f32 v[24:25], v[88:89], v[24:25], v[170:171]
	v_pk_fma_f32 v[26:27], v[90:91], v[26:27], v[172:173]
	v_pk_fma_f32 v[28:29], v[92:93], v[28:29], v[174:175]
	v_pk_fma_f32 v[30:31], v[94:95], v[30:31], v[176:177]
	v_cvt_pk_bf16_f32 v212, v16, v17
	v_cvt_pk_bf16_f32 v213, v18, v19
	v_cvt_pk_bf16_f32 v214, v20, v21
	v_cvt_pk_bf16_f32 v215, v22, v23
	v_cvt_pk_bf16_f32 v216, v24, v25
	v_cvt_pk_bf16_f32 v217, v26, v27
	v_cvt_pk_bf16_f32 v218, v28, v29
	v_cvt_pk_bf16_f32 v219, v30, v31
	global_store_dwordx4 v203, v[212:215], s[48:49] sc1
	global_store_dwordx4 v203, v[216:219], s[48:49] offset:1024 sc1
	s_add_u32 s48, s48, 0x800
	s_addc_u32 s49, s49, 0
	v_pk_mul_f32 v[32:33], v[194:195], v[32:33] op_sel_hi:[0,1]
	v_pk_mul_f32 v[34:35], v[194:195], v[34:35] op_sel_hi:[0,1]
	v_pk_mul_f32 v[36:37], v[194:195], v[36:37] op_sel_hi:[0,1]
	v_pk_mul_f32 v[38:39], v[194:195], v[38:39] op_sel_hi:[0,1]
	v_pk_mul_f32 v[40:41], v[194:195], v[40:41] op_sel_hi:[0,1]
	v_pk_mul_f32 v[42:43], v[194:195], v[42:43] op_sel_hi:[0,1]
	v_pk_mul_f32 v[44:45], v[194:195], v[44:45] op_sel_hi:[0,1]
	v_pk_mul_f32 v[46:47], v[194:195], v[46:47] op_sel_hi:[0,1]
	v_pk_mul_f32 v[32:33], v[64:65], v[32:33]
	v_pk_mul_f32 v[34:35], v[66:67], v[34:35]
	v_pk_mul_f32 v[36:37], v[68:69], v[36:37]
	v_pk_mul_f32 v[38:39], v[70:71], v[38:39]
	v_pk_mul_f32 v[40:41], v[72:73], v[40:41]
	v_pk_mul_f32 v[42:43], v[74:75], v[42:43]
	v_pk_mul_f32 v[44:45], v[76:77], v[44:45]
	v_pk_mul_f32 v[46:47], v[78:79], v[46:47]
	v_pk_fma_f32 v[32:33], v[80:81], v[32:33], v[162:163]
	v_pk_fma_f32 v[34:35], v[82:83], v[34:35], v[164:165]
	v_pk_fma_f32 v[36:37], v[84:85], v[36:37], v[166:167]
	v_pk_fma_f32 v[38:39], v[86:87], v[38:39], v[168:169]
	v_pk_fma_f32 v[40:41], v[88:89], v[40:41], v[170:171]
	v_pk_fma_f32 v[42:43], v[90:91], v[42:43], v[172:173]
	v_pk_fma_f32 v[44:45], v[92:93], v[44:45], v[174:175]
	v_pk_fma_f32 v[46:47], v[94:95], v[46:47], v[176:177]
	v_cvt_pk_bf16_f32 v204, v32, v33
	v_cvt_pk_bf16_f32 v205, v34, v35
	v_cvt_pk_bf16_f32 v206, v36, v37
	v_cvt_pk_bf16_f32 v207, v38, v39
	v_cvt_pk_bf16_f32 v208, v40, v41
	v_cvt_pk_bf16_f32 v209, v42, v43
	v_cvt_pk_bf16_f32 v210, v44, v45
	v_cvt_pk_bf16_f32 v211, v46, v47
	global_store_dwordx4 v203, v[204:207], s[48:49] sc1
	global_store_dwordx4 v203, v[208:211], s[48:49] offset:1024 sc1
	s_add_u32 s48, s48, 0x800
	s_addc_u32 s49, s49, 0
	v_pk_mul_f32 v[48:49], v[196:197], v[48:49] op_sel_hi:[0,1]
	v_pk_mul_f32 v[50:51], v[196:197], v[50:51] op_sel_hi:[0,1]
	v_pk_mul_f32 v[52:53], v[196:197], v[52:53] op_sel_hi:[0,1]
	v_pk_mul_f32 v[54:55], v[196:197], v[54:55] op_sel_hi:[0,1]
	v_pk_mul_f32 v[56:57], v[196:197], v[56:57] op_sel_hi:[0,1]
	v_pk_mul_f32 v[58:59], v[196:197], v[58:59] op_sel_hi:[0,1]
	v_pk_mul_f32 v[60:61], v[196:197], v[60:61] op_sel_hi:[0,1]
	v_pk_mul_f32 v[62:63], v[196:197], v[62:63] op_sel_hi:[0,1]
	v_pk_mul_f32 v[48:49], v[64:65], v[48:49]
	v_pk_mul_f32 v[50:51], v[66:67], v[50:51]
	v_pk_mul_f32 v[52:53], v[68:69], v[52:53]
	v_pk_mul_f32 v[54:55], v[70:71], v[54:55]
	v_pk_mul_f32 v[56:57], v[72:73], v[56:57]
	v_pk_mul_f32 v[58:59], v[74:75], v[58:59]
	v_pk_mul_f32 v[60:61], v[76:77], v[60:61]
	v_pk_mul_f32 v[62:63], v[78:79], v[62:63]
	v_pk_fma_f32 v[48:49], v[80:81], v[48:49], v[162:163]
	v_pk_fma_f32 v[50:51], v[82:83], v[50:51], v[164:165]
	v_pk_fma_f32 v[52:53], v[84:85], v[52:53], v[166:167]
	v_pk_fma_f32 v[54:55], v[86:87], v[54:55], v[168:169]
	v_pk_fma_f32 v[56:57], v[88:89], v[56:57], v[170:171]
	v_pk_fma_f32 v[58:59], v[90:91], v[58:59], v[172:173]
	v_pk_fma_f32 v[60:61], v[92:93], v[60:61], v[174:175]
	v_pk_fma_f32 v[62:63], v[94:95], v[62:63], v[176:177]
	v_cvt_pk_bf16_f32 v212, v48, v49
	v_cvt_pk_bf16_f32 v213, v50, v51
	v_cvt_pk_bf16_f32 v214, v52, v53
	v_cvt_pk_bf16_f32 v215, v54, v55
	v_cvt_pk_bf16_f32 v216, v56, v57
	v_cvt_pk_bf16_f32 v217, v58, v59
	v_cvt_pk_bf16_f32 v218, v60, v61
	v_cvt_pk_bf16_f32 v219, v62, v63
	global_store_dwordx4 v203, v[212:215], s[48:49] sc1
	global_store_dwordx4 v203, v[216:219], s[48:49] offset:1024 sc1
	s_add_u32 s48, s48, 0x800
	s_addc_u32 s49, s49, 0
	buffer_load_dwordx4 v[0:3], v202, s[12:15], s11 offen sc1
	buffer_load_dwordx4 v[4:7], v202, s[12:15], s11 offen offset:16 sc1
	buffer_load_dwordx4 v[8:11], v202, s[12:15], s11 offen offset:2048 sc1
	buffer_load_dwordx4 v[12:15], v202, s[12:15], s11 offen offset:2064 sc1
	s_add_u32 s11, s11, 0x1000
	buffer_load_dwordx4 v[16:19], v202, s[12:15], s11 offen sc1
	buffer_load_dwordx4 v[20:23], v202, s[12:15], s11 offen offset:16 sc1
	buffer_load_dwordx4 v[24:27], v202, s[12:15], s11 offen offset:2048 sc1
	buffer_load_dwordx4 v[28:31], v202, s[12:15], s11 offen offset:2064 sc1
	s_add_u32 s11, s11, 0x1000
	buffer_load_dwordx4 v[32:35], v202, s[12:15], s11 offen sc1
	buffer_load_dwordx4 v[36:39], v202, s[12:15], s11 offen offset:16 sc1
	buffer_load_dwordx4 v[40:43], v202, s[12:15], s11 offen offset:2048 sc1
	buffer_load_dwordx4 v[44:47], v202, s[12:15], s11 offen offset:2064 sc1
	s_add_u32 s11, s11, 0x1000
	buffer_load_dwordx4 v[48:51], v202, s[12:15], s11 offen sc1
	buffer_load_dwordx4 v[52:55], v202, s[12:15], s11 offen offset:16 sc1
	buffer_load_dwordx4 v[56:59], v202, s[12:15], s11 offen offset:2048 sc1
	buffer_load_dwordx4 v[60:63], v202, s[12:15], s11 offen offset:2064 sc1
	s_add_u32 s11, s11, 0x1000
	s_waitcnt vmcnt(24)
	v_mul_f32_e32 v178, v98, v98
	v_mul_f32_e32 v179, v114, v114
	v_mul_f32_e32 v180, v130, v130
	v_mul_f32_e32 v181, v146, v146
	v_fma_f32 v178, v99, v99, v178
	v_fma_f32 v179, v115, v115, v179
	v_fma_f32 v180, v131, v131, v180
	v_fma_f32 v181, v147, v147, v181
	v_fma_f32 v178, v100, v100, v178
	v_fma_f32 v179, v116, v116, v179
	v_fma_f32 v180, v132, v132, v180
	v_fma_f32 v181, v148, v148, v181
	v_fma_f32 v178, v101, v101, v178
	v_fma_f32 v179, v117, v117, v179
	v_fma_f32 v180, v133, v133, v180
	v_fma_f32 v181, v149, v149, v181
	v_fma_f32 v178, v102, v102, v178
	v_fma_f32 v179, v118, v118, v179
	v_fma_f32 v180, v134, v134, v180
	v_fma_f32 v181, v150, v150, v181
	v_fma_f32 v178, v103, v103, v178
	v_fma_f32 v179, v119, v119, v179
	v_fma_f32 v180, v135, v135, v180
	v_fma_f32 v181, v151, v151, v181
	v_fma_f32 v178, v104, v104, v178
	v_fma_f32 v179, v120, v120, v179
	v_fma_f32 v180, v136, v136, v180
	v_fma_f32 v181, v152, v152, v181
	v_fma_f32 v178, v105, v105, v178
	v_fma_f32 v179, v121, v121, v179
	v_fma_f32 v180, v137, v137, v180
	v_fma_f32 v181, v153, v153, v181
	v_fma_f32 v178, v106, v106, v178
	v_fma_f32 v179, v122, v122, v179
	v_fma_f32 v180, v138, v138, v180
	v_fma_f32 v181, v154, v154, v181
	v_fma_f32 v178, v107, v107, v178
	v_fma_f32 v179, v123, v123, v179
	v_fma_f32 v180, v139, v139, v180
	v_fma_f32 v181, v155, v155, v181
	v_fma_f32 v178, v108, v108, v178
	v_fma_f32 v179, v124, v124, v179
	v_fma_f32 v180, v140, v140, v180
	v_fma_f32 v181, v156, v156, v181
	v_fma_f32 v178, v109, v109, v178
	v_fma_f32 v179, v125, v125, v179
	v_fma_f32 v180, v141, v141, v180
	v_fma_f32 v181, v157, v157, v181
	v_fma_f32 v178, v110, v110, v178
	v_fma_f32 v179, v126, v126, v179
	v_fma_f32 v180, v142, v142, v180
	v_fma_f32 v181, v158, v158, v181
	v_fma_f32 v178, v111, v111, v178
	v_fma_f32 v179, v127, v127, v179
	v_fma_f32 v180, v143, v143, v180
	v_fma_f32 v181, v159, v159, v181
	v_fma_f32 v178, v112, v112, v178
	v_fma_f32 v179, v128, v128, v179
	v_fma_f32 v180, v144, v144, v180
	v_fma_f32 v181, v160, v160, v181
	v_fma_f32 v178, v113, v113, v178
	v_fma_f32 v179, v129, v129, v179
	v_fma_f32 v180, v145, v145, v180
	v_fma_f32 v181, v161, v161, v181
	v_add_f32_dpp v178, v178, v178 quad_perm:[1,0,3,2] row_mask:0xf bank_mask:0xf
	v_add_f32_dpp v179, v179, v179 quad_perm:[1,0,3,2] row_mask:0xf bank_mask:0xf
	v_add_f32_dpp v180, v180, v180 quad_perm:[1,0,3,2] row_mask:0xf bank_mask:0xf
	v_add_f32_dpp v181, v181, v181 quad_perm:[1,0,3,2] row_mask:0xf bank_mask:0xf
	v_add_f32_dpp v178, v178, v178 quad_perm:[2,3,0,1] row_mask:0xf bank_mask:0xf
	v_add_f32_dpp v179, v179, v179 quad_perm:[2,3,0,1] row_mask:0xf bank_mask:0xf
	v_add_f32_dpp v180, v180, v180 quad_perm:[2,3,0,1] row_mask:0xf bank_mask:0xf
	v_add_f32_dpp v181, v181, v181 quad_perm:[2,3,0,1] row_mask:0xf bank_mask:0xf
	v_add_f32_dpp v178, v178, v178 row_half_mirror row_mask:0xf bank_mask:0xf
	v_add_f32_dpp v179, v179, v179 row_half_mirror row_mask:0xf bank_mask:0xf
	v_add_f32_dpp v180, v180, v180 row_half_mirror row_mask:0xf bank_mask:0xf
	v_add_f32_dpp v181, v181, v181 row_half_mirror row_mask:0xf bank_mask:0xf
	v_add_f32_dpp v178, v178, v178 row_ror:8 row_mask:0xf bank_mask:0xf
	v_add_f32_dpp v179, v179, v179 row_ror:8 row_mask:0xf bank_mask:0xf
	v_add_f32_dpp v180, v180, v180 row_ror:8 row_mask:0xf bank_mask:0xf
	v_add_f32_dpp v181, v181, v181 row_ror:8 row_mask:0xf bank_mask:0xf
	v_mov_b32_e32 v182, v178
	v_mov_b32_e32 v183, v179
	v_mov_b32_e32 v184, v180
	v_mov_b32_e32 v185, v181
	v_permlane16_swap_b32_e32 v182, v178
	v_permlane16_swap_b32_e32 v183, v179
	v_permlane16_swap_b32_e32 v184, v180
	v_permlane16_swap_b32_e32 v185, v181
	v_add_f32_e32 v178, v178, v182
	v_add_f32_e32 v179, v179, v183
	v_add_f32_e32 v180, v180, v184
	v_add_f32_e32 v181, v181, v185
	v_mov_b32_e32 v182, v178
	v_mov_b32_e32 v183, v179
	v_mov_b32_e32 v184, v180
	v_mov_b32_e32 v185, v181
	v_permlane32_swap_b32_e32 v182, v178
	v_permlane32_swap_b32_e32 v183, v179
	v_permlane32_swap_b32_e32 v184, v180
	v_permlane32_swap_b32_e32 v185, v181
	v_add_f32_e32 v178, v178, v182
	v_add_f32_e32 v179, v179, v183
	v_add_f32_e32 v180, v180, v184
	v_add_f32_e32 v181, v181, v185
	v_fmamk_f32 v198, v178, 0x3a800000, v225
	v_fmamk_f32 v199, v179, 0x3a800000, v225
	v_fmamk_f32 v200, v180, 0x3a800000, v225
	v_fmamk_f32 v201, v181, 0x3a800000, v225
	v_mul_f32_e32 v182, 0x4b800000, v198
	v_mul_f32_e32 v183, 0x4b800000, v199
	v_mul_f32_e32 v184, 0x4b800000, v200
	v_mul_f32_e32 v185, 0x4b800000, v201
	v_cmp_gt_f32_e64 s[2:3], s30, v198
	v_cmp_gt_f32_e64 s[50:51], s30, v199
	v_cmp_gt_f32_e64 s[88:89], s30, v200
	v_cmp_gt_f32_e64 s[90:91], s30, v201
	v_cndmask_b32_e64 v198, v198, v182, s[2:3]
	v_cndmask_b32_e64 v199, v199, v183, s[50:51]
	v_cndmask_b32_e64 v200, v200, v184, s[88:89]
	v_cndmask_b32_e64 v201, v201, v185, s[90:91]
	v_rsq_f32_e32 v198, v198
	v_rsq_f32_e32 v199, v199
	v_rsq_f32_e32 v200, v200
	v_rsq_f32_e32 v201, v201
	v_mul_f32_e32 v182, 0x45800000, v198
	v_mul_f32_e32 v183, 0x45800000, v199
	v_mul_f32_e32 v184, 0x45800000, v200
	v_mul_f32_e32 v185, 0x45800000, v201
	v_cndmask_b32_e64 v186, v198, v182, s[2:3]
	v_cndmask_b32_e64 v192, v199, v183, s[50:51]
	v_cndmask_b32_e64 v194, v200, v184, s[88:89]
	v_cndmask_b32_e64 v196, v201, v185, s[90:91]
	v_pk_mul_f32 v[98:99], v[186:187], v[98:99] op_sel_hi:[0,1]
	v_pk_mul_f32 v[100:101], v[186:187], v[100:101] op_sel_hi:[0,1]
	v_pk_mul_f32 v[102:103], v[186:187], v[102:103] op_sel_hi:[0,1]
	v_pk_mul_f32 v[104:105], v[186:187], v[104:105] op_sel_hi:[0,1]
	v_pk_mul_f32 v[106:107], v[186:187], v[106:107] op_sel_hi:[0,1]
	v_pk_mul_f32 v[108:109], v[186:187], v[108:109] op_sel_hi:[0,1]
	v_pk_mul_f32 v[110:111], v[186:187], v[110:111] op_sel_hi:[0,1]
	v_pk_mul_f32 v[112:113], v[186:187], v[112:113] op_sel_hi:[0,1]
	v_pk_mul_f32 v[98:99], v[64:65], v[98:99]
	v_pk_mul_f32 v[100:101], v[66:67], v[100:101]
	v_pk_mul_f32 v[102:103], v[68:69], v[102:103]
	v_pk_mul_f32 v[104:105], v[70:71], v[104:105]
	v_pk_mul_f32 v[106:107], v[72:73], v[106:107]
	v_pk_mul_f32 v[108:109], v[74:75], v[108:109]
	v_pk_mul_f32 v[110:111], v[76:77], v[110:111]
	v_pk_mul_f32 v[112:113], v[78:79], v[112:113]
	v_pk_fma_f32 v[98:99], v[80:81], v[98:99], v[162:163]
	v_pk_fma_f32 v[100:101], v[82:83], v[100:101], v[164:165]
	v_pk_fma_f32 v[102:103], v[84:85], v[102:103], v[166:167]
	v_pk_fma_f32 v[104:105], v[86:87], v[104:105], v[168:169]
	v_pk_fma_f32 v[106:107], v[88:89], v[106:107], v[170:171]
	v_pk_fma_f32 v[108:109], v[90:91], v[108:109], v[172:173]
	v_pk_fma_f32 v[110:111], v[92:93], v[110:111], v[174:175]
	v_pk_fma_f32 v[112:113], v[94:95], v[112:113], v[176:177]
	v_cvt_pk_bf16_f32 v204, v98, v99
	v_cvt_pk_bf16_f32 v205, v100, v101
	v_cvt_pk_bf16_f32 v206, v102, v103
	v_cvt_pk_bf16_f32 v207, v104, v105
	v_cvt_pk_bf16_f32 v208, v106, v107
	v_cvt_pk_bf16_f32 v209, v108, v109
	v_cvt_pk_bf16_f32 v210, v110, v111
	v_cvt_pk_bf16_f32 v211, v112, v113
	global_store_dwordx4 v203, v[204:207], s[48:49] sc1
	global_store_dwordx4 v203, v[208:211], s[48:49] offset:1024 sc1
	s_add_u32 s48, s48, 0x800
	s_addc_u32 s49, s49, 0
	v_pk_mul_f32 v[114:115], v[192:193], v[114:115] op_sel_hi:[0,1]
	v_pk_mul_f32 v[116:117], v[192:193], v[116:117] op_sel_hi:[0,1]
	v_pk_mul_f32 v[118:119], v[192:193], v[118:119] op_sel_hi:[0,1]
	v_pk_mul_f32 v[120:121], v[192:193], v[120:121] op_sel_hi:[0,1]
	v_pk_mul_f32 v[122:123], v[192:193], v[122:123] op_sel_hi:[0,1]
	v_pk_mul_f32 v[124:125], v[192:193], v[124:125] op_sel_hi:[0,1]
	v_pk_mul_f32 v[126:127], v[192:193], v[126:127] op_sel_hi:[0,1]
	v_pk_mul_f32 v[128:129], v[192:193], v[128:129] op_sel_hi:[0,1]
	v_pk_mul_f32 v[114:115], v[64:65], v[114:115]
	v_pk_mul_f32 v[116:117], v[66:67], v[116:117]
	v_pk_mul_f32 v[118:119], v[68:69], v[118:119]
	v_pk_mul_f32 v[120:121], v[70:71], v[120:121]
	v_pk_mul_f32 v[122:123], v[72:73], v[122:123]
	v_pk_mul_f32 v[124:125], v[74:75], v[124:125]
	v_pk_mul_f32 v[126:127], v[76:77], v[126:127]
	v_pk_mul_f32 v[128:129], v[78:79], v[128:129]
	v_pk_fma_f32 v[114:115], v[80:81], v[114:115], v[162:163]
	v_pk_fma_f32 v[116:117], v[82:83], v[116:117], v[164:165]
	v_pk_fma_f32 v[118:119], v[84:85], v[118:119], v[166:167]
	v_pk_fma_f32 v[120:121], v[86:87], v[120:121], v[168:169]
	v_pk_fma_f32 v[122:123], v[88:89], v[122:123], v[170:171]
	v_pk_fma_f32 v[124:125], v[90:91], v[124:125], v[172:173]
	v_pk_fma_f32 v[126:127], v[92:93], v[126:127], v[174:175]
	v_pk_fma_f32 v[128:129], v[94:95], v[128:129], v[176:177]
	v_cvt_pk_bf16_f32 v212, v114, v115
	v_cvt_pk_bf16_f32 v213, v116, v117
	v_cvt_pk_bf16_f32 v214, v118, v119
	v_cvt_pk_bf16_f32 v215, v120, v121
	v_cvt_pk_bf16_f32 v216, v122, v123
	v_cvt_pk_bf16_f32 v217, v124, v125
	v_cvt_pk_bf16_f32 v218, v126, v127
	v_cvt_pk_bf16_f32 v219, v128, v129
	global_store_dwordx4 v203, v[212:215], s[48:49] sc1
	global_store_dwordx4 v203, v[216:219], s[48:49] offset:1024 sc1
	s_add_u32 s48, s48, 0x800
	s_addc_u32 s49, s49, 0
	v_pk_mul_f32 v[130:131], v[194:195], v[130:131] op_sel_hi:[0,1]
	v_pk_mul_f32 v[132:133], v[194:195], v[132:133] op_sel_hi:[0,1]
	v_pk_mul_f32 v[134:135], v[194:195], v[134:135] op_sel_hi:[0,1]
	v_pk_mul_f32 v[136:137], v[194:195], v[136:137] op_sel_hi:[0,1]
	v_pk_mul_f32 v[138:139], v[194:195], v[138:139] op_sel_hi:[0,1]
	v_pk_mul_f32 v[140:141], v[194:195], v[140:141] op_sel_hi:[0,1]
	v_pk_mul_f32 v[142:143], v[194:195], v[142:143] op_sel_hi:[0,1]
	v_pk_mul_f32 v[144:145], v[194:195], v[144:145] op_sel_hi:[0,1]
	v_pk_mul_f32 v[130:131], v[64:65], v[130:131]
	v_pk_mul_f32 v[132:133], v[66:67], v[132:133]
	v_pk_mul_f32 v[134:135], v[68:69], v[134:135]
	v_pk_mul_f32 v[136:137], v[70:71], v[136:137]
	v_pk_mul_f32 v[138:139], v[72:73], v[138:139]
	v_pk_mul_f32 v[140:141], v[74:75], v[140:141]
	v_pk_mul_f32 v[142:143], v[76:77], v[142:143]
	v_pk_mul_f32 v[144:145], v[78:79], v[144:145]
	v_pk_fma_f32 v[130:131], v[80:81], v[130:131], v[162:163]
	v_pk_fma_f32 v[132:133], v[82:83], v[132:133], v[164:165]
	v_pk_fma_f32 v[134:135], v[84:85], v[134:135], v[166:167]
	v_pk_fma_f32 v[136:137], v[86:87], v[136:137], v[168:169]
	v_pk_fma_f32 v[138:139], v[88:89], v[138:139], v[170:171]
	v_pk_fma_f32 v[140:141], v[90:91], v[140:141], v[172:173]
	v_pk_fma_f32 v[142:143], v[92:93], v[142:143], v[174:175]
	v_pk_fma_f32 v[144:145], v[94:95], v[144:145], v[176:177]
	v_cvt_pk_bf16_f32 v204, v130, v131
	v_cvt_pk_bf16_f32 v205, v132, v133
	v_cvt_pk_bf16_f32 v206, v134, v135
	v_cvt_pk_bf16_f32 v207, v136, v137
	v_cvt_pk_bf16_f32 v208, v138, v139
	v_cvt_pk_bf16_f32 v209, v140, v141
	v_cvt_pk_bf16_f32 v210, v142, v143
	v_cvt_pk_bf16_f32 v211, v144, v145
	global_store_dwordx4 v203, v[204:207], s[48:49] sc1
	global_store_dwordx4 v203, v[208:211], s[48:49] offset:1024 sc1
	s_add_u32 s48, s48, 0x800
	s_addc_u32 s49, s49, 0
	v_pk_mul_f32 v[146:147], v[196:197], v[146:147] op_sel_hi:[0,1]
	v_pk_mul_f32 v[148:149], v[196:197], v[148:149] op_sel_hi:[0,1]
	v_pk_mul_f32 v[150:151], v[196:197], v[150:151] op_sel_hi:[0,1]
	v_pk_mul_f32 v[152:153], v[196:197], v[152:153] op_sel_hi:[0,1]
	v_pk_mul_f32 v[154:155], v[196:197], v[154:155] op_sel_hi:[0,1]
	v_pk_mul_f32 v[156:157], v[196:197], v[156:157] op_sel_hi:[0,1]
	v_pk_mul_f32 v[158:159], v[196:197], v[158:159] op_sel_hi:[0,1]
	v_pk_mul_f32 v[160:161], v[196:197], v[160:161] op_sel_hi:[0,1]
	v_pk_mul_f32 v[146:147], v[64:65], v[146:147]
	v_pk_mul_f32 v[148:149], v[66:67], v[148:149]
	v_pk_mul_f32 v[150:151], v[68:69], v[150:151]
	v_pk_mul_f32 v[152:153], v[70:71], v[152:153]
	v_pk_mul_f32 v[154:155], v[72:73], v[154:155]
	v_pk_mul_f32 v[156:157], v[74:75], v[156:157]
	v_pk_mul_f32 v[158:159], v[76:77], v[158:159]
	v_pk_mul_f32 v[160:161], v[78:79], v[160:161]
	v_pk_fma_f32 v[146:147], v[80:81], v[146:147], v[162:163]
	v_pk_fma_f32 v[148:149], v[82:83], v[148:149], v[164:165]
	v_pk_fma_f32 v[150:151], v[84:85], v[150:151], v[166:167]
	v_pk_fma_f32 v[152:153], v[86:87], v[152:153], v[168:169]
	v_pk_fma_f32 v[154:155], v[88:89], v[154:155], v[170:171]
	v_pk_fma_f32 v[156:157], v[90:91], v[156:157], v[172:173]
	v_pk_fma_f32 v[158:159], v[92:93], v[158:159], v[174:175]
	v_pk_fma_f32 v[160:161], v[94:95], v[160:161], v[176:177]
	v_cvt_pk_bf16_f32 v212, v146, v147
	v_cvt_pk_bf16_f32 v213, v148, v149
	v_cvt_pk_bf16_f32 v214, v150, v151
	v_cvt_pk_bf16_f32 v215, v152, v153
	v_cvt_pk_bf16_f32 v216, v154, v155
	v_cvt_pk_bf16_f32 v217, v156, v157
	v_cvt_pk_bf16_f32 v218, v158, v159
	v_cvt_pk_bf16_f32 v219, v160, v161
	global_store_dwordx4 v203, v[212:215], s[48:49] sc1
	global_store_dwordx4 v203, v[216:219], s[48:49] offset:1024 sc1
	s_add_u32 s48, s48, 0x800
	s_addc_u32 s49, s49, 0
	buffer_load_dwordx4 v[98:101], v202, s[12:15], s11 offen sc1
	buffer_load_dwordx4 v[102:105], v202, s[12:15], s11 offen offset:16 sc1
	buffer_load_dwordx4 v[106:109], v202, s[12:15], s11 offen offset:2048 sc1
	buffer_load_dwordx4 v[110:113], v202, s[12:15], s11 offen offset:2064 sc1
	s_add_u32 s11, s11, 0x1000
	buffer_load_dwordx4 v[114:117], v202, s[12:15], s11 offen sc1
	buffer_load_dwordx4 v[118:121], v202, s[12:15], s11 offen offset:16 sc1
	buffer_load_dwordx4 v[122:125], v202, s[12:15], s11 offen offset:2048 sc1
	buffer_load_dwordx4 v[126:129], v202, s[12:15], s11 offen offset:2064 sc1
	s_add_u32 s11, s11, 0x1000
	buffer_load_dwordx4 v[130:133], v202, s[12:15], s11 offen sc1
	buffer_load_dwordx4 v[134:137], v202, s[12:15], s11 offen offset:16 sc1
	buffer_load_dwordx4 v[138:141], v202, s[12:15], s11 offen offset:2048 sc1
	buffer_load_dwordx4 v[142:145], v202, s[12:15], s11 offen offset:2064 sc1
	s_add_u32 s11, s11, 0x1000
	buffer_load_dwordx4 v[146:149], v202, s[12:15], s11 offen sc1
	buffer_load_dwordx4 v[150:153], v202, s[12:15], s11 offen offset:16 sc1
	buffer_load_dwordx4 v[154:157], v202, s[12:15], s11 offen offset:2048 sc1
	buffer_load_dwordx4 v[158:161], v202, s[12:15], s11 offen offset:2064 sc1
	s_add_u32 s11, s11, 0x1000
	s_waitcnt vmcnt(24)
	v_mul_f32_e32 v178, v0, v0
	v_mul_f32_e32 v179, v16, v16
	v_mul_f32_e32 v180, v32, v32
	v_mul_f32_e32 v181, v48, v48
	v_fma_f32 v178, v1, v1, v178
	v_fma_f32 v179, v17, v17, v179
	v_fma_f32 v180, v33, v33, v180
	v_fma_f32 v181, v49, v49, v181
	v_fma_f32 v178, v2, v2, v178
	v_fma_f32 v179, v18, v18, v179
	v_fma_f32 v180, v34, v34, v180
	v_fma_f32 v181, v50, v50, v181
	v_fma_f32 v178, v3, v3, v178
	v_fma_f32 v179, v19, v19, v179
	v_fma_f32 v180, v35, v35, v180
	v_fma_f32 v181, v51, v51, v181
	v_fma_f32 v178, v4, v4, v178
	v_fma_f32 v179, v20, v20, v179
	v_fma_f32 v180, v36, v36, v180
	v_fma_f32 v181, v52, v52, v181
	v_fma_f32 v178, v5, v5, v178
	v_fma_f32 v179, v21, v21, v179
	v_fma_f32 v180, v37, v37, v180
	v_fma_f32 v181, v53, v53, v181
	v_fma_f32 v178, v6, v6, v178
	v_fma_f32 v179, v22, v22, v179
	v_fma_f32 v180, v38, v38, v180
	v_fma_f32 v181, v54, v54, v181
	v_fma_f32 v178, v7, v7, v178
	v_fma_f32 v179, v23, v23, v179
	v_fma_f32 v180, v39, v39, v180
	v_fma_f32 v181, v55, v55, v181
	v_fma_f32 v178, v8, v8, v178
	v_fma_f32 v179, v24, v24, v179
	v_fma_f32 v180, v40, v40, v180
	v_fma_f32 v181, v56, v56, v181
	v_fma_f32 v178, v9, v9, v178
	v_fma_f32 v179, v25, v25, v179
	v_fma_f32 v180, v41, v41, v180
	v_fma_f32 v181, v57, v57, v181
	v_fma_f32 v178, v10, v10, v178
	v_fma_f32 v179, v26, v26, v179
	v_fma_f32 v180, v42, v42, v180
	v_fma_f32 v181, v58, v58, v181
	v_fma_f32 v178, v11, v11, v178
	v_fma_f32 v179, v27, v27, v179
	v_fma_f32 v180, v43, v43, v180
	v_fma_f32 v181, v59, v59, v181
	v_fma_f32 v178, v12, v12, v178
	v_fma_f32 v179, v28, v28, v179
	v_fma_f32 v180, v44, v44, v180
	v_fma_f32 v181, v60, v60, v181
	v_fma_f32 v178, v13, v13, v178
	v_fma_f32 v179, v29, v29, v179
	v_fma_f32 v180, v45, v45, v180
	v_fma_f32 v181, v61, v61, v181
	v_fma_f32 v178, v14, v14, v178
	v_fma_f32 v179, v30, v30, v179
	v_fma_f32 v180, v46, v46, v180
	v_fma_f32 v181, v62, v62, v181
	v_fma_f32 v178, v15, v15, v178
	v_fma_f32 v179, v31, v31, v179
	v_fma_f32 v180, v47, v47, v180
	v_fma_f32 v181, v63, v63, v181
	v_add_f32_dpp v178, v178, v178 quad_perm:[1,0,3,2] row_mask:0xf bank_mask:0xf
	v_add_f32_dpp v179, v179, v179 quad_perm:[1,0,3,2] row_mask:0xf bank_mask:0xf
	v_add_f32_dpp v180, v180, v180 quad_perm:[1,0,3,2] row_mask:0xf bank_mask:0xf
	v_add_f32_dpp v181, v181, v181 quad_perm:[1,0,3,2] row_mask:0xf bank_mask:0xf
	v_add_f32_dpp v178, v178, v178 quad_perm:[2,3,0,1] row_mask:0xf bank_mask:0xf
	v_add_f32_dpp v179, v179, v179 quad_perm:[2,3,0,1] row_mask:0xf bank_mask:0xf
	v_add_f32_dpp v180, v180, v180 quad_perm:[2,3,0,1] row_mask:0xf bank_mask:0xf
	v_add_f32_dpp v181, v181, v181 quad_perm:[2,3,0,1] row_mask:0xf bank_mask:0xf
	v_add_f32_dpp v178, v178, v178 row_half_mirror row_mask:0xf bank_mask:0xf
	v_add_f32_dpp v179, v179, v179 row_half_mirror row_mask:0xf bank_mask:0xf
	v_add_f32_dpp v180, v180, v180 row_half_mirror row_mask:0xf bank_mask:0xf
	v_add_f32_dpp v181, v181, v181 row_half_mirror row_mask:0xf bank_mask:0xf
	v_add_f32_dpp v178, v178, v178 row_ror:8 row_mask:0xf bank_mask:0xf
	v_add_f32_dpp v179, v179, v179 row_ror:8 row_mask:0xf bank_mask:0xf
	v_add_f32_dpp v180, v180, v180 row_ror:8 row_mask:0xf bank_mask:0xf
	v_add_f32_dpp v181, v181, v181 row_ror:8 row_mask:0xf bank_mask:0xf
	v_mov_b32_e32 v182, v178
	v_mov_b32_e32 v183, v179
	v_mov_b32_e32 v184, v180
	v_mov_b32_e32 v185, v181
	v_permlane16_swap_b32_e32 v182, v178
	v_permlane16_swap_b32_e32 v183, v179
	v_permlane16_swap_b32_e32 v184, v180
	v_permlane16_swap_b32_e32 v185, v181
	v_add_f32_e32 v178, v178, v182
	v_add_f32_e32 v179, v179, v183
	v_add_f32_e32 v180, v180, v184
	v_add_f32_e32 v181, v181, v185
	v_mov_b32_e32 v182, v178
	v_mov_b32_e32 v183, v179
	v_mov_b32_e32 v184, v180
	v_mov_b32_e32 v185, v181
	v_permlane32_swap_b32_e32 v182, v178
	v_permlane32_swap_b32_e32 v183, v179
	v_permlane32_swap_b32_e32 v184, v180
	v_permlane32_swap_b32_e32 v185, v181
	v_add_f32_e32 v178, v178, v182
	v_add_f32_e32 v179, v179, v183
	v_add_f32_e32 v180, v180, v184
	v_add_f32_e32 v181, v181, v185
	v_fmamk_f32 v198, v178, 0x3a800000, v225
	v_fmamk_f32 v199, v179, 0x3a800000, v225
	v_fmamk_f32 v200, v180, 0x3a800000, v225
	v_fmamk_f32 v201, v181, 0x3a800000, v225
	v_mul_f32_e32 v182, 0x4b800000, v198
	v_mul_f32_e32 v183, 0x4b800000, v199
	v_mul_f32_e32 v184, 0x4b800000, v200
	v_mul_f32_e32 v185, 0x4b800000, v201
	v_cmp_gt_f32_e64 s[2:3], s30, v198
	v_cmp_gt_f32_e64 s[50:51], s30, v199
	v_cmp_gt_f32_e64 s[88:89], s30, v200
	v_cmp_gt_f32_e64 s[90:91], s30, v201
	v_cndmask_b32_e64 v198, v198, v182, s[2:3]
	v_cndmask_b32_e64 v199, v199, v183, s[50:51]
	v_cndmask_b32_e64 v200, v200, v184, s[88:89]
	v_cndmask_b32_e64 v201, v201, v185, s[90:91]
	v_rsq_f32_e32 v198, v198
	v_rsq_f32_e32 v199, v199
	v_rsq_f32_e32 v200, v200
	v_rsq_f32_e32 v201, v201
	v_mul_f32_e32 v182, 0x45800000, v198
	v_mul_f32_e32 v183, 0x45800000, v199
	v_mul_f32_e32 v184, 0x45800000, v200
	v_mul_f32_e32 v185, 0x45800000, v201
	v_cndmask_b32_e64 v186, v198, v182, s[2:3]
	v_cndmask_b32_e64 v192, v199, v183, s[50:51]
	v_cndmask_b32_e64 v194, v200, v184, s[88:89]
	v_cndmask_b32_e64 v196, v201, v185, s[90:91]
	v_pk_mul_f32 v[0:1], v[186:187], v[0:1] op_sel_hi:[0,1]
	v_pk_mul_f32 v[2:3], v[186:187], v[2:3] op_sel_hi:[0,1]
	v_pk_mul_f32 v[4:5], v[186:187], v[4:5] op_sel_hi:[0,1]
	v_pk_mul_f32 v[6:7], v[186:187], v[6:7] op_sel_hi:[0,1]
	v_pk_mul_f32 v[8:9], v[186:187], v[8:9] op_sel_hi:[0,1]
	v_pk_mul_f32 v[10:11], v[186:187], v[10:11] op_sel_hi:[0,1]
	v_pk_mul_f32 v[12:13], v[186:187], v[12:13] op_sel_hi:[0,1]
	v_pk_mul_f32 v[14:15], v[186:187], v[14:15] op_sel_hi:[0,1]
	v_pk_mul_f32 v[0:1], v[64:65], v[0:1]
	v_pk_mul_f32 v[2:3], v[66:67], v[2:3]
	v_pk_mul_f32 v[4:5], v[68:69], v[4:5]
	v_pk_mul_f32 v[6:7], v[70:71], v[6:7]
	v_pk_mul_f32 v[8:9], v[72:73], v[8:9]
	v_pk_mul_f32 v[10:11], v[74:75], v[10:11]
	v_pk_mul_f32 v[12:13], v[76:77], v[12:13]
	v_pk_mul_f32 v[14:15], v[78:79], v[14:15]
	v_pk_fma_f32 v[0:1], v[80:81], v[0:1], v[162:163]
	v_pk_fma_f32 v[2:3], v[82:83], v[2:3], v[164:165]
	v_pk_fma_f32 v[4:5], v[84:85], v[4:5], v[166:167]
	v_pk_fma_f32 v[6:7], v[86:87], v[6:7], v[168:169]
	v_pk_fma_f32 v[8:9], v[88:89], v[8:9], v[170:171]
	v_pk_fma_f32 v[10:11], v[90:91], v[10:11], v[172:173]
	v_pk_fma_f32 v[12:13], v[92:93], v[12:13], v[174:175]
	v_pk_fma_f32 v[14:15], v[94:95], v[14:15], v[176:177]
	v_cvt_pk_bf16_f32 v204, v0, v1
	v_cvt_pk_bf16_f32 v205, v2, v3
	v_cvt_pk_bf16_f32 v206, v4, v5
	v_cvt_pk_bf16_f32 v207, v6, v7
	v_cvt_pk_bf16_f32 v208, v8, v9
	v_cvt_pk_bf16_f32 v209, v10, v11
	v_cvt_pk_bf16_f32 v210, v12, v13
	v_cvt_pk_bf16_f32 v211, v14, v15
	global_store_dwordx4 v203, v[204:207], s[48:49] sc1
	global_store_dwordx4 v203, v[208:211], s[48:49] offset:1024 sc1
	s_add_u32 s48, s48, 0x800
	s_addc_u32 s49, s49, 0
	v_pk_mul_f32 v[16:17], v[192:193], v[16:17] op_sel_hi:[0,1]
	v_pk_mul_f32 v[18:19], v[192:193], v[18:19] op_sel_hi:[0,1]
	v_pk_mul_f32 v[20:21], v[192:193], v[20:21] op_sel_hi:[0,1]
	v_pk_mul_f32 v[22:23], v[192:193], v[22:23] op_sel_hi:[0,1]
	v_pk_mul_f32 v[24:25], v[192:193], v[24:25] op_sel_hi:[0,1]
	v_pk_mul_f32 v[26:27], v[192:193], v[26:27] op_sel_hi:[0,1]
	v_pk_mul_f32 v[28:29], v[192:193], v[28:29] op_sel_hi:[0,1]
	v_pk_mul_f32 v[30:31], v[192:193], v[30:31] op_sel_hi:[0,1]
	v_pk_mul_f32 v[16:17], v[64:65], v[16:17]
	v_pk_mul_f32 v[18:19], v[66:67], v[18:19]
	v_pk_mul_f32 v[20:21], v[68:69], v[20:21]
	v_pk_mul_f32 v[22:23], v[70:71], v[22:23]
	v_pk_mul_f32 v[24:25], v[72:73], v[24:25]
	v_pk_mul_f32 v[26:27], v[74:75], v[26:27]
	v_pk_mul_f32 v[28:29], v[76:77], v[28:29]
	v_pk_mul_f32 v[30:31], v[78:79], v[30:31]
	v_pk_fma_f32 v[16:17], v[80:81], v[16:17], v[162:163]
	v_pk_fma_f32 v[18:19], v[82:83], v[18:19], v[164:165]
	v_pk_fma_f32 v[20:21], v[84:85], v[20:21], v[166:167]
	v_pk_fma_f32 v[22:23], v[86:87], v[22:23], v[168:169]
	v_pk_fma_f32 v[24:25], v[88:89], v[24:25], v[170:171]
	v_pk_fma_f32 v[26:27], v[90:91], v[26:27], v[172:173]
	v_pk_fma_f32 v[28:29], v[92:93], v[28:29], v[174:175]
	v_pk_fma_f32 v[30:31], v[94:95], v[30:31], v[176:177]
	v_cvt_pk_bf16_f32 v212, v16, v17
	v_cvt_pk_bf16_f32 v213, v18, v19
	v_cvt_pk_bf16_f32 v214, v20, v21
	v_cvt_pk_bf16_f32 v215, v22, v23
	v_cvt_pk_bf16_f32 v216, v24, v25
	v_cvt_pk_bf16_f32 v217, v26, v27
	v_cvt_pk_bf16_f32 v218, v28, v29
	v_cvt_pk_bf16_f32 v219, v30, v31
	global_store_dwordx4 v203, v[212:215], s[48:49] sc1
	global_store_dwordx4 v203, v[216:219], s[48:49] offset:1024 sc1
	s_add_u32 s48, s48, 0x800
	s_addc_u32 s49, s49, 0
	v_pk_mul_f32 v[32:33], v[194:195], v[32:33] op_sel_hi:[0,1]
	v_pk_mul_f32 v[34:35], v[194:195], v[34:35] op_sel_hi:[0,1]
	v_pk_mul_f32 v[36:37], v[194:195], v[36:37] op_sel_hi:[0,1]
	v_pk_mul_f32 v[38:39], v[194:195], v[38:39] op_sel_hi:[0,1]
	v_pk_mul_f32 v[40:41], v[194:195], v[40:41] op_sel_hi:[0,1]
	v_pk_mul_f32 v[42:43], v[194:195], v[42:43] op_sel_hi:[0,1]
	v_pk_mul_f32 v[44:45], v[194:195], v[44:45] op_sel_hi:[0,1]
	v_pk_mul_f32 v[46:47], v[194:195], v[46:47] op_sel_hi:[0,1]
	v_pk_mul_f32 v[32:33], v[64:65], v[32:33]
	v_pk_mul_f32 v[34:35], v[66:67], v[34:35]
	v_pk_mul_f32 v[36:37], v[68:69], v[36:37]
	v_pk_mul_f32 v[38:39], v[70:71], v[38:39]
	v_pk_mul_f32 v[40:41], v[72:73], v[40:41]
	v_pk_mul_f32 v[42:43], v[74:75], v[42:43]
	v_pk_mul_f32 v[44:45], v[76:77], v[44:45]
	v_pk_mul_f32 v[46:47], v[78:79], v[46:47]
	v_pk_fma_f32 v[32:33], v[80:81], v[32:33], v[162:163]
	v_pk_fma_f32 v[34:35], v[82:83], v[34:35], v[164:165]
	v_pk_fma_f32 v[36:37], v[84:85], v[36:37], v[166:167]
	v_pk_fma_f32 v[38:39], v[86:87], v[38:39], v[168:169]
	v_pk_fma_f32 v[40:41], v[88:89], v[40:41], v[170:171]
	v_pk_fma_f32 v[42:43], v[90:91], v[42:43], v[172:173]
	v_pk_fma_f32 v[44:45], v[92:93], v[44:45], v[174:175]
	v_pk_fma_f32 v[46:47], v[94:95], v[46:47], v[176:177]
	v_cvt_pk_bf16_f32 v204, v32, v33
	v_cvt_pk_bf16_f32 v205, v34, v35
	v_cvt_pk_bf16_f32 v206, v36, v37
	v_cvt_pk_bf16_f32 v207, v38, v39
	v_cvt_pk_bf16_f32 v208, v40, v41
	v_cvt_pk_bf16_f32 v209, v42, v43
	v_cvt_pk_bf16_f32 v210, v44, v45
	v_cvt_pk_bf16_f32 v211, v46, v47
	global_store_dwordx4 v203, v[204:207], s[48:49] sc1
	global_store_dwordx4 v203, v[208:211], s[48:49] offset:1024 sc1
	s_add_u32 s48, s48, 0x800
	s_addc_u32 s49, s49, 0
	v_pk_mul_f32 v[48:49], v[196:197], v[48:49] op_sel_hi:[0,1]
	v_pk_mul_f32 v[50:51], v[196:197], v[50:51] op_sel_hi:[0,1]
	v_pk_mul_f32 v[52:53], v[196:197], v[52:53] op_sel_hi:[0,1]
	v_pk_mul_f32 v[54:55], v[196:197], v[54:55] op_sel_hi:[0,1]
	v_pk_mul_f32 v[56:57], v[196:197], v[56:57] op_sel_hi:[0,1]
	v_pk_mul_f32 v[58:59], v[196:197], v[58:59] op_sel_hi:[0,1]
	v_pk_mul_f32 v[60:61], v[196:197], v[60:61] op_sel_hi:[0,1]
	v_pk_mul_f32 v[62:63], v[196:197], v[62:63] op_sel_hi:[0,1]
	v_pk_mul_f32 v[48:49], v[64:65], v[48:49]
	v_pk_mul_f32 v[50:51], v[66:67], v[50:51]
	v_pk_mul_f32 v[52:53], v[68:69], v[52:53]
	v_pk_mul_f32 v[54:55], v[70:71], v[54:55]
	v_pk_mul_f32 v[56:57], v[72:73], v[56:57]
	v_pk_mul_f32 v[58:59], v[74:75], v[58:59]
	v_pk_mul_f32 v[60:61], v[76:77], v[60:61]
	v_pk_mul_f32 v[62:63], v[78:79], v[62:63]
	v_pk_fma_f32 v[48:49], v[80:81], v[48:49], v[162:163]
	v_pk_fma_f32 v[50:51], v[82:83], v[50:51], v[164:165]
	v_pk_fma_f32 v[52:53], v[84:85], v[52:53], v[166:167]
	v_pk_fma_f32 v[54:55], v[86:87], v[54:55], v[168:169]
	v_pk_fma_f32 v[56:57], v[88:89], v[56:57], v[170:171]
	v_pk_fma_f32 v[58:59], v[90:91], v[58:59], v[172:173]
	v_pk_fma_f32 v[60:61], v[92:93], v[60:61], v[174:175]
	v_pk_fma_f32 v[62:63], v[94:95], v[62:63], v[176:177]
	v_cvt_pk_bf16_f32 v212, v48, v49
	v_cvt_pk_bf16_f32 v213, v50, v51
	v_cvt_pk_bf16_f32 v214, v52, v53
	v_cvt_pk_bf16_f32 v215, v54, v55
	v_cvt_pk_bf16_f32 v216, v56, v57
	v_cvt_pk_bf16_f32 v217, v58, v59
	v_cvt_pk_bf16_f32 v218, v60, v61
	v_cvt_pk_bf16_f32 v219, v62, v63
	global_store_dwordx4 v203, v[212:215], s[48:49] sc1
	global_store_dwordx4 v203, v[216:219], s[48:49] offset:1024 sc1
	s_add_u32 s48, s48, 0x800
	s_addc_u32 s49, s49, 0
	s_waitcnt vmcnt(8)
	v_mul_f32_e32 v178, v98, v98
	v_mul_f32_e32 v179, v114, v114
	v_mul_f32_e32 v180, v130, v130
	v_mul_f32_e32 v181, v146, v146
	v_fma_f32 v178, v99, v99, v178
	v_fma_f32 v179, v115, v115, v179
	v_fma_f32 v180, v131, v131, v180
	v_fma_f32 v181, v147, v147, v181
	v_fma_f32 v178, v100, v100, v178
	v_fma_f32 v179, v116, v116, v179
	v_fma_f32 v180, v132, v132, v180
	v_fma_f32 v181, v148, v148, v181
	v_fma_f32 v178, v101, v101, v178
	v_fma_f32 v179, v117, v117, v179
	v_fma_f32 v180, v133, v133, v180
	v_fma_f32 v181, v149, v149, v181
	v_fma_f32 v178, v102, v102, v178
	v_fma_f32 v179, v118, v118, v179
	v_fma_f32 v180, v134, v134, v180
	v_fma_f32 v181, v150, v150, v181
	v_fma_f32 v178, v103, v103, v178
	v_fma_f32 v179, v119, v119, v179
	v_fma_f32 v180, v135, v135, v180
	v_fma_f32 v181, v151, v151, v181
	v_fma_f32 v178, v104, v104, v178
	v_fma_f32 v179, v120, v120, v179
	v_fma_f32 v180, v136, v136, v180
	v_fma_f32 v181, v152, v152, v181
	v_fma_f32 v178, v105, v105, v178
	v_fma_f32 v179, v121, v121, v179
	v_fma_f32 v180, v137, v137, v180
	v_fma_f32 v181, v153, v153, v181
	v_fma_f32 v178, v106, v106, v178
	v_fma_f32 v179, v122, v122, v179
	v_fma_f32 v180, v138, v138, v180
	v_fma_f32 v181, v154, v154, v181
	v_fma_f32 v178, v107, v107, v178
	v_fma_f32 v179, v123, v123, v179
	v_fma_f32 v180, v139, v139, v180
	v_fma_f32 v181, v155, v155, v181
	v_fma_f32 v178, v108, v108, v178
	v_fma_f32 v179, v124, v124, v179
	v_fma_f32 v180, v140, v140, v180
	v_fma_f32 v181, v156, v156, v181
	v_fma_f32 v178, v109, v109, v178
	v_fma_f32 v179, v125, v125, v179
	v_fma_f32 v180, v141, v141, v180
	v_fma_f32 v181, v157, v157, v181
	v_fma_f32 v178, v110, v110, v178
	v_fma_f32 v179, v126, v126, v179
	v_fma_f32 v180, v142, v142, v180
	v_fma_f32 v181, v158, v158, v181
	v_fma_f32 v178, v111, v111, v178
	v_fma_f32 v179, v127, v127, v179
	v_fma_f32 v180, v143, v143, v180
	v_fma_f32 v181, v159, v159, v181
	v_fma_f32 v178, v112, v112, v178
	v_fma_f32 v179, v128, v128, v179
	v_fma_f32 v180, v144, v144, v180
	v_fma_f32 v181, v160, v160, v181
	v_fma_f32 v178, v113, v113, v178
	v_fma_f32 v179, v129, v129, v179
	v_fma_f32 v180, v145, v145, v180
	v_fma_f32 v181, v161, v161, v181
	v_add_f32_dpp v178, v178, v178 quad_perm:[1,0,3,2] row_mask:0xf bank_mask:0xf
	v_add_f32_dpp v179, v179, v179 quad_perm:[1,0,3,2] row_mask:0xf bank_mask:0xf
	v_add_f32_dpp v180, v180, v180 quad_perm:[1,0,3,2] row_mask:0xf bank_mask:0xf
	v_add_f32_dpp v181, v181, v181 quad_perm:[1,0,3,2] row_mask:0xf bank_mask:0xf
	v_add_f32_dpp v178, v178, v178 quad_perm:[2,3,0,1] row_mask:0xf bank_mask:0xf
	v_add_f32_dpp v179, v179, v179 quad_perm:[2,3,0,1] row_mask:0xf bank_mask:0xf
	v_add_f32_dpp v180, v180, v180 quad_perm:[2,3,0,1] row_mask:0xf bank_mask:0xf
	v_add_f32_dpp v181, v181, v181 quad_perm:[2,3,0,1] row_mask:0xf bank_mask:0xf
	v_add_f32_dpp v178, v178, v178 row_half_mirror row_mask:0xf bank_mask:0xf
	v_add_f32_dpp v179, v179, v179 row_half_mirror row_mask:0xf bank_mask:0xf
	v_add_f32_dpp v180, v180, v180 row_half_mirror row_mask:0xf bank_mask:0xf
	v_add_f32_dpp v181, v181, v181 row_half_mirror row_mask:0xf bank_mask:0xf
	v_add_f32_dpp v178, v178, v178 row_ror:8 row_mask:0xf bank_mask:0xf
	v_add_f32_dpp v179, v179, v179 row_ror:8 row_mask:0xf bank_mask:0xf
	v_add_f32_dpp v180, v180, v180 row_ror:8 row_mask:0xf bank_mask:0xf
	v_add_f32_dpp v181, v181, v181 row_ror:8 row_mask:0xf bank_mask:0xf
	v_mov_b32_e32 v182, v178
	v_mov_b32_e32 v183, v179
	v_mov_b32_e32 v184, v180
	v_mov_b32_e32 v185, v181
	v_permlane16_swap_b32_e32 v182, v178
	v_permlane16_swap_b32_e32 v183, v179
	v_permlane16_swap_b32_e32 v184, v180
	v_permlane16_swap_b32_e32 v185, v181
	v_add_f32_e32 v178, v178, v182
	v_add_f32_e32 v179, v179, v183
	v_add_f32_e32 v180, v180, v184
	v_add_f32_e32 v181, v181, v185
	v_mov_b32_e32 v182, v178
	v_mov_b32_e32 v183, v179
	v_mov_b32_e32 v184, v180
	v_mov_b32_e32 v185, v181
	v_permlane32_swap_b32_e32 v182, v178
	v_permlane32_swap_b32_e32 v183, v179
	v_permlane32_swap_b32_e32 v184, v180
	v_permlane32_swap_b32_e32 v185, v181
	v_add_f32_e32 v178, v178, v182
	v_add_f32_e32 v179, v179, v183
	v_add_f32_e32 v180, v180, v184
	v_add_f32_e32 v181, v181, v185
	v_fmamk_f32 v198, v178, 0x3a800000, v225
	v_fmamk_f32 v199, v179, 0x3a800000, v225
	v_fmamk_f32 v200, v180, 0x3a800000, v225
	v_fmamk_f32 v201, v181, 0x3a800000, v225
	v_mul_f32_e32 v182, 0x4b800000, v198
	v_mul_f32_e32 v183, 0x4b800000, v199
	v_mul_f32_e32 v184, 0x4b800000, v200
	v_mul_f32_e32 v185, 0x4b800000, v201
	v_cmp_gt_f32_e64 s[2:3], s30, v198
	v_cmp_gt_f32_e64 s[50:51], s30, v199
	v_cmp_gt_f32_e64 s[88:89], s30, v200
	v_cmp_gt_f32_e64 s[90:91], s30, v201
	v_cndmask_b32_e64 v198, v198, v182, s[2:3]
	v_cndmask_b32_e64 v199, v199, v183, s[50:51]
	v_cndmask_b32_e64 v200, v200, v184, s[88:89]
	v_cndmask_b32_e64 v201, v201, v185, s[90:91]
	v_rsq_f32_e32 v198, v198
	v_rsq_f32_e32 v199, v199
	v_rsq_f32_e32 v200, v200
	v_rsq_f32_e32 v201, v201
	v_mul_f32_e32 v182, 0x45800000, v198
	v_mul_f32_e32 v183, 0x45800000, v199
	v_mul_f32_e32 v184, 0x45800000, v200
	v_mul_f32_e32 v185, 0x45800000, v201
	v_cndmask_b32_e64 v186, v198, v182, s[2:3]
	v_cndmask_b32_e64 v192, v199, v183, s[50:51]
	v_cndmask_b32_e64 v194, v200, v184, s[88:89]
	v_cndmask_b32_e64 v196, v201, v185, s[90:91]
	v_pk_mul_f32 v[98:99], v[186:187], v[98:99] op_sel_hi:[0,1]
	v_pk_mul_f32 v[100:101], v[186:187], v[100:101] op_sel_hi:[0,1]
	v_pk_mul_f32 v[102:103], v[186:187], v[102:103] op_sel_hi:[0,1]
	v_pk_mul_f32 v[104:105], v[186:187], v[104:105] op_sel_hi:[0,1]
	v_pk_mul_f32 v[106:107], v[186:187], v[106:107] op_sel_hi:[0,1]
	v_pk_mul_f32 v[108:109], v[186:187], v[108:109] op_sel_hi:[0,1]
	v_pk_mul_f32 v[110:111], v[186:187], v[110:111] op_sel_hi:[0,1]
	v_pk_mul_f32 v[112:113], v[186:187], v[112:113] op_sel_hi:[0,1]
	v_pk_mul_f32 v[98:99], v[64:65], v[98:99]
	v_pk_mul_f32 v[100:101], v[66:67], v[100:101]
	v_pk_mul_f32 v[102:103], v[68:69], v[102:103]
	v_pk_mul_f32 v[104:105], v[70:71], v[104:105]
	v_pk_mul_f32 v[106:107], v[72:73], v[106:107]
	v_pk_mul_f32 v[108:109], v[74:75], v[108:109]
	v_pk_mul_f32 v[110:111], v[76:77], v[110:111]
	v_pk_mul_f32 v[112:113], v[78:79], v[112:113]
	v_pk_fma_f32 v[98:99], v[80:81], v[98:99], v[162:163]
	v_pk_fma_f32 v[100:101], v[82:83], v[100:101], v[164:165]
	v_pk_fma_f32 v[102:103], v[84:85], v[102:103], v[166:167]
	v_pk_fma_f32 v[104:105], v[86:87], v[104:105], v[168:169]
	v_pk_fma_f32 v[106:107], v[88:89], v[106:107], v[170:171]
	v_pk_fma_f32 v[108:109], v[90:91], v[108:109], v[172:173]
	v_pk_fma_f32 v[110:111], v[92:93], v[110:111], v[174:175]
	v_pk_fma_f32 v[112:113], v[94:95], v[112:113], v[176:177]
	v_cvt_pk_bf16_f32 v204, v98, v99
	v_cvt_pk_bf16_f32 v205, v100, v101
	v_cvt_pk_bf16_f32 v206, v102, v103
	v_cvt_pk_bf16_f32 v207, v104, v105
	v_cvt_pk_bf16_f32 v208, v106, v107
	v_cvt_pk_bf16_f32 v209, v108, v109
	v_cvt_pk_bf16_f32 v210, v110, v111
	v_cvt_pk_bf16_f32 v211, v112, v113
	global_store_dwordx4 v203, v[204:207], s[48:49] sc1
	global_store_dwordx4 v203, v[208:211], s[48:49] offset:1024 sc1
	s_add_u32 s48, s48, 0x800
	s_addc_u32 s49, s49, 0
	v_pk_mul_f32 v[114:115], v[192:193], v[114:115] op_sel_hi:[0,1]
	v_pk_mul_f32 v[116:117], v[192:193], v[116:117] op_sel_hi:[0,1]
	v_pk_mul_f32 v[118:119], v[192:193], v[118:119] op_sel_hi:[0,1]
	v_pk_mul_f32 v[120:121], v[192:193], v[120:121] op_sel_hi:[0,1]
	v_pk_mul_f32 v[122:123], v[192:193], v[122:123] op_sel_hi:[0,1]
	v_pk_mul_f32 v[124:125], v[192:193], v[124:125] op_sel_hi:[0,1]
	v_pk_mul_f32 v[126:127], v[192:193], v[126:127] op_sel_hi:[0,1]
	v_pk_mul_f32 v[128:129], v[192:193], v[128:129] op_sel_hi:[0,1]
	v_pk_mul_f32 v[114:115], v[64:65], v[114:115]
	v_pk_mul_f32 v[116:117], v[66:67], v[116:117]
	v_pk_mul_f32 v[118:119], v[68:69], v[118:119]
	v_pk_mul_f32 v[120:121], v[70:71], v[120:121]
	v_pk_mul_f32 v[122:123], v[72:73], v[122:123]
	v_pk_mul_f32 v[124:125], v[74:75], v[124:125]
	v_pk_mul_f32 v[126:127], v[76:77], v[126:127]
	v_pk_mul_f32 v[128:129], v[78:79], v[128:129]
	v_pk_fma_f32 v[114:115], v[80:81], v[114:115], v[162:163]
	v_pk_fma_f32 v[116:117], v[82:83], v[116:117], v[164:165]
	v_pk_fma_f32 v[118:119], v[84:85], v[118:119], v[166:167]
	v_pk_fma_f32 v[120:121], v[86:87], v[120:121], v[168:169]
	v_pk_fma_f32 v[122:123], v[88:89], v[122:123], v[170:171]
	v_pk_fma_f32 v[124:125], v[90:91], v[124:125], v[172:173]
	v_pk_fma_f32 v[126:127], v[92:93], v[126:127], v[174:175]
	v_pk_fma_f32 v[128:129], v[94:95], v[128:129], v[176:177]
	v_cvt_pk_bf16_f32 v212, v114, v115
	v_cvt_pk_bf16_f32 v213, v116, v117
	v_cvt_pk_bf16_f32 v214, v118, v119
	v_cvt_pk_bf16_f32 v215, v120, v121
	v_cvt_pk_bf16_f32 v216, v122, v123
	v_cvt_pk_bf16_f32 v217, v124, v125
	v_cvt_pk_bf16_f32 v218, v126, v127
	v_cvt_pk_bf16_f32 v219, v128, v129
	global_store_dwordx4 v203, v[212:215], s[48:49] sc1
	global_store_dwordx4 v203, v[216:219], s[48:49] offset:1024 sc1
	s_add_u32 s48, s48, 0x800
	s_addc_u32 s49, s49, 0
	v_pk_mul_f32 v[130:131], v[194:195], v[130:131] op_sel_hi:[0,1]
	v_pk_mul_f32 v[132:133], v[194:195], v[132:133] op_sel_hi:[0,1]
	v_pk_mul_f32 v[134:135], v[194:195], v[134:135] op_sel_hi:[0,1]
	v_pk_mul_f32 v[136:137], v[194:195], v[136:137] op_sel_hi:[0,1]
	v_pk_mul_f32 v[138:139], v[194:195], v[138:139] op_sel_hi:[0,1]
	v_pk_mul_f32 v[140:141], v[194:195], v[140:141] op_sel_hi:[0,1]
	v_pk_mul_f32 v[142:143], v[194:195], v[142:143] op_sel_hi:[0,1]
	v_pk_mul_f32 v[144:145], v[194:195], v[144:145] op_sel_hi:[0,1]
	v_pk_mul_f32 v[130:131], v[64:65], v[130:131]
	v_pk_mul_f32 v[132:133], v[66:67], v[132:133]
	v_pk_mul_f32 v[134:135], v[68:69], v[134:135]
	v_pk_mul_f32 v[136:137], v[70:71], v[136:137]
	v_pk_mul_f32 v[138:139], v[72:73], v[138:139]
	v_pk_mul_f32 v[140:141], v[74:75], v[140:141]
	v_pk_mul_f32 v[142:143], v[76:77], v[142:143]
	v_pk_mul_f32 v[144:145], v[78:79], v[144:145]
	v_pk_fma_f32 v[130:131], v[80:81], v[130:131], v[162:163]
	v_pk_fma_f32 v[132:133], v[82:83], v[132:133], v[164:165]
	v_pk_fma_f32 v[134:135], v[84:85], v[134:135], v[166:167]
	v_pk_fma_f32 v[136:137], v[86:87], v[136:137], v[168:169]
	v_pk_fma_f32 v[138:139], v[88:89], v[138:139], v[170:171]
	v_pk_fma_f32 v[140:141], v[90:91], v[140:141], v[172:173]
	v_pk_fma_f32 v[142:143], v[92:93], v[142:143], v[174:175]
	v_pk_fma_f32 v[144:145], v[94:95], v[144:145], v[176:177]
	v_cvt_pk_bf16_f32 v204, v130, v131
	v_cvt_pk_bf16_f32 v205, v132, v133
	v_cvt_pk_bf16_f32 v206, v134, v135
	v_cvt_pk_bf16_f32 v207, v136, v137
	v_cvt_pk_bf16_f32 v208, v138, v139
	v_cvt_pk_bf16_f32 v209, v140, v141
	v_cvt_pk_bf16_f32 v210, v142, v143
	v_cvt_pk_bf16_f32 v211, v144, v145
	global_store_dwordx4 v203, v[204:207], s[48:49] sc1
	global_store_dwordx4 v203, v[208:211], s[48:49] offset:1024 sc1
	s_add_u32 s48, s48, 0x800
	s_addc_u32 s49, s49, 0
	v_pk_mul_f32 v[146:147], v[196:197], v[146:147] op_sel_hi:[0,1]
	v_pk_mul_f32 v[148:149], v[196:197], v[148:149] op_sel_hi:[0,1]
	v_pk_mul_f32 v[150:151], v[196:197], v[150:151] op_sel_hi:[0,1]
	v_pk_mul_f32 v[152:153], v[196:197], v[152:153] op_sel_hi:[0,1]
	v_pk_mul_f32 v[154:155], v[196:197], v[154:155] op_sel_hi:[0,1]
	v_pk_mul_f32 v[156:157], v[196:197], v[156:157] op_sel_hi:[0,1]
	v_pk_mul_f32 v[158:159], v[196:197], v[158:159] op_sel_hi:[0,1]
	v_pk_mul_f32 v[160:161], v[196:197], v[160:161] op_sel_hi:[0,1]
	v_pk_mul_f32 v[146:147], v[64:65], v[146:147]
	v_pk_mul_f32 v[148:149], v[66:67], v[148:149]
	v_pk_mul_f32 v[150:151], v[68:69], v[150:151]
	v_pk_mul_f32 v[152:153], v[70:71], v[152:153]
	v_pk_mul_f32 v[154:155], v[72:73], v[154:155]
	v_pk_mul_f32 v[156:157], v[74:75], v[156:157]
	v_pk_mul_f32 v[158:159], v[76:77], v[158:159]
	v_pk_mul_f32 v[160:161], v[78:79], v[160:161]
	v_pk_fma_f32 v[146:147], v[80:81], v[146:147], v[162:163]
	v_pk_fma_f32 v[148:149], v[82:83], v[148:149], v[164:165]
	v_pk_fma_f32 v[150:151], v[84:85], v[150:151], v[166:167]
	v_pk_fma_f32 v[152:153], v[86:87], v[152:153], v[168:169]
	v_pk_fma_f32 v[154:155], v[88:89], v[154:155], v[170:171]
	v_pk_fma_f32 v[156:157], v[90:91], v[156:157], v[172:173]
	v_pk_fma_f32 v[158:159], v[92:93], v[158:159], v[174:175]
	v_pk_fma_f32 v[160:161], v[94:95], v[160:161], v[176:177]
	v_cvt_pk_bf16_f32 v212, v146, v147
	v_cvt_pk_bf16_f32 v213, v148, v149
	v_cvt_pk_bf16_f32 v214, v150, v151
	v_cvt_pk_bf16_f32 v215, v152, v153
	v_cvt_pk_bf16_f32 v216, v154, v155
	v_cvt_pk_bf16_f32 v217, v156, v157
	v_cvt_pk_bf16_f32 v218, v158, v159
	v_cvt_pk_bf16_f32 v219, v160, v161
	global_store_dwordx4 v203, v[212:215], s[48:49] sc1
	global_store_dwordx4 v203, v[216:219], s[48:49] offset:1024 sc1
	s_add_u32 s48, s48, 0x800
	s_addc_u32 s49, s49, 0
	s_nop 1
	s_branch .LBB0_281
.Lnrm_A_fallback:
	v_and_b32_e32 v0, 64, v227
	v_add_u32_e32 v0, 64, v0
	v_xor_b32_e32 v1, 1, v227
	v_lshlrev_b32_e32 v96, 4, v231
	v_cmp_lt_i32_e32 vcc, v1, v0
	v_lshl_add_u64 v[64:65], s[72:73], 0, v[96:97]
	v_readlane_b32 s2, v250, 44
	v_cndmask_b32_e32 v1, v227, v1, vcc
	v_lshlrev_b32_e32 v65, 2, v1
	v_xor_b32_e32 v1, 2, v227
	v_cmp_lt_i32_e32 vcc, v1, v0
	v_readlane_b32 s3, v250, 45
	v_readlane_b32 s12, v250, 27
	v_cndmask_b32_e32 v1, v227, v1, vcc
	v_lshlrev_b32_e32 v75, 2, v1
	v_xor_b32_e32 v1, 4, v227
	v_cmp_lt_i32_e32 vcc, v1, v0
	v_lshl_add_u64 v[68:69], s[2:3], 0, v[96:97]
	v_readlane_b32 s2, v250, 46
	v_cndmask_b32_e32 v1, v227, v1, vcc
	v_lshlrev_b32_e32 v80, 2, v1
	v_xor_b32_e32 v1, 8, v227
	v_cmp_lt_i32_e32 vcc, v1, v0
	v_readlane_b32 s3, v250, 47
	s_ashr_i32 s53, s52, 31
	v_cndmask_b32_e32 v1, v227, v1, vcc
	v_lshlrev_b32_e32 v81, 2, v1
	v_xor_b32_e32 v1, 16, v227
	v_cmp_lt_i32_e32 vcc, v1, v0
	v_readlane_b32 s13, v250, 28
	v_lshl_add_u64 v[70:71], s[2:3], 0, v[96:97]
	v_cndmask_b32_e32 v1, v227, v1, vcc
	s_lshl_b64 s[2:3], s[52:53], 11
	v_lshlrev_b32_e32 v82, 2, v1
	v_xor_b32_e32 v1, 32, v227
	v_lshl_add_u64 v[66:67], s[12:13], 0, v[96:97]
	s_add_u32 s12, s6, s2
	v_cmp_lt_i32_e32 vcc, v1, v0
	s_addc_u32 s13, s7, s3
	s_lshl_b64 s[2:3], s[52:53], 12
	v_cndmask_b32_e32 v0, v227, v1, vcc
	s_add_u32 s2, s72, s2
	v_lshlrev_b32_e32 v83, 2, v0
	v_lshlrev_b32_e32 v0, 2, v231
	s_addc_u32 s3, s73, s3
	v_lshl_add_u64 v[72:73], s[2:3], 0, v[96:97]
	v_lshlrev_b32_e32 v96, 1, v0
	s_mov_b32 s2, s52
	v_readlane_b32 s14, v250, 29
	v_readlane_b32 s15, v250, 30

.LBB0_281:
	v_readlane_b32 s2, v254, 58
	v_readlane_b32 s3, v254, 59
	s_mov_b64 s[56:57], s[84:85]
	s_andn2_b64 vcc, exec, s[2:3]
	s_mov_b64 s[58:59], s[86:87]
	s_cbranch_vccnz .LBB0_355
	v_readlane_b32 s2, v254, 60
	s_and_b32 s2, 0xffff, s2
	s_cmp_gt_i32 s2, 0
	s_mov_b64 s[12:13], -1
	s_cbranch_scc0 .LBB0_287
	v_readlane_b32 s44, v254, 34
	v_readlane_b32 s48, v254, 38
	s_cmpk_gt_i32 s52, 0x7fff
	v_readlane_b32 s16, v254, 18
	v_readlane_b32 s45, v254, 35
	v_readlane_b32 s49, v254, 39
	s_mov_b64 s[50:51], 0x200
	s_mov_b64 s[82:83], 0x400
	s_mov_b32 s17, s63
	s_mov_b64 s[62:63], 0x600
	s_cbranch_scc1 .LBB0_286
	v_readlane_b32 s2, v250, 0
	s_cmpk_lg_u32 s2, 0x100
	s_cbranch_scc1 .Lnrm_B_fallback
	v_lshrrev_b32_e32 v0, 6, v222
	v_and_b32_e32 v1, 63, v222
	v_readlane_b32 s4, v254, 48
	v_readfirstlane_b32 s3, v0
	v_readlane_b32 s82, v250, 2
	v_readlane_b32 s83, v250, 3
	s_lshl_b32 s4, s4, 3
	s_add_i32 s4, s4, s3
	s_load_dwordx2 s[18:19], s[82:83], 0x20
	s_load_dwordx2 s[12:13], s[82:83], 0x0
	s_lshr_b32 s2, s4, 7
	s_mul_i32 s2, s2, 0x9000
	s_add_u32 s20, s74, s2
	s_addc_u32 s21, s75, 0
	s_add_u32 s88, s20, 0x1000
	s_addc_u32 s89, s21, 0
	s_add_u32 s90, s20, 0x0
	s_addc_u32 s91, s21, 0
	v_lshlrev_b32_e32 v202, 5, v1
	v_lshlrev_b32_e32 v203, 4, v1
	s_lshl_b32 s11, s4, 16
	s_lshl_b32 s2, s4, 15
	s_add_u32 s48, s74, s2
	s_addc_u32 s49, s75, 0
	s_add_u32 s48, s48, 0x3000000
	s_addc_u32 s49, s49, 0
	s_waitcnt lgkmcnt(0)
	s_and_b32 s13, s13, 0xffff
	s_mov_b32 s14, 0x8000000
	s_mov_b32 s15, 0x20000
	global_load_dwordx4 v[64:67], v202, s[18:19]
	global_load_dwordx4 v[68:71], v202, s[18:19] offset:16
	global_load_dwordx4 v[72:75], v202, s[18:19] offset:2048
	global_load_dwordx4 v[76:79], v202, s[18:19] offset:2064
	global_load_dwordx4 v[80:83], v202, s[88:89]
	global_load_dwordx4 v[84:87], v202, s[88:89] offset:16
	global_load_dwordx4 v[88:91], v202, s[88:89] offset:2048
	global_load_dwordx4 v[92:95], v202, s[88:89] offset:2064
	global_load_dwordx4 v[162:165], v202, s[90:91]
	global_load_dwordx4 v[166:169], v202, s[90:91] offset:16
	global_load_dwordx4 v[170:173], v202, s[90:91] offset:2048
	global_load_dwordx4 v[174:177], v202, s[90:91] offset:2064
	buffer_load_dwordx4 v[0:3], v202, s[12:15], s11 offen sc1
	buffer_load_dwordx4 v[4:7], v202, s[12:15], s11 offen offset:16 sc1
	buffer_load_dwordx4 v[8:11], v202, s[12:15], s11 offen offset:2048 sc1
	buffer_load_dwordx4 v[12:15], v202, s[12:15], s11 offen offset:2064 sc1
	s_add_u32 s11, s11, 0x1000
	buffer_load_dwordx4 v[16:19], v202, s[12:15], s11 offen sc1
	buffer_load_dwordx4 v[20:23], v202, s[12:15], s11 offen offset:16 sc1
	buffer_load_dwordx4 v[24:27], v202, s[12:15], s11 offen offset:2048 sc1
	buffer_load_dwordx4 v[28:31], v202, s[12:15], s11 offen offset:2064 sc1
	s_add_u32 s11, s11, 0x1000
	buffer_load_dwordx4 v[32:35], v202, s[12:15], s11 offen sc1
	buffer_load_dwordx4 v[36:39], v202, s[12:15], s11 offen offset:16 sc1
	buffer_load_dwordx4 v[40:43], v202, s[12:15], s11 offen offset:2048 sc1
	buffer_load_dwordx4 v[44:47], v202, s[12:15], s11 offen offset:2064 sc1
	s_add_u32 s11, s11, 0x1000
	buffer_load_dwordx4 v[48:51], v202, s[12:15], s11 offen sc1
	buffer_load_dwordx4 v[52:55], v202, s[12:15], s11 offen offset:16 sc1
	buffer_load_dwordx4 v[56:59], v202, s[12:15], s11 offen offset:2048 sc1
	buffer_load_dwordx4 v[60:63], v202, s[12:15], s11 offen offset:2064 sc1
	s_add_u32 s11, s11, 0x1000
	buffer_load_dwordx4 v[98:101], v202, s[12:15], s11 offen sc1
	buffer_load_dwordx4 v[102:105], v202, s[12:15], s11 offen offset:16 sc1
	buffer_load_dwordx4 v[106:109], v202, s[12:15], s11 offen offset:2048 sc1
	buffer_load_dwordx4 v[110:113], v202, s[12:15], s11 offen offset:2064 sc1
	s_add_u32 s11, s11, 0x1000
	buffer_load_dwordx4 v[114:117], v202, s[12:15], s11 offen sc1
	buffer_load_dwordx4 v[118:121], v202, s[12:15], s11 offen offset:16 sc1
	buffer_load_dwordx4 v[122:125], v202, s[12:15], s11 offen offset:2048 sc1
	buffer_load_dwordx4 v[126:129], v202, s[12:15], s11 offen offset:2064 sc1
	s_add_u32 s11, s11, 0x1000
	buffer_load_dwordx4 v[130:133], v202, s[12:15], s11 offen sc1
	buffer_load_dwordx4 v[134:137], v202, s[12:15], s11 offen offset:16 sc1
	buffer_load_dwordx4 v[138:141], v202, s[12:15], s11 offen offset:2048 sc1
	buffer_load_dwordx4 v[142:145], v202, s[12:15], s11 offen offset:2064 sc1
	s_add_u32 s11, s11, 0x1000
	buffer_load_dwordx4 v[146:149], v202, s[12:15], s11 offen sc1
	buffer_load_dwordx4 v[150:153], v202, s[12:15], s11 offen offset:16 sc1
	buffer_load_dwordx4 v[154:157], v202, s[12:15], s11 offen offset:2048 sc1
	buffer_load_dwordx4 v[158:161], v202, s[12:15], s11 offen offset:2064 sc1
	s_add_u32 s11, s11, 0x1000
	s_waitcnt vmcnt(16)
	v_pk_add_f32 v[80:81], v[80:81], 1.0 op_sel_hi:[1,0]
	v_pk_add_f32 v[82:83], v[82:83], 1.0 op_sel_hi:[1,0]
	v_pk_add_f32 v[84:85], v[84:85], 1.0 op_sel_hi:[1,0]
	v_pk_add_f32 v[86:87], v[86:87], 1.0 op_sel_hi:[1,0]
	v_pk_add_f32 v[88:89], v[88:89], 1.0 op_sel_hi:[1,0]
	v_pk_add_f32 v[90:91], v[90:91], 1.0 op_sel_hi:[1,0]
	v_pk_add_f32 v[92:93], v[92:93], 1.0 op_sel_hi:[1,0]
	v_pk_add_f32 v[94:95], v[94:95], 1.0 op_sel_hi:[1,0]
	v_mul_f32_e32 v178, v0, v0
	v_mul_f32_e32 v179, v16, v16
	v_mul_f32_e32 v180, v32, v32
	v_mul_f32_e32 v181, v48, v48
	v_fma_f32 v178, v1, v1, v178
	v_fma_f32 v179, v17, v17, v179
	v_fma_f32 v180, v33, v33, v180
	v_fma_f32 v181, v49, v49, v181
	v_fma_f32 v178, v2, v2, v178
	v_fma_f32 v179, v18, v18, v179
	v_fma_f32 v180, v34, v34, v180
	v_fma_f32 v181, v50, v50, v181
	v_fma_f32 v178, v3, v3, v178
	v_fma_f32 v179, v19, v19, v179
	v_fma_f32 v180, v35, v35, v180
	v_fma_f32 v181, v51, v51, v181
	v_fma_f32 v178, v4, v4, v178
	v_fma_f32 v179, v20, v20, v179
	v_fma_f32 v180, v36, v36, v180
	v_fma_f32 v181, v52, v52, v181
	v_fma_f32 v178, v5, v5, v178
	v_fma_f32 v179, v21, v21, v179
	v_fma_f32 v180, v37, v37, v180
	v_fma_f32 v181, v53, v53, v181
	v_fma_f32 v178, v6, v6, v178
	v_fma_f32 v179, v22, v22, v179
	v_fma_f32 v180, v38, v38, v180
	v_fma_f32 v181, v54, v54, v181
	v_fma_f32 v178, v7, v7, v178
	v_fma_f32 v179, v23, v23, v179
	v_fma_f32 v180, v39, v39, v180
	v_fma_f32 v181, v55, v55, v181
	v_fma_f32 v178, v8, v8, v178
	v_fma_f32 v179, v24, v24, v179
	v_fma_f32 v180, v40, v40, v180
	v_fma_f32 v181, v56, v56, v181
	v_fma_f32 v178, v9, v9, v178
	v_fma_f32 v179, v25, v25, v179
	v_fma_f32 v180, v41, v41, v180
	v_fma_f32 v181, v57, v57, v181
	v_fma_f32 v178, v10, v10, v178
	v_fma_f32 v179, v26, v26, v179
	v_fma_f32 v180, v42, v42, v180
	v_fma_f32 v181, v58, v58, v181
	v_fma_f32 v178, v11, v11, v178
	v_fma_f32 v179, v27, v27, v179
	v_fma_f32 v180, v43, v43, v180
	v_fma_f32 v181, v59, v59, v181
	v_fma_f32 v178, v12, v12, v178
	v_fma_f32 v179, v28, v28, v179
	v_fma_f32 v180, v44, v44, v180
	v_fma_f32 v181, v60, v60, v181
	v_fma_f32 v178, v13, v13, v178
	v_fma_f32 v179, v29, v29, v179
	v_fma_f32 v180, v45, v45, v180
	v_fma_f32 v181, v61, v61, v181
	v_fma_f32 v178, v14, v14, v178
	v_fma_f32 v179, v30, v30, v179
	v_fma_f32 v180, v46, v46, v180
	v_fma_f32 v181, v62, v62, v181
	v_fma_f32 v178, v15, v15, v178
	v_fma_f32 v179, v31, v31, v179
	v_fma_f32 v180, v47, v47, v180
	v_fma_f32 v181, v63, v63, v181
	v_add_f32_dpp v178, v178, v178 quad_perm:[1,0,3,2] row_mask:0xf bank_mask:0xf
	v_add_f32_dpp v179, v179, v179 quad_perm:[1,0,3,2] row_mask:0xf bank_mask:0xf
	v_add_f32_dpp v180, v180, v180 quad_perm:[1,0,3,2] row_mask:0xf bank_mask:0xf
	v_add_f32_dpp v181, v181, v181 quad_perm:[1,0,3,2] row_mask:0xf bank_mask:0xf
	v_add_f32_dpp v178, v178, v178 quad_perm:[2,3,0,1] row_mask:0xf bank_mask:0xf
	v_add_f32_dpp v179, v179, v179 quad_perm:[2,3,0,1] row_mask:0xf bank_mask:0xf
	v_add_f32_dpp v180, v180, v180 quad_perm:[2,3,0,1] row_mask:0xf bank_mask:0xf
	v_add_f32_dpp v181, v181, v181 quad_perm:[2,3,0,1] row_mask:0xf bank_mask:0xf
	v_add_f32_dpp v178, v178, v178 row_half_mirror row_mask:0xf bank_mask:0xf
	v_add_f32_dpp v179, v179, v179 row_half_mirror row_mask:0xf bank_mask:0xf
	v_add_f32_dpp v180, v180, v180 row_half_mirror row_mask:0xf bank_mask:0xf
	v_add_f32_dpp v181, v181, v181 row_half_mirror row_mask:0xf bank_mask:0xf
	v_add_f32_dpp v178, v178, v178 row_ror:8 row_mask:0xf bank_mask:0xf
	v_add_f32_dpp v179, v179, v179 row_ror:8 row_mask:0xf bank_mask:0xf
	v_add_f32_dpp v180, v180, v180 row_ror:8 row_mask:0xf bank_mask:0xf
	v_add_f32_dpp v181, v181, v181 row_ror:8 row_mask:0xf bank_mask:0xf
	v_mov_b32_e32 v182, v178
	v_mov_b32_e32 v183, v179
	v_mov_b32_e32 v184, v180
	v_mov_b32_e32 v185, v181
	v_permlane16_swap_b32_e32 v182, v178
	v_permlane16_swap_b32_e32 v183, v179
	v_permlane16_swap_b32_e32 v184, v180
	v_permlane16_swap_b32_e32 v185, v181
	v_add_f32_e32 v178, v178, v182
	v_add_f32_e32 v179, v179, v183
	v_add_f32_e32 v180, v180, v184
	v_add_f32_e32 v181, v181, v185
	v_mov_b32_e32 v182, v178
	v_mov_b32_e32 v183, v179
	v_mov_b32_e32 v184, v180
	v_mov_b32_e32 v185, v181
	v_permlane32_swap_b32_e32 v182, v178
	v_permlane32_swap_b32_e32 v183, v179
	v_permlane32_swap_b32_e32 v184, v180
	v_permlane32_swap_b32_e32 v185, v181
	v_add_f32_e32 v178, v178, v182
	v_add_f32_e32 v179, v179, v183
	v_add_f32_e32 v180, v180, v184
	v_add_f32_e32 v181, v181, v185
	v_fmamk_f32 v198, v178, 0x3a800000, v225
	v_fmamk_f32 v199, v179, 0x3a800000, v225
	v_fmamk_f32 v200, v180, 0x3a800000, v225
	v_fmamk_f32 v201, v181, 0x3a800000, v225
	v_mul_f32_e32 v182, 0x4b800000, v198
	v_mul_f32_e32 v183, 0x4b800000, v199
	v_mul_f32_e32 v184, 0x4b800000, v200
	v_mul_f32_e32 v185, 0x4b800000, v201
	v_cmp_gt_f32_e64 s[2:3], s30, v198
	v_cmp_gt_f32_e64 s[50:51], s30, v199
	v_cmp_gt_f32_e64 s[88:89], s30, v200
	v_cmp_gt_f32_e64 s[90:91], s30, v201
	v_cndmask_b32_e64 v198, v198, v182, s[2:3]
	v_cndmask_b32_e64 v199, v199, v183, s[50:51]
	v_cndmask_b32_e64 v200, v200, v184, s[88:89]
	v_cndmask_b32_e64 v201, v201, v185, s[90:91]
	v_rsq_f32_e32 v198, v198
	v_rsq_f32_e32 v199, v199
	v_rsq_f32_e32 v200, v200
	v_rsq_f32_e32 v201, v201
	v_mul_f32_e32 v182, 0x45800000, v198
	v_mul_f32_e32 v183, 0x45800000, v199
	v_mul_f32_e32 v184, 0x45800000, v200
	v_mul_f32_e32 v185, 0x45800000, v201
	v_cndmask_b32_e64 v186, v198, v182, s[2:3]
	v_cndmask_b32_e64 v192, v199, v183, s[50:51]
	v_cndmask_b32_e64 v194, v200, v184, s[88:89]
	v_cndmask_b32_e64 v196, v201, v185, s[90:91]
	v_pk_mul_f32 v[0:1], v[186:187], v[0:1] op_sel_hi:[0,1]
	v_pk_mul_f32 v[2:3], v[186:187], v[2:3] op_sel_hi:[0,1]
	v_pk_mul_f32 v[4:5], v[186:187], v[4:5] op_sel_hi:[0,1]
	v_pk_mul_f32 v[6:7], v[186:187], v[6:7] op_sel_hi:[0,1]
	v_pk_mul_f32 v[8:9], v[186:187], v[8:9] op_sel_hi:[0,1]
	v_pk_mul_f32 v[10:11], v[186:187], v[10:11] op_sel_hi:[0,1]
	v_pk_mul_f32 v[12:13], v[186:187], v[12:13] op_sel_hi:[0,1]
	v_pk_mul_f32 v[14:15], v[186:187], v[14:15] op_sel_hi:[0,1]
	v_pk_mul_f32 v[0:1], v[64:65], v[0:1]
	v_pk_mul_f32 v[2:3], v[66:67], v[2:3]
	v_pk_mul_f32 v[4:5], v[68:69], v[4:5]
	v_pk_mul_f32 v[6:7], v[70:71], v[6:7]
	v_pk_mul_f32 v[8:9], v[72:73], v[8:9]
	v_pk_mul_f32 v[10:11], v[74:75], v[10:11]
	v_pk_mul_f32 v[12:13], v[76:77], v[12:13]
	v_pk_mul_f32 v[14:15], v[78:79], v[14:15]
	v_pk_fma_f32 v[0:1], v[80:81], v[0:1], v[162:163]
	v_pk_fma_f32 v[2:3], v[82:83], v[2:3], v[164:165]
	v_pk_fma_f32 v[4:5], v[84:85], v[4:5], v[166:167]
	v_pk_fma_f32 v[6:7], v[86:87], v[6:7], v[168:169]
	v_pk_fma_f32 v[8:9], v[88:89], v[8:9], v[170:171]
	v_pk_fma_f32 v[10:11], v[90:91], v[10:11], v[172:173]
	v_pk_fma_f32 v[12:13], v[92:93], v[12:13], v[174:175]
	v_pk_fma_f32 v[14:15], v[94:95], v[14:15], v[176:177]
	v_cvt_pk_bf16_f32 v204, v0, v1
	v_cvt_pk_bf16_f32 v205, v2, v3
	v_cvt_pk_bf16_f32 v206, v4, v5
	v_cvt_pk_bf16_f32 v207, v6, v7
	v_cvt_pk_bf16_f32 v208, v8, v9
	v_cvt_pk_bf16_f32 v209, v10, v11
	v_cvt_pk_bf16_f32 v210, v12, v13
	v_cvt_pk_bf16_f32 v211, v14, v15
	global_store_dwordx4 v203, v[204:207], s[48:49] sc1
	global_store_dwordx4 v203, v[208:211], s[48:49] offset:1024 sc1
	s_add_u32 s48, s48, 0x800
	s_addc_u32 s49, s49, 0
	v_pk_mul_f32 v[16:17], v[192:193], v[16:17] op_sel_hi:[0,1]
	v_pk_mul_f32 v[18:19], v[192:193], v[18:19] op_sel_hi:[0,1]
	v_pk_mul_f32 v[20:21], v[192:193], v[20:21] op_sel_hi:[0,1]
	v_pk_mul_f32 v[22:23], v[192:193], v[22:23] op_sel_hi:[0,1]
	v_pk_mul_f32 v[24:25], v[192:193], v[24:25] op_sel_hi:[0,1]
	v_pk_mul_f32 v[26:27], v[192:193], v[26:27] op_sel_hi:[0,1]
	v_pk_mul_f32 v[28:29], v[192:193], v[28:29] op_sel_hi:[0,1]
	v_pk_mul_f32 v[30:31], v[192:193], v[30:31] op_sel_hi:[0,1]
	v_pk_mul_f32 v[16:17], v[64:65], v[16:17]
	v_pk_mul_f32 v[18:19], v[66:67], v[18:19]
	v_pk_mul_f32 v[20:21], v[68:69], v[20:21]
	v_pk_mul_f32 v[22:23], v[70:71], v[22:23]
	v_pk_mul_f32 v[24:25], v[72:73], v[24:25]
	v_pk_mul_f32 v[26:27], v[74:75], v[26:27]
	v_pk_mul_f32 v[28:29], v[76:77], v[28:29]
	v_pk_mul_f32 v[30:31], v[78:79], v[30:31]
	v_pk_fma_f32 v[16:17], v[80:81], v[16:17], v[162:163]
	v_pk_fma_f32 v[18:19], v[82:83], v[18:19], v[164:165]
	v_pk_fma_f32 v[20:21], v[84:85], v[20:21], v[166:167]
	v_pk_fma_f32 v[22:23], v[86:87], v[22:23], v[168:169]
	v_pk_fma_f32 v[24:25], v[88:89], v[24:25], v[170:171]
	v_pk_fma_f32 v[26:27], v[90:91], v[26:27], v[172:173]
	v_pk_fma_f32 v[28:29], v[92:93], v[28:29], v[174:175]
	v_pk_fma_f32 v[30:31], v[94:95], v[30:31], v[176:177]
	v_cvt_pk_bf16_f32 v212, v16, v17
	v_cvt_pk_bf16_f32 v213, v18, v19
	v_cvt_pk_bf16_f32 v214, v20, v21
	v_cvt_pk_bf16_f32 v215, v22, v23
	v_cvt_pk_bf16_f32 v216, v24, v25
	v_cvt_pk_bf16_f32 v217, v26, v27
	v_cvt_pk_bf16_f32 v218, v28, v29
	v_cvt_pk_bf16_f32 v219, v30, v31
	global_store_dwordx4 v203, v[212:215], s[48:49] sc1
	global_store_dwordx4 v203, v[216:219], s[48:49] offset:1024 sc1
	s_add_u32 s48, s48, 0x800
	s_addc_u32 s49, s49, 0
	v_pk_mul_f32 v[32:33], v[194:195], v[32:33] op_sel_hi:[0,1]
	v_pk_mul_f32 v[34:35], v[194:195], v[34:35] op_sel_hi:[0,1]
	v_pk_mul_f32 v[36:37], v[194:195], v[36:37] op_sel_hi:[0,1]
	v_pk_mul_f32 v[38:39], v[194:195], v[38:39] op_sel_hi:[0,1]
	v_pk_mul_f32 v[40:41], v[194:195], v[40:41] op_sel_hi:[0,1]
	v_pk_mul_f32 v[42:43], v[194:195], v[42:43] op_sel_hi:[0,1]
	v_pk_mul_f32 v[44:45], v[194:195], v[44:45] op_sel_hi:[0,1]
	v_pk_mul_f32 v[46:47], v[194:195], v[46:47] op_sel_hi:[0,1]
	v_pk_mul_f32 v[32:33], v[64:65], v[32:33]
	v_pk_mul_f32 v[34:35], v[66:67], v[34:35]
	v_pk_mul_f32 v[36:37], v[68:69], v[36:37]
	v_pk_mul_f32 v[38:39], v[70:71], v[38:39]
	v_pk_mul_f32 v[40:41], v[72:73], v[40:41]
	v_pk_mul_f32 v[42:43], v[74:75], v[42:43]
	v_pk_mul_f32 v[44:45], v[76:77], v[44:45]
	v_pk_mul_f32 v[46:47], v[78:79], v[46:47]
	v_pk_fma_f32 v[32:33], v[80:81], v[32:33], v[162:163]
	v_pk_fma_f32 v[34:35], v[82:83], v[34:35], v[164:165]
	v_pk_fma_f32 v[36:37], v[84:85], v[36:37], v[166:167]
	v_pk_fma_f32 v[38:39], v[86:87], v[38:39], v[168:169]
	v_pk_fma_f32 v[40:41], v[88:89], v[40:41], v[170:171]
	v_pk_fma_f32 v[42:43], v[90:91], v[42:43], v[172:173]
	v_pk_fma_f32 v[44:45], v[92:93], v[44:45], v[174:175]
	v_pk_fma_f32 v[46:47], v[94:95], v[46:47], v[176:177]
	v_cvt_pk_bf16_f32 v204, v32, v33
	v_cvt_pk_bf16_f32 v205, v34, v35
	v_cvt_pk_bf16_f32 v206, v36, v37
	v_cvt_pk_bf16_f32 v207, v38, v39
	v_cvt_pk_bf16_f32 v208, v40, v41
	v_cvt_pk_bf16_f32 v209, v42, v43
	v_cvt_pk_bf16_f32 v210, v44, v45
	v_cvt_pk_bf16_f32 v211, v46, v47
	global_store_dwordx4 v203, v[204:207], s[48:49] sc1
	global_store_dwordx4 v203, v[208:211], s[48:49] offset:1024 sc1
	s_add_u32 s48, s48, 0x800
	s_addc_u32 s49, s49, 0
	v_pk_mul_f32 v[48:49], v[196:197], v[48:49] op_sel_hi:[0,1]
	v_pk_mul_f32 v[50:51], v[196:197], v[50:51] op_sel_hi:[0,1]
	v_pk_mul_f32 v[52:53], v[196:197], v[52:53] op_sel_hi:[0,1]
	v_pk_mul_f32 v[54:55], v[196:197], v[54:55] op_sel_hi:[0,1]
	v_pk_mul_f32 v[56:57], v[196:197], v[56:57] op_sel_hi:[0,1]
	v_pk_mul_f32 v[58:59], v[196:197], v[58:59] op_sel_hi:[0,1]
	v_pk_mul_f32 v[60:61], v[196:197], v[60:61] op_sel_hi:[0,1]
	v_pk_mul_f32 v[62:63], v[196:197], v[62:63] op_sel_hi:[0,1]
	v_pk_mul_f32 v[48:49], v[64:65], v[48:49]
	v_pk_mul_f32 v[50:51], v[66:67], v[50:51]
	v_pk_mul_f32 v[52:53], v[68:69], v[52:53]
	v_pk_mul_f32 v[54:55], v[70:71], v[54:55]
	v_pk_mul_f32 v[56:57], v[72:73], v[56:57]
	v_pk_mul_f32 v[58:59], v[74:75], v[58:59]
	v_pk_mul_f32 v[60:61], v[76:77], v[60:61]
	v_pk_mul_f32 v[62:63], v[78:79], v[62:63]
	v_pk_fma_f32 v[48:49], v[80:81], v[48:49], v[162:163]
	v_pk_fma_f32 v[50:51], v[82:83], v[50:51], v[164:165]
	v_pk_fma_f32 v[52:53], v[84:85], v[52:53], v[166:167]
	v_pk_fma_f32 v[54:55], v[86:87], v[54:55], v[168:169]
	v_pk_fma_f32 v[56:57], v[88:89], v[56:57], v[170:171]
	v_pk_fma_f32 v[58:59], v[90:91], v[58:59], v[172:173]
	v_pk_fma_f32 v[60:61], v[92:93], v[60:61], v[174:175]
	v_pk_fma_f32 v[62:63], v[94:95], v[62:63], v[176:177]
	v_cvt_pk_bf16_f32 v212, v48, v49
	v_cvt_pk_bf16_f32 v213, v50, v51
	v_cvt_pk_bf16_f32 v214, v52, v53
	v_cvt_pk_bf16_f32 v215, v54, v55
	v_cvt_pk_bf16_f32 v216, v56, v57
	v_cvt_pk_bf16_f32 v217, v58, v59
	v_cvt_pk_bf16_f32 v218, v60, v61
	v_cvt_pk_bf16_f32 v219, v62, v63
	global_store_dwordx4 v203, v[212:215], s[48:49] sc1
	global_store_dwordx4 v203, v[216:219], s[48:49] offset:1024 sc1
	s_add_u32 s48, s48, 0x800
	s_addc_u32 s49, s49, 0
	buffer_load_dwordx4 v[0:3], v202, s[12:15], s11 offen sc1
	buffer_load_dwordx4 v[4:7], v202, s[12:15], s11 offen offset:16 sc1
	buffer_load_dwordx4 v[8:11], v202, s[12:15], s11 offen offset:2048 sc1
	buffer_load_dwordx4 v[12:15], v202, s[12:15], s11 offen offset:2064 sc1
	s_add_u32 s11, s11, 0x1000
	buffer_load_dwordx4 v[16:19], v202, s[12:15], s11 offen sc1
	buffer_load_dwordx4 v[20:23], v202, s[12:15], s11 offen offset:16 sc1
	buffer_load_dwordx4 v[24:27], v202, s[12:15], s11 offen offset:2048 sc1
	buffer_load_dwordx4 v[28:31], v202, s[12:15], s11 offen offset:2064 sc1
	s_add_u32 s11, s11, 0x1000
	buffer_load_dwordx4 v[32:35], v202, s[12:15], s11 offen sc1
	buffer_load_dwordx4 v[36:39], v202, s[12:15], s11 offen offset:16 sc1
	buffer_load_dwordx4 v[40:43], v202, s[12:15], s11 offen offset:2048 sc1
	buffer_load_dwordx4 v[44:47], v202, s[12:15], s11 offen offset:2064 sc1
	s_add_u32 s11, s11, 0x1000
	buffer_load_dwordx4 v[48:51], v202, s[12:15], s11 offen sc1
	buffer_load_dwordx4 v[52:55], v202, s[12:15], s11 offen offset:16 sc1
	buffer_load_dwordx4 v[56:59], v202, s[12:15], s11 offen offset:2048 sc1
	buffer_load_dwordx4 v[60:63], v202, s[12:15], s11 offen offset:2064 sc1
	s_add_u32 s11, s11, 0x1000
	s_waitcnt vmcnt(24)
	v_mul_f32_e32 v178, v98, v98
	v_mul_f32_e32 v179, v114, v114
	v_mul_f32_e32 v180, v130, v130
	v_mul_f32_e32 v181, v146, v146
	v_fma_f32 v178, v99, v99, v178
	v_fma_f32 v179, v115, v115, v179
	v_fma_f32 v180, v131, v131, v180
	v_fma_f32 v181, v147, v147, v181
	v_fma_f32 v178, v100, v100, v178
	v_fma_f32 v179, v116, v116, v179
	v_fma_f32 v180, v132, v132, v180
	v_fma_f32 v181, v148, v148, v181
	v_fma_f32 v178, v101, v101, v178
	v_fma_f32 v179, v117, v117, v179
	v_fma_f32 v180, v133, v133, v180
	v_fma_f32 v181, v149, v149, v181
	v_fma_f32 v178, v102, v102, v178
	v_fma_f32 v179, v118, v118, v179
	v_fma_f32 v180, v134, v134, v180
	v_fma_f32 v181, v150, v150, v181
	v_fma_f32 v178, v103, v103, v178
	v_fma_f32 v179, v119, v119, v179
	v_fma_f32 v180, v135, v135, v180
	v_fma_f32 v181, v151, v151, v181
	v_fma_f32 v178, v104, v104, v178
	v_fma_f32 v179, v120, v120, v179
	v_fma_f32 v180, v136, v136, v180
	v_fma_f32 v181, v152, v152, v181
	v_fma_f32 v178, v105, v105, v178
	v_fma_f32 v179, v121, v121, v179
	v_fma_f32 v180, v137, v137, v180
	v_fma_f32 v181, v153, v153, v181
	v_fma_f32 v178, v106, v106, v178
	v_fma_f32 v179, v122, v122, v179
	v_fma_f32 v180, v138, v138, v180
	v_fma_f32 v181, v154, v154, v181
	v_fma_f32 v178, v107, v107, v178
	v_fma_f32 v179, v123, v123, v179
	v_fma_f32 v180, v139, v139, v180
	v_fma_f32 v181, v155, v155, v181
	v_fma_f32 v178, v108, v108, v178
	v_fma_f32 v179, v124, v124, v179
	v_fma_f32 v180, v140, v140, v180
	v_fma_f32 v181, v156, v156, v181
	v_fma_f32 v178, v109, v109, v178
	v_fma_f32 v179, v125, v125, v179
	v_fma_f32 v180, v141, v141, v180
	v_fma_f32 v181, v157, v157, v181
	v_fma_f32 v178, v110, v110, v178
	v_fma_f32 v179, v126, v126, v179
	v_fma_f32 v180, v142, v142, v180
	v_fma_f32 v181, v158, v158, v181
	v_fma_f32 v178, v111, v111, v178
	v_fma_f32 v179, v127, v127, v179
	v_fma_f32 v180, v143, v143, v180
	v_fma_f32 v181, v159, v159, v181
	v_fma_f32 v178, v112, v112, v178
	v_fma_f32 v179, v128, v128, v179
	v_fma_f32 v180, v144, v144, v180
	v_fma_f32 v181, v160, v160, v181
	v_fma_f32 v178, v113, v113, v178
	v_fma_f32 v179, v129, v129, v179
	v_fma_f32 v180, v145, v145, v180
	v_fma_f32 v181, v161, v161, v181
	v_add_f32_dpp v178, v178, v178 quad_perm:[1,0,3,2] row_mask:0xf bank_mask:0xf
	v_add_f32_dpp v179, v179, v179 quad_perm:[1,0,3,2] row_mask:0xf bank_mask:0xf
	v_add_f32_dpp v180, v180, v180 quad_perm:[1,0,3,2] row_mask:0xf bank_mask:0xf
	v_add_f32_dpp v181, v181, v181 quad_perm:[1,0,3,2] row_mask:0xf bank_mask:0xf
	v_add_f32_dpp v178, v178, v178 quad_perm:[2,3,0,1] row_mask:0xf bank_mask:0xf
	v_add_f32_dpp v179, v179, v179 quad_perm:[2,3,0,1] row_mask:0xf bank_mask:0xf
	v_add_f32_dpp v180, v180, v180 quad_perm:[2,3,0,1] row_mask:0xf bank_mask:0xf
	v_add_f32_dpp v181, v181, v181 quad_perm:[2,3,0,1] row_mask:0xf bank_mask:0xf
	v_add_f32_dpp v178, v178, v178 row_half_mirror row_mask:0xf bank_mask:0xf
	v_add_f32_dpp v179, v179, v179 row_half_mirror row_mask:0xf bank_mask:0xf
	v_add_f32_dpp v180, v180, v180 row_half_mirror row_mask:0xf bank_mask:0xf
	v_add_f32_dpp v181, v181, v181 row_half_mirror row_mask:0xf bank_mask:0xf
	v_add_f32_dpp v178, v178, v178 row_ror:8 row_mask:0xf bank_mask:0xf
	v_add_f32_dpp v179, v179, v179 row_ror:8 row_mask:0xf bank_mask:0xf
	v_add_f32_dpp v180, v180, v180 row_ror:8 row_mask:0xf bank_mask:0xf
	v_add_f32_dpp v181, v181, v181 row_ror:8 row_mask:0xf bank_mask:0xf
	v_mov_b32_e32 v182, v178
	v_mov_b32_e32 v183, v179
	v_mov_b32_e32 v184, v180
	v_mov_b32_e32 v185, v181
	v_permlane16_swap_b32_e32 v182, v178
	v_permlane16_swap_b32_e32 v183, v179
	v_permlane16_swap_b32_e32 v184, v180
	v_permlane16_swap_b32_e32 v185, v181
	v_add_f32_e32 v178, v178, v182
	v_add_f32_e32 v179, v179, v183
	v_add_f32_e32 v180, v180, v184
	v_add_f32_e32 v181, v181, v185
	v_mov_b32_e32 v182, v178
	v_mov_b32_e32 v183, v179
	v_mov_b32_e32 v184, v180
	v_mov_b32_e32 v185, v181
	v_permlane32_swap_b32_e32 v182, v178
	v_permlane32_swap_b32_e32 v183, v179
	v_permlane32_swap_b32_e32 v184, v180
	v_permlane32_swap_b32_e32 v185, v181
	v_add_f32_e32 v178, v178, v182
	v_add_f32_e32 v179, v179, v183
	v_add_f32_e32 v180, v180, v184
	v_add_f32_e32 v181, v181, v185
	v_fmamk_f32 v198, v178, 0x3a800000, v225
	v_fmamk_f32 v199, v179, 0x3a800000, v225
	v_fmamk_f32 v200, v180, 0x3a800000, v225
	v_fmamk_f32 v201, v181, 0x3a800000, v225
	v_mul_f32_e32 v182, 0x4b800000, v198
	v_mul_f32_e32 v183, 0x4b800000, v199
	v_mul_f32_e32 v184, 0x4b800000, v200
	v_mul_f32_e32 v185, 0x4b800000, v201
	v_cmp_gt_f32_e64 s[2:3], s30, v198
	v_cmp_gt_f32_e64 s[50:51], s30, v199
	v_cmp_gt_f32_e64 s[88:89], s30, v200
	v_cmp_gt_f32_e64 s[90:91], s30, v201
	v_cndmask_b32_e64 v198, v198, v182, s[2:3]
	v_cndmask_b32_e64 v199, v199, v183, s[50:51]
	v_cndmask_b32_e64 v200, v200, v184, s[88:89]
	v_cndmask_b32_e64 v201, v201, v185, s[90:91]
	v_rsq_f32_e32 v198, v198
	v_rsq_f32_e32 v199, v199
	v_rsq_f32_e32 v200, v200
	v_rsq_f32_e32 v201, v201
	v_mul_f32_e32 v182, 0x45800000, v198
	v_mul_f32_e32 v183, 0x45800000, v199
	v_mul_f32_e32 v184, 0x45800000, v200
	v_mul_f32_e32 v185, 0x45800000, v201
	v_cndmask_b32_e64 v186, v198, v182, s[2:3]
	v_cndmask_b32_e64 v192, v199, v183, s[50:51]
	v_cndmask_b32_e64 v194, v200, v184, s[88:89]
	v_cndmask_b32_e64 v196, v201, v185, s[90:91]
	v_pk_mul_f32 v[98:99], v[186:187], v[98:99] op_sel_hi:[0,1]
	v_pk_mul_f32 v[100:101], v[186:187], v[100:101] op_sel_hi:[0,1]
	v_pk_mul_f32 v[102:103], v[186:187], v[102:103] op_sel_hi:[0,1]
	v_pk_mul_f32 v[104:105], v[186:187], v[104:105] op_sel_hi:[0,1]
	v_pk_mul_f32 v[106:107], v[186:187], v[106:107] op_sel_hi:[0,1]
	v_pk_mul_f32 v[108:109], v[186:187], v[108:109] op_sel_hi:[0,1]
	v_pk_mul_f32 v[110:111], v[186:187], v[110:111] op_sel_hi:[0,1]
	v_pk_mul_f32 v[112:113], v[186:187], v[112:113] op_sel_hi:[0,1]
	v_pk_mul_f32 v[98:99], v[64:65], v[98:99]
	v_pk_mul_f32 v[100:101], v[66:67], v[100:101]
	v_pk_mul_f32 v[102:103], v[68:69], v[102:103]
	v_pk_mul_f32 v[104:105], v[70:71], v[104:105]
	v_pk_mul_f32 v[106:107], v[72:73], v[106:107]
	v_pk_mul_f32 v[108:109], v[74:75], v[108:109]
	v_pk_mul_f32 v[110:111], v[76:77], v[110:111]
	v_pk_mul_f32 v[112:113], v[78:79], v[112:113]
	v_pk_fma_f32 v[98:99], v[80:81], v[98:99], v[162:163]
	v_pk_fma_f32 v[100:101], v[82:83], v[100:101], v[164:165]
	v_pk_fma_f32 v[102:103], v[84:85], v[102:103], v[166:167]
	v_pk_fma_f32 v[104:105], v[86:87], v[104:105], v[168:169]
	v_pk_fma_f32 v[106:107], v[88:89], v[106:107], v[170:171]
	v_pk_fma_f32 v[108:109], v[90:91], v[108:109], v[172:173]
	v_pk_fma_f32 v[110:111], v[92:93], v[110:111], v[174:175]
	v_pk_fma_f32 v[112:113], v[94:95], v[112:113], v[176:177]
	v_cvt_pk_bf16_f32 v204, v98, v99
	v_cvt_pk_bf16_f32 v205, v100, v101
	v_cvt_pk_bf16_f32 v206, v102, v103
	v_cvt_pk_bf16_f32 v207, v104, v105
	v_cvt_pk_bf16_f32 v208, v106, v107
	v_cvt_pk_bf16_f32 v209, v108, v109
	v_cvt_pk_bf16_f32 v210, v110, v111
	v_cvt_pk_bf16_f32 v211, v112, v113
	global_store_dwordx4 v203, v[204:207], s[48:49] sc1
	global_store_dwordx4 v203, v[208:211], s[48:49] offset:1024 sc1
	s_add_u32 s48, s48, 0x800
	s_addc_u32 s49, s49, 0
	v_pk_mul_f32 v[114:115], v[192:193], v[114:115] op_sel_hi:[0,1]
	v_pk_mul_f32 v[116:117], v[192:193], v[116:117] op_sel_hi:[0,1]
	v_pk_mul_f32 v[118:119], v[192:193], v[118:119] op_sel_hi:[0,1]
	v_pk_mul_f32 v[120:121], v[192:193], v[120:121] op_sel_hi:[0,1]
	v_pk_mul_f32 v[122:123], v[192:193], v[122:123] op_sel_hi:[0,1]
	v_pk_mul_f32 v[124:125], v[192:193], v[124:125] op_sel_hi:[0,1]
	v_pk_mul_f32 v[126:127], v[192:193], v[126:127] op_sel_hi:[0,1]
	v_pk_mul_f32 v[128:129], v[192:193], v[128:129] op_sel_hi:[0,1]
	v_pk_mul_f32 v[114:115], v[64:65], v[114:115]
	v_pk_mul_f32 v[116:117], v[66:67], v[116:117]
	v_pk_mul_f32 v[118:119], v[68:69], v[118:119]
	v_pk_mul_f32 v[120:121], v[70:71], v[120:121]
	v_pk_mul_f32 v[122:123], v[72:73], v[122:123]
	v_pk_mul_f32 v[124:125], v[74:75], v[124:125]
	v_pk_mul_f32 v[126:127], v[76:77], v[126:127]
	v_pk_mul_f32 v[128:129], v[78:79], v[128:129]
	v_pk_fma_f32 v[114:115], v[80:81], v[114:115], v[162:163]
	v_pk_fma_f32 v[116:117], v[82:83], v[116:117], v[164:165]
	v_pk_fma_f32 v[118:119], v[84:85], v[118:119], v[166:167]
	v_pk_fma_f32 v[120:121], v[86:87], v[120:121], v[168:169]
	v_pk_fma_f32 v[122:123], v[88:89], v[122:123], v[170:171]
	v_pk_fma_f32 v[124:125], v[90:91], v[124:125], v[172:173]
	v_pk_fma_f32 v[126:127], v[92:93], v[126:127], v[174:175]
	v_pk_fma_f32 v[128:129], v[94:95], v[128:129], v[176:177]
	v_cvt_pk_bf16_f32 v212, v114, v115
	v_cvt_pk_bf16_f32 v213, v116, v117
	v_cvt_pk_bf16_f32 v214, v118, v119
	v_cvt_pk_bf16_f32 v215, v120, v121
	v_cvt_pk_bf16_f32 v216, v122, v123
	v_cvt_pk_bf16_f32 v217, v124, v125
	v_cvt_pk_bf16_f32 v218, v126, v127
	v_cvt_pk_bf16_f32 v219, v128, v129
	global_store_dwordx4 v203, v[212:215], s[48:49] sc1
	global_store_dwordx4 v203, v[216:219], s[48:49] offset:1024 sc1
	s_add_u32 s48, s48, 0x800
	s_addc_u32 s49, s49, 0
	v_pk_mul_f32 v[130:131], v[194:195], v[130:131] op_sel_hi:[0,1]
	v_pk_mul_f32 v[132:133], v[194:195], v[132:133] op_sel_hi:[0,1]
	v_pk_mul_f32 v[134:135], v[194:195], v[134:135] op_sel_hi:[0,1]
	v_pk_mul_f32 v[136:137], v[194:195], v[136:137] op_sel_hi:[0,1]
	v_pk_mul_f32 v[138:139], v[194:195], v[138:139] op_sel_hi:[0,1]
	v_pk_mul_f32 v[140:141], v[194:195], v[140:141] op_sel_hi:[0,1]
	v_pk_mul_f32 v[142:143], v[194:195], v[142:143] op_sel_hi:[0,1]
	v_pk_mul_f32 v[144:145], v[194:195], v[144:145] op_sel_hi:[0,1]
	v_pk_mul_f32 v[130:131], v[64:65], v[130:131]
	v_pk_mul_f32 v[132:133], v[66:67], v[132:133]
	v_pk_mul_f32 v[134:135], v[68:69], v[134:135]
	v_pk_mul_f32 v[136:137], v[70:71], v[136:137]
	v_pk_mul_f32 v[138:139], v[72:73], v[138:139]
	v_pk_mul_f32 v[140:141], v[74:75], v[140:141]
	v_pk_mul_f32 v[142:143], v[76:77], v[142:143]
	v_pk_mul_f32 v[144:145], v[78:79], v[144:145]
	v_pk_fma_f32 v[130:131], v[80:81], v[130:131], v[162:163]
	v_pk_fma_f32 v[132:133], v[82:83], v[132:133], v[164:165]
	v_pk_fma_f32 v[134:135], v[84:85], v[134:135], v[166:167]
	v_pk_fma_f32 v[136:137], v[86:87], v[136:137], v[168:169]
	v_pk_fma_f32 v[138:139], v[88:89], v[138:139], v[170:171]
	v_pk_fma_f32 v[140:141], v[90:91], v[140:141], v[172:173]
	v_pk_fma_f32 v[142:143], v[92:93], v[142:143], v[174:175]
	v_pk_fma_f32 v[144:145], v[94:95], v[144:145], v[176:177]
	v_cvt_pk_bf16_f32 v204, v130, v131
	v_cvt_pk_bf16_f32 v205, v132, v133
	v_cvt_pk_bf16_f32 v206, v134, v135
	v_cvt_pk_bf16_f32 v207, v136, v137
	v_cvt_pk_bf16_f32 v208, v138, v139
	v_cvt_pk_bf16_f32 v209, v140, v141
	v_cvt_pk_bf16_f32 v210, v142, v143
	v_cvt_pk_bf16_f32 v211, v144, v145
	global_store_dwordx4 v203, v[204:207], s[48:49] sc1
	global_store_dwordx4 v203, v[208:211], s[48:49] offset:1024 sc1
	s_add_u32 s48, s48, 0x800
	s_addc_u32 s49, s49, 0
	v_pk_mul_f32 v[146:147], v[196:197], v[146:147] op_sel_hi:[0,1]
	v_pk_mul_f32 v[148:149], v[196:197], v[148:149] op_sel_hi:[0,1]
	v_pk_mul_f32 v[150:151], v[196:197], v[150:151] op_sel_hi:[0,1]
	v_pk_mul_f32 v[152:153], v[196:197], v[152:153] op_sel_hi:[0,1]
	v_pk_mul_f32 v[154:155], v[196:197], v[154:155] op_sel_hi:[0,1]
	v_pk_mul_f32 v[156:157], v[196:197], v[156:157] op_sel_hi:[0,1]
	v_pk_mul_f32 v[158:159], v[196:197], v[158:159] op_sel_hi:[0,1]
	v_pk_mul_f32 v[160:161], v[196:197], v[160:161] op_sel_hi:[0,1]
	v_pk_mul_f32 v[146:147], v[64:65], v[146:147]
	v_pk_mul_f32 v[148:149], v[66:67], v[148:149]
	v_pk_mul_f32 v[150:151], v[68:69], v[150:151]
	v_pk_mul_f32 v[152:153], v[70:71], v[152:153]
	v_pk_mul_f32 v[154:155], v[72:73], v[154:155]
	v_pk_mul_f32 v[156:157], v[74:75], v[156:157]
	v_pk_mul_f32 v[158:159], v[76:77], v[158:159]
	v_pk_mul_f32 v[160:161], v[78:79], v[160:161]
	v_pk_fma_f32 v[146:147], v[80:81], v[146:147], v[162:163]
	v_pk_fma_f32 v[148:149], v[82:83], v[148:149], v[164:165]
	v_pk_fma_f32 v[150:151], v[84:85], v[150:151], v[166:167]
	v_pk_fma_f32 v[152:153], v[86:87], v[152:153], v[168:169]
	v_pk_fma_f32 v[154:155], v[88:89], v[154:155], v[170:171]
	v_pk_fma_f32 v[156:157], v[90:91], v[156:157], v[172:173]
	v_pk_fma_f32 v[158:159], v[92:93], v[158:159], v[174:175]
	v_pk_fma_f32 v[160:161], v[94:95], v[160:161], v[176:177]
	v_cvt_pk_bf16_f32 v212, v146, v147
	v_cvt_pk_bf16_f32 v213, v148, v149
	v_cvt_pk_bf16_f32 v214, v150, v151
	v_cvt_pk_bf16_f32 v215, v152, v153
	v_cvt_pk_bf16_f32 v216, v154, v155
	v_cvt_pk_bf16_f32 v217, v156, v157
	v_cvt_pk_bf16_f32 v218, v158, v159
	v_cvt_pk_bf16_f32 v219, v160, v161
	global_store_dwordx4 v203, v[212:215], s[48:49] sc1
	global_store_dwordx4 v203, v[216:219], s[48:49] offset:1024 sc1
	s_add_u32 s48, s48, 0x800
	s_addc_u32 s49, s49, 0
	buffer_load_dwordx4 v[98:101], v202, s[12:15], s11 offen sc1
	buffer_load_dwordx4 v[102:105], v202, s[12:15], s11 offen offset:16 sc1
	buffer_load_dwordx4 v[106:109], v202, s[12:15], s11 offen offset:2048 sc1
	buffer_load_dwordx4 v[110:113], v202, s[12:15], s11 offen offset:2064 sc1
	s_add_u32 s11, s11, 0x1000
	buffer_load_dwordx4 v[114:117], v202, s[12:15], s11 offen sc1
	buffer_load_dwordx4 v[118:121], v202, s[12:15], s11 offen offset:16 sc1
	buffer_load_dwordx4 v[122:125], v202, s[12:15], s11 offen offset:2048 sc1
	buffer_load_dwordx4 v[126:129], v202, s[12:15], s11 offen offset:2064 sc1
	s_add_u32 s11, s11, 0x1000
	buffer_load_dwordx4 v[130:133], v202, s[12:15], s11 offen sc1
	buffer_load_dwordx4 v[134:137], v202, s[12:15], s11 offen offset:16 sc1
	buffer_load_dwordx4 v[138:141], v202, s[12:15], s11 offen offset:2048 sc1
	buffer_load_dwordx4 v[142:145], v202, s[12:15], s11 offen offset:2064 sc1
	s_add_u32 s11, s11, 0x1000
	buffer_load_dwordx4 v[146:149], v202, s[12:15], s11 offen sc1
	buffer_load_dwordx4 v[150:153], v202, s[12:15], s11 offen offset:16 sc1
	buffer_load_dwordx4 v[154:157], v202, s[12:15], s11 offen offset:2048 sc1
	buffer_load_dwordx4 v[158:161], v202, s[12:15], s11 offen offset:2064 sc1
	s_add_u32 s11, s11, 0x1000
	s_waitcnt vmcnt(24)
	v_mul_f32_e32 v178, v0, v0
	v_mul_f32_e32 v179, v16, v16
	v_mul_f32_e32 v180, v32, v32
	v_mul_f32_e32 v181, v48, v48
	v_fma_f32 v178, v1, v1, v178
	v_fma_f32 v179, v17, v17, v179
	v_fma_f32 v180, v33, v33, v180
	v_fma_f32 v181, v49, v49, v181
	v_fma_f32 v178, v2, v2, v178
	v_fma_f32 v179, v18, v18, v179
	v_fma_f32 v180, v34, v34, v180
	v_fma_f32 v181, v50, v50, v181
	v_fma_f32 v178, v3, v3, v178
	v_fma_f32 v179, v19, v19, v179
	v_fma_f32 v180, v35, v35, v180
	v_fma_f32 v181, v51, v51, v181
	v_fma_f32 v178, v4, v4, v178
	v_fma_f32 v179, v20, v20, v179
	v_fma_f32 v180, v36, v36, v180
	v_fma_f32 v181, v52, v52, v181
	v_fma_f32 v178, v5, v5, v178
	v_fma_f32 v179, v21, v21, v179
	v_fma_f32 v180, v37, v37, v180
	v_fma_f32 v181, v53, v53, v181
	v_fma_f32 v178, v6, v6, v178
	v_fma_f32 v179, v22, v22, v179
	v_fma_f32 v180, v38, v38, v180
	v_fma_f32 v181, v54, v54, v181
	v_fma_f32 v178, v7, v7, v178
	v_fma_f32 v179, v23, v23, v179
	v_fma_f32 v180, v39, v39, v180
	v_fma_f32 v181, v55, v55, v181
	v_fma_f32 v178, v8, v8, v178
	v_fma_f32 v179, v24, v24, v179
	v_fma_f32 v180, v40, v40, v180
	v_fma_f32 v181, v56, v56, v181
	v_fma_f32 v178, v9, v9, v178
	v_fma_f32 v179, v25, v25, v179
	v_fma_f32 v180, v41, v41, v180
	v_fma_f32 v181, v57, v57, v181
	v_fma_f32 v178, v10, v10, v178
	v_fma_f32 v179, v26, v26, v179
	v_fma_f32 v180, v42, v42, v180
	v_fma_f32 v181, v58, v58, v181
	v_fma_f32 v178, v11, v11, v178
	v_fma_f32 v179, v27, v27, v179
	v_fma_f32 v180, v43, v43, v180
	v_fma_f32 v181, v59, v59, v181
	v_fma_f32 v178, v12, v12, v178
	v_fma_f32 v179, v28, v28, v179
	v_fma_f32 v180, v44, v44, v180
	v_fma_f32 v181, v60, v60, v181
	v_fma_f32 v178, v13, v13, v178
	v_fma_f32 v179, v29, v29, v179
	v_fma_f32 v180, v45, v45, v180
	v_fma_f32 v181, v61, v61, v181
	v_fma_f32 v178, v14, v14, v178
	v_fma_f32 v179, v30, v30, v179
	v_fma_f32 v180, v46, v46, v180
	v_fma_f32 v181, v62, v62, v181
	v_fma_f32 v178, v15, v15, v178
	v_fma_f32 v179, v31, v31, v179
	v_fma_f32 v180, v47, v47, v180
	v_fma_f32 v181, v63, v63, v181
	v_add_f32_dpp v178, v178, v178 quad_perm:[1,0,3,2] row_mask:0xf bank_mask:0xf
	v_add_f32_dpp v179, v179, v179 quad_perm:[1,0,3,2] row_mask:0xf bank_mask:0xf
	v_add_f32_dpp v180, v180, v180 quad_perm:[1,0,3,2] row_mask:0xf bank_mask:0xf
	v_add_f32_dpp v181, v181, v181 quad_perm:[1,0,3,2] row_mask:0xf bank_mask:0xf
	v_add_f32_dpp v178, v178, v178 quad_perm:[2,3,0,1] row_mask:0xf bank_mask:0xf
	v_add_f32_dpp v179, v179, v179 quad_perm:[2,3,0,1] row_mask:0xf bank_mask:0xf
	v_add_f32_dpp v180, v180, v180 quad_perm:[2,3,0,1] row_mask:0xf bank_mask:0xf
	v_add_f32_dpp v181, v181, v181 quad_perm:[2,3,0,1] row_mask:0xf bank_mask:0xf
	v_add_f32_dpp v178, v178, v178 row_half_mirror row_mask:0xf bank_mask:0xf
	v_add_f32_dpp v179, v179, v179 row_half_mirror row_mask:0xf bank_mask:0xf
	v_add_f32_dpp v180, v180, v180 row_half_mirror row_mask:0xf bank_mask:0xf
	v_add_f32_dpp v181, v181, v181 row_half_mirror row_mask:0xf bank_mask:0xf
	v_add_f32_dpp v178, v178, v178 row_ror:8 row_mask:0xf bank_mask:0xf
	v_add_f32_dpp v179, v179, v179 row_ror:8 row_mask:0xf bank_mask:0xf
	v_add_f32_dpp v180, v180, v180 row_ror:8 row_mask:0xf bank_mask:0xf
	v_add_f32_dpp v181, v181, v181 row_ror:8 row_mask:0xf bank_mask:0xf
	v_mov_b32_e32 v182, v178
	v_mov_b32_e32 v183, v179
	v_mov_b32_e32 v184, v180
	v_mov_b32_e32 v185, v181
	v_permlane16_swap_b32_e32 v182, v178
	v_permlane16_swap_b32_e32 v183, v179
	v_permlane16_swap_b32_e32 v184, v180
	v_permlane16_swap_b32_e32 v185, v181
	v_add_f32_e32 v178, v178, v182
	v_add_f32_e32 v179, v179, v183
	v_add_f32_e32 v180, v180, v184
	v_add_f32_e32 v181, v181, v185
	v_mov_b32_e32 v182, v178
	v_mov_b32_e32 v183, v179
	v_mov_b32_e32 v184, v180
	v_mov_b32_e32 v185, v181
	v_permlane32_swap_b32_e32 v182, v178
	v_permlane32_swap_b32_e32 v183, v179
	v_permlane32_swap_b32_e32 v184, v180
	v_permlane32_swap_b32_e32 v185, v181
	v_add_f32_e32 v178, v178, v182
	v_add_f32_e32 v179, v179, v183
	v_add_f32_e32 v180, v180, v184
	v_add_f32_e32 v181, v181, v185
	v_fmamk_f32 v198, v178, 0x3a800000, v225
	v_fmamk_f32 v199, v179, 0x3a800000, v225
	v_fmamk_f32 v200, v180, 0x3a800000, v225
	v_fmamk_f32 v201, v181, 0x3a800000, v225
	v_mul_f32_e32 v182, 0x4b800000, v198
	v_mul_f32_e32 v183, 0x4b800000, v199
	v_mul_f32_e32 v184, 0x4b800000, v200
	v_mul_f32_e32 v185, 0x4b800000, v201
	v_cmp_gt_f32_e64 s[2:3], s30, v198
	v_cmp_gt_f32_e64 s[50:51], s30, v199
	v_cmp_gt_f32_e64 s[88:89], s30, v200
	v_cmp_gt_f32_e64 s[90:91], s30, v201
	v_cndmask_b32_e64 v198, v198, v182, s[2:3]
	v_cndmask_b32_e64 v199, v199, v183, s[50:51]
	v_cndmask_b32_e64 v200, v200, v184, s[88:89]
	v_cndmask_b32_e64 v201, v201, v185, s[90:91]
	v_rsq_f32_e32 v198, v198
	v_rsq_f32_e32 v199, v199
	v_rsq_f32_e32 v200, v200
	v_rsq_f32_e32 v201, v201
	v_mul_f32_e32 v182, 0x45800000, v198
	v_mul_f32_e32 v183, 0x45800000, v199
	v_mul_f32_e32 v184, 0x45800000, v200
	v_mul_f32_e32 v185, 0x45800000, v201
	v_cndmask_b32_e64 v186, v198, v182, s[2:3]
	v_cndmask_b32_e64 v192, v199, v183, s[50:51]
	v_cndmask_b32_e64 v194, v200, v184, s[88:89]
	v_cndmask_b32_e64 v196, v201, v185, s[90:91]
	v_pk_mul_f32 v[0:1], v[186:187], v[0:1] op_sel_hi:[0,1]
	v_pk_mul_f32 v[2:3], v[186:187], v[2:3] op_sel_hi:[0,1]
	v_pk_mul_f32 v[4:5], v[186:187], v[4:5] op_sel_hi:[0,1]
	v_pk_mul_f32 v[6:7], v[186:187], v[6:7] op_sel_hi:[0,1]
	v_pk_mul_f32 v[8:9], v[186:187], v[8:9] op_sel_hi:[0,1]
	v_pk_mul_f32 v[10:11], v[186:187], v[10:11] op_sel_hi:[0,1]
	v_pk_mul_f32 v[12:13], v[186:187], v[12:13] op_sel_hi:[0,1]
	v_pk_mul_f32 v[14:15], v[186:187], v[14:15] op_sel_hi:[0,1]
	v_pk_mul_f32 v[0:1], v[64:65], v[0:1]
	v_pk_mul_f32 v[2:3], v[66:67], v[2:3]
	v_pk_mul_f32 v[4:5], v[68:69], v[4:5]
	v_pk_mul_f32 v[6:7], v[70:71], v[6:7]
	v_pk_mul_f32 v[8:9], v[72:73], v[8:9]
	v_pk_mul_f32 v[10:11], v[74:75], v[10:11]
	v_pk_mul_f32 v[12:13], v[76:77], v[12:13]
	v_pk_mul_f32 v[14:15], v[78:79], v[14:15]
	v_pk_fma_f32 v[0:1], v[80:81], v[0:1], v[162:163]
	v_pk_fma_f32 v[2:3], v[82:83], v[2:3], v[164:165]
	v_pk_fma_f32 v[4:5], v[84:85], v[4:5], v[166:167]
	v_pk_fma_f32 v[6:7], v[86:87], v[6:7], v[168:169]
	v_pk_fma_f32 v[8:9], v[88:89], v[8:9], v[170:171]
	v_pk_fma_f32 v[10:11], v[90:91], v[10:11], v[172:173]
	v_pk_fma_f32 v[12:13], v[92:93], v[12:13], v[174:175]
	v_pk_fma_f32 v[14:15], v[94:95], v[14:15], v[176:177]
	v_cvt_pk_bf16_f32 v204, v0, v1
	v_cvt_pk_bf16_f32 v205, v2, v3
	v_cvt_pk_bf16_f32 v206, v4, v5
	v_cvt_pk_bf16_f32 v207, v6, v7
	v_cvt_pk_bf16_f32 v208, v8, v9
	v_cvt_pk_bf16_f32 v209, v10, v11
	v_cvt_pk_bf16_f32 v210, v12, v13
	v_cvt_pk_bf16_f32 v211, v14, v15
	global_store_dwordx4 v203, v[204:207], s[48:49] sc1
	global_store_dwordx4 v203, v[208:211], s[48:49] offset:1024 sc1
	s_add_u32 s48, s48, 0x800
	s_addc_u32 s49, s49, 0
	v_pk_mul_f32 v[16:17], v[192:193], v[16:17] op_sel_hi:[0,1]
	v_pk_mul_f32 v[18:19], v[192:193], v[18:19] op_sel_hi:[0,1]
	v_pk_mul_f32 v[20:21], v[192:193], v[20:21] op_sel_hi:[0,1]
	v_pk_mul_f32 v[22:23], v[192:193], v[22:23] op_sel_hi:[0,1]
	v_pk_mul_f32 v[24:25], v[192:193], v[24:25] op_sel_hi:[0,1]
	v_pk_mul_f32 v[26:27], v[192:193], v[26:27] op_sel_hi:[0,1]
	v_pk_mul_f32 v[28:29], v[192:193], v[28:29] op_sel_hi:[0,1]
	v_pk_mul_f32 v[30:31], v[192:193], v[30:31] op_sel_hi:[0,1]
	v_pk_mul_f32 v[16:17], v[64:65], v[16:17]
	v_pk_mul_f32 v[18:19], v[66:67], v[18:19]
	v_pk_mul_f32 v[20:21], v[68:69], v[20:21]
	v_pk_mul_f32 v[22:23], v[70:71], v[22:23]
	v_pk_mul_f32 v[24:25], v[72:73], v[24:25]
	v_pk_mul_f32 v[26:27], v[74:75], v[26:27]
	v_pk_mul_f32 v[28:29], v[76:77], v[28:29]
	v_pk_mul_f32 v[30:31], v[78:79], v[30:31]
	v_pk_fma_f32 v[16:17], v[80:81], v[16:17], v[162:163]
	v_pk_fma_f32 v[18:19], v[82:83], v[18:19], v[164:165]
	v_pk_fma_f32 v[20:21], v[84:85], v[20:21], v[166:167]
	v_pk_fma_f32 v[22:23], v[86:87], v[22:23], v[168:169]
	v_pk_fma_f32 v[24:25], v[88:89], v[24:25], v[170:171]
	v_pk_fma_f32 v[26:27], v[90:91], v[26:27], v[172:173]
	v_pk_fma_f32 v[28:29], v[92:93], v[28:29], v[174:175]
	v_pk_fma_f32 v[30:31], v[94:95], v[30:31], v[176:177]
	v_cvt_pk_bf16_f32 v212, v16, v17
	v_cvt_pk_bf16_f32 v213, v18, v19
	v_cvt_pk_bf16_f32 v214, v20, v21
	v_cvt_pk_bf16_f32 v215, v22, v23
	v_cvt_pk_bf16_f32 v216, v24, v25
	v_cvt_pk_bf16_f32 v217, v26, v27
	v_cvt_pk_bf16_f32 v218, v28, v29
	v_cvt_pk_bf16_f32 v219, v30, v31
	global_store_dwordx4 v203, v[212:215], s[48:49] sc1
	global_store_dwordx4 v203, v[216:219], s[48:49] offset:1024 sc1
	s_add_u32 s48, s48, 0x800
	s_addc_u32 s49, s49, 0
	v_pk_mul_f32 v[32:33], v[194:195], v[32:33] op_sel_hi:[0,1]
	v_pk_mul_f32 v[34:35], v[194:195], v[34:35] op_sel_hi:[0,1]
	v_pk_mul_f32 v[36:37], v[194:195], v[36:37] op_sel_hi:[0,1]
	v_pk_mul_f32 v[38:39], v[194:195], v[38:39] op_sel_hi:[0,1]
	v_pk_mul_f32 v[40:41], v[194:195], v[40:41] op_sel_hi:[0,1]
	v_pk_mul_f32 v[42:43], v[194:195], v[42:43] op_sel_hi:[0,1]
	v_pk_mul_f32 v[44:45], v[194:195], v[44:45] op_sel_hi:[0,1]
	v_pk_mul_f32 v[46:47], v[194:195], v[46:47] op_sel_hi:[0,1]
	v_pk_mul_f32 v[32:33], v[64:65], v[32:33]
	v_pk_mul_f32 v[34:35], v[66:67], v[34:35]
	v_pk_mul_f32 v[36:37], v[68:69], v[36:37]
	v_pk_mul_f32 v[38:39], v[70:71], v[38:39]
	v_pk_mul_f32 v[40:41], v[72:73], v[40:41]
	v_pk_mul_f32 v[42:43], v[74:75], v[42:43]
	v_pk_mul_f32 v[44:45], v[76:77], v[44:45]
	v_pk_mul_f32 v[46:47], v[78:79], v[46:47]
	v_pk_fma_f32 v[32:33], v[80:81], v[32:33], v[162:163]
	v_pk_fma_f32 v[34:35], v[82:83], v[34:35], v[164:165]
	v_pk_fma_f32 v[36:37], v[84:85], v[36:37], v[166:167]
	v_pk_fma_f32 v[38:39], v[86:87], v[38:39], v[168:169]
	v_pk_fma_f32 v[40:41], v[88:89], v[40:41], v[170:171]
	v_pk_fma_f32 v[42:43], v[90:91], v[42:43], v[172:173]
	v_pk_fma_f32 v[44:45], v[92:93], v[44:45], v[174:175]
	v_pk_fma_f32 v[46:47], v[94:95], v[46:47], v[176:177]
	v_cvt_pk_bf16_f32 v204, v32, v33
	v_cvt_pk_bf16_f32 v205, v34, v35
	v_cvt_pk_bf16_f32 v206, v36, v37
	v_cvt_pk_bf16_f32 v207, v38, v39
	v_cvt_pk_bf16_f32 v208, v40, v41
	v_cvt_pk_bf16_f32 v209, v42, v43
	v_cvt_pk_bf16_f32 v210, v44, v45
	v_cvt_pk_bf16_f32 v211, v46, v47
	global_store_dwordx4 v203, v[204:207], s[48:49] sc1
	global_store_dwordx4 v203, v[208:211], s[48:49] offset:1024 sc1
	s_add_u32 s48, s48, 0x800
	s_addc_u32 s49, s49, 0
	v_pk_mul_f32 v[48:49], v[196:197], v[48:49] op_sel_hi:[0,1]
	v_pk_mul_f32 v[50:51], v[196:197], v[50:51] op_sel_hi:[0,1]
	v_pk_mul_f32 v[52:53], v[196:197], v[52:53] op_sel_hi:[0,1]
	v_pk_mul_f32 v[54:55], v[196:197], v[54:55] op_sel_hi:[0,1]
	v_pk_mul_f32 v[56:57], v[196:197], v[56:57] op_sel_hi:[0,1]
	v_pk_mul_f32 v[58:59], v[196:197], v[58:59] op_sel_hi:[0,1]
	v_pk_mul_f32 v[60:61], v[196:197], v[60:61] op_sel_hi:[0,1]
	v_pk_mul_f32 v[62:63], v[196:197], v[62:63] op_sel_hi:[0,1]
	v_pk_mul_f32 v[48:49], v[64:65], v[48:49]
	v_pk_mul_f32 v[50:51], v[66:67], v[50:51]
	v_pk_mul_f32 v[52:53], v[68:69], v[52:53]
	v_pk_mul_f32 v[54:55], v[70:71], v[54:55]
	v_pk_mul_f32 v[56:57], v[72:73], v[56:57]
	v_pk_mul_f32 v[58:59], v[74:75], v[58:59]
	v_pk_mul_f32 v[60:61], v[76:77], v[60:61]
	v_pk_mul_f32 v[62:63], v[78:79], v[62:63]
	v_pk_fma_f32 v[48:49], v[80:81], v[48:49], v[162:163]
	v_pk_fma_f32 v[50:51], v[82:83], v[50:51], v[164:165]
	v_pk_fma_f32 v[52:53], v[84:85], v[52:53], v[166:167]
	v_pk_fma_f32 v[54:55], v[86:87], v[54:55], v[168:169]
	v_pk_fma_f32 v[56:57], v[88:89], v[56:57], v[170:171]
	v_pk_fma_f32 v[58:59], v[90:91], v[58:59], v[172:173]
	v_pk_fma_f32 v[60:61], v[92:93], v[60:61], v[174:175]
	v_pk_fma_f32 v[62:63], v[94:95], v[62:63], v[176:177]
	v_cvt_pk_bf16_f32 v212, v48, v49
	v_cvt_pk_bf16_f32 v213, v50, v51
	v_cvt_pk_bf16_f32 v214, v52, v53
	v_cvt_pk_bf16_f32 v215, v54, v55
	v_cvt_pk_bf16_f32 v216, v56, v57
	v_cvt_pk_bf16_f32 v217, v58, v59
	v_cvt_pk_bf16_f32 v218, v60, v61
	v_cvt_pk_bf16_f32 v219, v62, v63
	global_store_dwordx4 v203, v[212:215], s[48:49] sc1
	global_store_dwordx4 v203, v[216:219], s[48:49] offset:1024 sc1
	s_add_u32 s48, s48, 0x800
	s_addc_u32 s49, s49, 0
	s_waitcnt vmcnt(8)
	v_mul_f32_e32 v178, v98, v98
	v_mul_f32_e32 v179, v114, v114
	v_mul_f32_e32 v180, v130, v130
	v_mul_f32_e32 v181, v146, v146
	v_fma_f32 v178, v99, v99, v178
	v_fma_f32 v179, v115, v115, v179
	v_fma_f32 v180, v131, v131, v180
	v_fma_f32 v181, v147, v147, v181
	v_fma_f32 v178, v100, v100, v178
	v_fma_f32 v179, v116, v116, v179
	v_fma_f32 v180, v132, v132, v180
	v_fma_f32 v181, v148, v148, v181
	v_fma_f32 v178, v101, v101, v178
	v_fma_f32 v179, v117, v117, v179
	v_fma_f32 v180, v133, v133, v180
	v_fma_f32 v181, v149, v149, v181
	v_fma_f32 v178, v102, v102, v178
	v_fma_f32 v179, v118, v118, v179
	v_fma_f32 v180, v134, v134, v180
	v_fma_f32 v181, v150, v150, v181
	v_fma_f32 v178, v103, v103, v178
	v_fma_f32 v179, v119, v119, v179
	v_fma_f32 v180, v135, v135, v180
	v_fma_f32 v181, v151, v151, v181
	v_fma_f32 v178, v104, v104, v178
	v_fma_f32 v179, v120, v120, v179
	v_fma_f32 v180, v136, v136, v180
	v_fma_f32 v181, v152, v152, v181
	v_fma_f32 v178, v105, v105, v178
	v_fma_f32 v179, v121, v121, v179
	v_fma_f32 v180, v137, v137, v180
	v_fma_f32 v181, v153, v153, v181
	v_fma_f32 v178, v106, v106, v178
	v_fma_f32 v179, v122, v122, v179
	v_fma_f32 v180, v138, v138, v180
	v_fma_f32 v181, v154, v154, v181
	v_fma_f32 v178, v107, v107, v178
	v_fma_f32 v179, v123, v123, v179
	v_fma_f32 v180, v139, v139, v180
	v_fma_f32 v181, v155, v155, v181
	v_fma_f32 v178, v108, v108, v178
	v_fma_f32 v179, v124, v124, v179
	v_fma_f32 v180, v140, v140, v180
	v_fma_f32 v181, v156, v156, v181
	v_fma_f32 v178, v109, v109, v178
	v_fma_f32 v179, v125, v125, v179
	v_fma_f32 v180, v141, v141, v180
	v_fma_f32 v181, v157, v157, v181
	v_fma_f32 v178, v110, v110, v178
	v_fma_f32 v179, v126, v126, v179
	v_fma_f32 v180, v142, v142, v180
	v_fma_f32 v181, v158, v158, v181
	v_fma_f32 v178, v111, v111, v178
	v_fma_f32 v179, v127, v127, v179
	v_fma_f32 v180, v143, v143, v180
	v_fma_f32 v181, v159, v159, v181
	v_fma_f32 v178, v112, v112, v178
	v_fma_f32 v179, v128, v128, v179
	v_fma_f32 v180, v144, v144, v180
	v_fma_f32 v181, v160, v160, v181
	v_fma_f32 v178, v113, v113, v178
	v_fma_f32 v179, v129, v129, v179
	v_fma_f32 v180, v145, v145, v180
	v_fma_f32 v181, v161, v161, v181
	v_add_f32_dpp v178, v178, v178 quad_perm:[1,0,3,2] row_mask:0xf bank_mask:0xf
	v_add_f32_dpp v179, v179, v179 quad_perm:[1,0,3,2] row_mask:0xf bank_mask:0xf
	v_add_f32_dpp v180, v180, v180 quad_perm:[1,0,3,2] row_mask:0xf bank_mask:0xf
	v_add_f32_dpp v181, v181, v181 quad_perm:[1,0,3,2] row_mask:0xf bank_mask:0xf
	v_add_f32_dpp v178, v178, v178 quad_perm:[2,3,0,1] row_mask:0xf bank_mask:0xf
	v_add_f32_dpp v179, v179, v179 quad_perm:[2,3,0,1] row_mask:0xf bank_mask:0xf
	v_add_f32_dpp v180, v180, v180 quad_perm:[2,3,0,1] row_mask:0xf bank_mask:0xf
	v_add_f32_dpp v181, v181, v181 quad_perm:[2,3,0,1] row_mask:0xf bank_mask:0xf
	v_add_f32_dpp v178, v178, v178 row_half_mirror row_mask:0xf bank_mask:0xf
	v_add_f32_dpp v179, v179, v179 row_half_mirror row_mask:0xf bank_mask:0xf
	v_add_f32_dpp v180, v180, v180 row_half_mirror row_mask:0xf bank_mask:0xf
	v_add_f32_dpp v181, v181, v181 row_half_mirror row_mask:0xf bank_mask:0xf
	v_add_f32_dpp v178, v178, v178 row_ror:8 row_mask:0xf bank_mask:0xf
	v_add_f32_dpp v179, v179, v179 row_ror:8 row_mask:0xf bank_mask:0xf
	v_add_f32_dpp v180, v180, v180 row_ror:8 row_mask:0xf bank_mask:0xf
	v_add_f32_dpp v181, v181, v181 row_ror:8 row_mask:0xf bank_mask:0xf
	v_mov_b32_e32 v182, v178
	v_mov_b32_e32 v183, v179
	v_mov_b32_e32 v184, v180
	v_mov_b32_e32 v185, v181
	v_permlane16_swap_b32_e32 v182, v178
	v_permlane16_swap_b32_e32 v183, v179
	v_permlane16_swap_b32_e32 v184, v180
	v_permlane16_swap_b32_e32 v185, v181
	v_add_f32_e32 v178, v178, v182
	v_add_f32_e32 v179, v179, v183
	v_add_f32_e32 v180, v180, v184
	v_add_f32_e32 v181, v181, v185
	v_mov_b32_e32 v182, v178
	v_mov_b32_e32 v183, v179
	v_mov_b32_e32 v184, v180
	v_mov_b32_e32 v185, v181
	v_permlane32_swap_b32_e32 v182, v178
	v_permlane32_swap_b32_e32 v183, v179
	v_permlane32_swap_b32_e32 v184, v180
	v_permlane32_swap_b32_e32 v185, v181
	v_add_f32_e32 v178, v178, v182
	v_add_f32_e32 v179, v179, v183
	v_add_f32_e32 v180, v180, v184
	v_add_f32_e32 v181, v181, v185
	v_fmamk_f32 v198, v178, 0x3a800000, v225
	v_fmamk_f32 v199, v179, 0x3a800000, v225
	v_fmamk_f32 v200, v180, 0x3a800000, v225
	v_fmamk_f32 v201, v181, 0x3a800000, v225
	v_mul_f32_e32 v182, 0x4b800000, v198
	v_mul_f32_e32 v183, 0x4b800000, v199
	v_mul_f32_e32 v184, 0x4b800000, v200
	v_mul_f32_e32 v185, 0x4b800000, v201
	v_cmp_gt_f32_e64 s[2:3], s30, v198
	v_cmp_gt_f32_e64 s[50:51], s30, v199
	v_cmp_gt_f32_e64 s[88:89], s30, v200
	v_cmp_gt_f32_e64 s[90:91], s30, v201
	v_cndmask_b32_e64 v198, v198, v182, s[2:3]
	v_cndmask_b32_e64 v199, v199, v183, s[50:51]
	v_cndmask_b32_e64 v200, v200, v184, s[88:89]
	v_cndmask_b32_e64 v201, v201, v185, s[90:91]
	v_rsq_f32_e32 v198, v198
	v_rsq_f32_e32 v199, v199
	v_rsq_f32_e32 v200, v200
	v_rsq_f32_e32 v201, v201
	v_mul_f32_e32 v182, 0x45800000, v198
	v_mul_f32_e32 v183, 0x45800000, v199
	v_mul_f32_e32 v184, 0x45800000, v200
	v_mul_f32_e32 v185, 0x45800000, v201
	v_cndmask_b32_e64 v186, v198, v182, s[2:3]
	v_cndmask_b32_e64 v192, v199, v183, s[50:51]
	v_cndmask_b32_e64 v194, v200, v184, s[88:89]
	v_cndmask_b32_e64 v196, v201, v185, s[90:91]
	v_pk_mul_f32 v[98:99], v[186:187], v[98:99] op_sel_hi:[0,1]
	v_pk_mul_f32 v[100:101], v[186:187], v[100:101] op_sel_hi:[0,1]
	v_pk_mul_f32 v[102:103], v[186:187], v[102:103] op_sel_hi:[0,1]
	v_pk_mul_f32 v[104:105], v[186:187], v[104:105] op_sel_hi:[0,1]
	v_pk_mul_f32 v[106:107], v[186:187], v[106:107] op_sel_hi:[0,1]
	v_pk_mul_f32 v[108:109], v[186:187], v[108:109] op_sel_hi:[0,1]
	v_pk_mul_f32 v[110:111], v[186:187], v[110:111] op_sel_hi:[0,1]
	v_pk_mul_f32 v[112:113], v[186:187], v[112:113] op_sel_hi:[0,1]
	v_pk_mul_f32 v[98:99], v[64:65], v[98:99]
	v_pk_mul_f32 v[100:101], v[66:67], v[100:101]
	v_pk_mul_f32 v[102:103], v[68:69], v[102:103]
	v_pk_mul_f32 v[104:105], v[70:71], v[104:105]
	v_pk_mul_f32 v[106:107], v[72:73], v[106:107]
	v_pk_mul_f32 v[108:109], v[74:75], v[108:109]
	v_pk_mul_f32 v[110:111], v[76:77], v[110:111]
	v_pk_mul_f32 v[112:113], v[78:79], v[112:113]
	v_pk_fma_f32 v[98:99], v[80:81], v[98:99], v[162:163]
	v_pk_fma_f32 v[100:101], v[82:83], v[100:101], v[164:165]
	v_pk_fma_f32 v[102:103], v[84:85], v[102:103], v[166:167]
	v_pk_fma_f32 v[104:105], v[86:87], v[104:105], v[168:169]
	v_pk_fma_f32 v[106:107], v[88:89], v[106:107], v[170:171]
	v_pk_fma_f32 v[108:109], v[90:91], v[108:109], v[172:173]
	v_pk_fma_f32 v[110:111], v[92:93], v[110:111], v[174:175]
	v_pk_fma_f32 v[112:113], v[94:95], v[112:113], v[176:177]
	v_cvt_pk_bf16_f32 v204, v98, v99
	v_cvt_pk_bf16_f32 v205, v100, v101
	v_cvt_pk_bf16_f32 v206, v102, v103
	v_cvt_pk_bf16_f32 v207, v104, v105
	v_cvt_pk_bf16_f32 v208, v106, v107
	v_cvt_pk_bf16_f32 v209, v108, v109
	v_cvt_pk_bf16_f32 v210, v110, v111
	v_cvt_pk_bf16_f32 v211, v112, v113
	global_store_dwordx4 v203, v[204:207], s[48:49] sc1
	global_store_dwordx4 v203, v[208:211], s[48:49] offset:1024 sc1
	s_add_u32 s48, s48, 0x800
	s_addc_u32 s49, s49, 0
	v_pk_mul_f32 v[114:115], v[192:193], v[114:115] op_sel_hi:[0,1]
	v_pk_mul_f32 v[116:117], v[192:193], v[116:117] op_sel_hi:[0,1]
	v_pk_mul_f32 v[118:119], v[192:193], v[118:119] op_sel_hi:[0,1]
	v_pk_mul_f32 v[120:121], v[192:193], v[120:121] op_sel_hi:[0,1]
	v_pk_mul_f32 v[122:123], v[192:193], v[122:123] op_sel_hi:[0,1]
	v_pk_mul_f32 v[124:125], v[192:193], v[124:125] op_sel_hi:[0,1]
	v_pk_mul_f32 v[126:127], v[192:193], v[126:127] op_sel_hi:[0,1]
	v_pk_mul_f32 v[128:129], v[192:193], v[128:129] op_sel_hi:[0,1]
	v_pk_mul_f32 v[114:115], v[64:65], v[114:115]
	v_pk_mul_f32 v[116:117], v[66:67], v[116:117]
	v_pk_mul_f32 v[118:119], v[68:69], v[118:119]
	v_pk_mul_f32 v[120:121], v[70:71], v[120:121]
	v_pk_mul_f32 v[122:123], v[72:73], v[122:123]
	v_pk_mul_f32 v[124:125], v[74:75], v[124:125]
	v_pk_mul_f32 v[126:127], v[76:77], v[126:127]
	v_pk_mul_f32 v[128:129], v[78:79], v[128:129]
	v_pk_fma_f32 v[114:115], v[80:81], v[114:115], v[162:163]
	v_pk_fma_f32 v[116:117], v[82:83], v[116:117], v[164:165]
	v_pk_fma_f32 v[118:119], v[84:85], v[118:119], v[166:167]
	v_pk_fma_f32 v[120:121], v[86:87], v[120:121], v[168:169]
	v_pk_fma_f32 v[122:123], v[88:89], v[122:123], v[170:171]
	v_pk_fma_f32 v[124:125], v[90:91], v[124:125], v[172:173]
	v_pk_fma_f32 v[126:127], v[92:93], v[126:127], v[174:175]
	v_pk_fma_f32 v[128:129], v[94:95], v[128:129], v[176:177]
	v_cvt_pk_bf16_f32 v212, v114, v115
	v_cvt_pk_bf16_f32 v213, v116, v117
	v_cvt_pk_bf16_f32 v214, v118, v119
	v_cvt_pk_bf16_f32 v215, v120, v121
	v_cvt_pk_bf16_f32 v216, v122, v123
	v_cvt_pk_bf16_f32 v217, v124, v125
	v_cvt_pk_bf16_f32 v218, v126, v127
	v_cvt_pk_bf16_f32 v219, v128, v129
	global_store_dwordx4 v203, v[212:215], s[48:49] sc1
	global_store_dwordx4 v203, v[216:219], s[48:49] offset:1024 sc1
	s_add_u32 s48, s48, 0x800
	s_addc_u32 s49, s49, 0
	v_pk_mul_f32 v[130:131], v[194:195], v[130:131] op_sel_hi:[0,1]
	v_pk_mul_f32 v[132:133], v[194:195], v[132:133] op_sel_hi:[0,1]
	v_pk_mul_f32 v[134:135], v[194:195], v[134:135] op_sel_hi:[0,1]
	v_pk_mul_f32 v[136:137], v[194:195], v[136:137] op_sel_hi:[0,1]
	v_pk_mul_f32 v[138:139], v[194:195], v[138:139] op_sel_hi:[0,1]
	v_pk_mul_f32 v[140:141], v[194:195], v[140:141] op_sel_hi:[0,1]
	v_pk_mul_f32 v[142:143], v[194:195], v[142:143] op_sel_hi:[0,1]
	v_pk_mul_f32 v[144:145], v[194:195], v[144:145] op_sel_hi:[0,1]
	v_pk_mul_f32 v[130:131], v[64:65], v[130:131]
	v_pk_mul_f32 v[132:133], v[66:67], v[132:133]
	v_pk_mul_f32 v[134:135], v[68:69], v[134:135]
	v_pk_mul_f32 v[136:137], v[70:71], v[136:137]
	v_pk_mul_f32 v[138:139], v[72:73], v[138:139]
	v_pk_mul_f32 v[140:141], v[74:75], v[140:141]
	v_pk_mul_f32 v[142:143], v[76:77], v[142:143]
	v_pk_mul_f32 v[144:145], v[78:79], v[144:145]
	v_pk_fma_f32 v[130:131], v[80:81], v[130:131], v[162:163]
	v_pk_fma_f32 v[132:133], v[82:83], v[132:133], v[164:165]
	v_pk_fma_f32 v[134:135], v[84:85], v[134:135], v[166:167]
	v_pk_fma_f32 v[136:137], v[86:87], v[136:137], v[168:169]
	v_pk_fma_f32 v[138:139], v[88:89], v[138:139], v[170:171]
	v_pk_fma_f32 v[140:141], v[90:91], v[140:141], v[172:173]
	v_pk_fma_f32 v[142:143], v[92:93], v[142:143], v[174:175]
	v_pk_fma_f32 v[144:145], v[94:95], v[144:145], v[176:177]
	v_cvt_pk_bf16_f32 v204, v130, v131
	v_cvt_pk_bf16_f32 v205, v132, v133
	v_cvt_pk_bf16_f32 v206, v134, v135
	v_cvt_pk_bf16_f32 v207, v136, v137
	v_cvt_pk_bf16_f32 v208, v138, v139
	v_cvt_pk_bf16_f32 v209, v140, v141
	v_cvt_pk_bf16_f32 v210, v142, v143
	v_cvt_pk_bf16_f32 v211, v144, v145
	global_store_dwordx4 v203, v[204:207], s[48:49] sc1
	global_store_dwordx4 v203, v[208:211], s[48:49] offset:1024 sc1
	s_add_u32 s48, s48, 0x800
	s_addc_u32 s49, s49, 0
	v_pk_mul_f32 v[146:147], v[196:197], v[146:147] op_sel_hi:[0,1]
	v_pk_mul_f32 v[148:149], v[196:197], v[148:149] op_sel_hi:[0,1]
	v_pk_mul_f32 v[150:151], v[196:197], v[150:151] op_sel_hi:[0,1]
	v_pk_mul_f32 v[152:153], v[196:197], v[152:153] op_sel_hi:[0,1]
	v_pk_mul_f32 v[154:155], v[196:197], v[154:155] op_sel_hi:[0,1]
	v_pk_mul_f32 v[156:157], v[196:197], v[156:157] op_sel_hi:[0,1]
	v_pk_mul_f32 v[158:159], v[196:197], v[158:159] op_sel_hi:[0,1]
	v_pk_mul_f32 v[160:161], v[196:197], v[160:161] op_sel_hi:[0,1]
	v_pk_mul_f32 v[146:147], v[64:65], v[146:147]
	v_pk_mul_f32 v[148:149], v[66:67], v[148:149]
	v_pk_mul_f32 v[150:151], v[68:69], v[150:151]
	v_pk_mul_f32 v[152:153], v[70:71], v[152:153]
	v_pk_mul_f32 v[154:155], v[72:73], v[154:155]
	v_pk_mul_f32 v[156:157], v[74:75], v[156:157]
	v_pk_mul_f32 v[158:159], v[76:77], v[158:159]
	v_pk_mul_f32 v[160:161], v[78:79], v[160:161]
	v_pk_fma_f32 v[146:147], v[80:81], v[146:147], v[162:163]
	v_pk_fma_f32 v[148:149], v[82:83], v[148:149], v[164:165]
	v_pk_fma_f32 v[150:151], v[84:85], v[150:151], v[166:167]
	v_pk_fma_f32 v[152:153], v[86:87], v[152:153], v[168:169]
	v_pk_fma_f32 v[154:155], v[88:89], v[154:155], v[170:171]
	v_pk_fma_f32 v[156:157], v[90:91], v[156:157], v[172:173]
	v_pk_fma_f32 v[158:159], v[92:93], v[158:159], v[174:175]
	v_pk_fma_f32 v[160:161], v[94:95], v[160:161], v[176:177]
	v_cvt_pk_bf16_f32 v212, v146, v147
	v_cvt_pk_bf16_f32 v213, v148, v149
	v_cvt_pk_bf16_f32 v214, v150, v151
	v_cvt_pk_bf16_f32 v215, v152, v153
	v_cvt_pk_bf16_f32 v216, v154, v155
	v_cvt_pk_bf16_f32 v217, v156, v157
	v_cvt_pk_bf16_f32 v218, v158, v159
	v_cvt_pk_bf16_f32 v219, v160, v161
	global_store_dwordx4 v203, v[212:215], s[48:49] sc1
	global_store_dwordx4 v203, v[216:219], s[48:49] offset:1024 sc1
	s_add_u32 s48, s48, 0x800
	s_addc_u32 s49, s49, 0
	s_nop 1
	s_branch .LBB0_286
.Lnrm_B_fallback:
	v_and_b32_e32 v0, 64, v227
	v_add_u32_e32 v0, 64, v0
	v_xor_b32_e32 v1, 1, v227
	v_lshlrev_b32_e32 v96, 4, v231
	v_cmp_lt_i32_e32 vcc, v1, v0
	v_lshl_add_u64 v[72:73], s[46:47], 0, v[96:97]
	v_readlane_b32 s2, v250, 48
	v_cndmask_b32_e32 v1, v227, v1, vcc
	v_lshlrev_b32_e32 v73, 2, v1
	v_xor_b32_e32 v1, 2, v227
	v_cmp_lt_i32_e32 vcc, v1, v0
	v_readlane_b32 s3, v250, 49
	s_ashr_i32 s53, s52, 31
	v_cndmask_b32_e32 v1, v227, v1, vcc
	v_lshlrev_b32_e32 v100, 2, v1
	v_xor_b32_e32 v1, 4, v227
	v_cmp_lt_i32_e32 vcc, v1, v0
	v_lshl_add_u64 v[76:77], s[2:3], 0, v[96:97]
	s_lshl_b64 s[2:3], s[52:53], 11
	v_cndmask_b32_e32 v1, v227, v1, vcc
	v_lshlrev_b32_e32 v101, 2, v1
	v_xor_b32_e32 v1, 8, v227
	v_cmp_lt_i32_e32 vcc, v1, v0
	s_add_u32 s12, s6, s2
	s_addc_u32 s13, s7, s3
	v_cndmask_b32_e32 v1, v227, v1, vcc
	v_lshlrev_b32_e32 v102, 2, v1
	v_xor_b32_e32 v1, 16, v227
	v_cmp_lt_i32_e32 vcc, v1, v0
	s_lshl_b64 s[2:3], s[52:53], 12
	v_readlane_b32 s84, v254, 40
	v_cndmask_b32_e32 v1, v227, v1, vcc
	v_lshlrev_b32_e32 v103, 2, v1
	v_xor_b32_e32 v1, 32, v227
	v_cmp_lt_i32_e32 vcc, v1, v0
	s_add_u32 s2, s46, s2
	v_readlane_b32 s90, v254, 46
	v_cndmask_b32_e32 v0, v227, v1, vcc
	v_lshlrev_b32_e32 v104, 2, v0
	v_lshlrev_b32_e32 v0, 2, v231
	v_readlane_b32 s91, v254, 47
	s_addc_u32 s3, s47, s3
	v_lshl_add_u64 v[78:79], s[74:75], 0, v[96:97]
	v_lshl_add_u64 v[74:75], s[90:91], 0, v[96:97]
	v_lshl_add_u64 v[80:81], s[2:3], 0, v[96:97]
	v_lshlrev_b32_e32 v96, 1, v0
	s_mov_b32 s2, s52
	v_readlane_b32 s85, v254, 41
	v_readlane_b32 s86, v254, 42
	v_readlane_b32 s87, v254, 43
	v_readlane_b32 s88, v254, 44
	v_readlane_b32 s89, v254, 45

.LBB0_455:
	s_andn2_b64 vcc, exec, s[12:13]
	s_cbranch_vccnz .LBB0_479
	s_cmp_gt_i32 s5, 11
	s_mov_b64 s[12:13], -1
	s_cbranch_scc0 .LBB0_461
	v_readlane_b32 s40, v253, 43
	v_readlane_b32 s42, v254, 34
	v_readlane_b32 s44, v254, 38
	s_mov_b64 s[86:87], s[58:59]
	s_cmpk_gt_i32 s52, 0x7fff
	v_readlane_b32 s41, v253, 44
	v_readlane_b32 s11, v254, 18
	v_readlane_b32 s43, v254, 35
	v_readlane_b32 s45, v254, 39
	s_mov_b64 s[48:49], 0x200
	s_mov_b64 s[50:51], 0x400
	s_mov_b64 s[84:85], s[56:57]
	s_mov_b64 s[56:57], 0x600
	s_cbranch_scc1 .LBB0_460
	v_readlane_b32 s2, v250, 0
	s_cmpk_lg_u32 s2, 0x100
	s_cbranch_scc1 .Lnrm_C_fallback
	v_lshrrev_b32_e32 v0, 6, v222
	v_and_b32_e32 v1, 63, v222
	v_readlane_b32 s4, v254, 48
	v_readfirstlane_b32 s3, v0
	v_readlane_b32 s82, v250, 2
	v_readlane_b32 s83, v250, 3
	s_lshl_b32 s4, s4, 3
	s_add_i32 s4, s4, s3
	s_load_dwordx2 s[18:19], s[82:83], 0x90
	s_mov_b32 s12, s72
	s_mov_b32 s13, s73
	s_lshr_b32 s2, s4, 7
	s_mul_i32 s2, s2, 0x9000
	s_add_u32 s20, s74, s2
	s_addc_u32 s21, s75, 0
	s_add_u32 s88, s20, 0x7000
	s_addc_u32 s89, s21, 0
	s_add_u32 s90, s20, 0x6000
	s_addc_u32 s91, s21, 0
	v_lshlrev_b32_e32 v202, 5, v1
	v_lshlrev_b32_e32 v203, 4, v1
	s_lshl_b32 s11, s4, 16
	s_lshl_b32 s2, s4, 15
	s_add_u32 s48, s74, s2
	s_addc_u32 s49, s75, 0
	s_add_u32 s48, s48, 0x13000000
	s_addc_u32 s49, s49, 0
	s_waitcnt lgkmcnt(0)
	s_and_b32 s13, s13, 0xffff
	s_mov_b32 s14, 0x8000000
	s_mov_b32 s15, 0x20000
	global_load_dwordx4 v[64:67], v202, s[18:19]
	global_load_dwordx4 v[68:71], v202, s[18:19] offset:16
	global_load_dwordx4 v[72:75], v202, s[18:19] offset:2048
	global_load_dwordx4 v[76:79], v202, s[18:19] offset:2064
	global_load_dwordx4 v[80:83], v202, s[88:89]
	global_load_dwordx4 v[84:87], v202, s[88:89] offset:16
	global_load_dwordx4 v[88:91], v202, s[88:89] offset:2048
	global_load_dwordx4 v[92:95], v202, s[88:89] offset:2064
	global_load_dwordx4 v[162:165], v202, s[90:91]
	global_load_dwordx4 v[166:169], v202, s[90:91] offset:16
	global_load_dwordx4 v[170:173], v202, s[90:91] offset:2048
	global_load_dwordx4 v[174:177], v202, s[90:91] offset:2064
	buffer_load_dwordx4 v[0:3], v202, s[12:15], s11 offen sc1
	buffer_load_dwordx4 v[4:7], v202, s[12:15], s11 offen offset:16 sc1
	buffer_load_dwordx4 v[8:11], v202, s[12:15], s11 offen offset:2048 sc1
	buffer_load_dwordx4 v[12:15], v202, s[12:15], s11 offen offset:2064 sc1
	s_add_u32 s11, s11, 0x1000
	buffer_load_dwordx4 v[16:19], v202, s[12:15], s11 offen sc1
	buffer_load_dwordx4 v[20:23], v202, s[12:15], s11 offen offset:16 sc1
	buffer_load_dwordx4 v[24:27], v202, s[12:15], s11 offen offset:2048 sc1
	buffer_load_dwordx4 v[28:31], v202, s[12:15], s11 offen offset:2064 sc1
	s_add_u32 s11, s11, 0x1000
	buffer_load_dwordx4 v[32:35], v202, s[12:15], s11 offen sc1
	buffer_load_dwordx4 v[36:39], v202, s[12:15], s11 offen offset:16 sc1
	buffer_load_dwordx4 v[40:43], v202, s[12:15], s11 offen offset:2048 sc1
	buffer_load_dwordx4 v[44:47], v202, s[12:15], s11 offen offset:2064 sc1
	s_add_u32 s11, s11, 0x1000
	buffer_load_dwordx4 v[48:51], v202, s[12:15], s11 offen sc1
	buffer_load_dwordx4 v[52:55], v202, s[12:15], s11 offen offset:16 sc1
	buffer_load_dwordx4 v[56:59], v202, s[12:15], s11 offen offset:2048 sc1
	buffer_load_dwordx4 v[60:63], v202, s[12:15], s11 offen offset:2064 sc1
	s_add_u32 s11, s11, 0x1000
	buffer_load_dwordx4 v[98:101], v202, s[12:15], s11 offen sc1
	buffer_load_dwordx4 v[102:105], v202, s[12:15], s11 offen offset:16 sc1
	buffer_load_dwordx4 v[106:109], v202, s[12:15], s11 offen offset:2048 sc1
	buffer_load_dwordx4 v[110:113], v202, s[12:15], s11 offen offset:2064 sc1
	s_add_u32 s11, s11, 0x1000
	buffer_load_dwordx4 v[114:117], v202, s[12:15], s11 offen sc1
	buffer_load_dwordx4 v[118:121], v202, s[12:15], s11 offen offset:16 sc1
	buffer_load_dwordx4 v[122:125], v202, s[12:15], s11 offen offset:2048 sc1
	buffer_load_dwordx4 v[126:129], v202, s[12:15], s11 offen offset:2064 sc1
	s_add_u32 s11, s11, 0x1000
	buffer_load_dwordx4 v[130:133], v202, s[12:15], s11 offen sc1
	buffer_load_dwordx4 v[134:137], v202, s[12:15], s11 offen offset:16 sc1
	buffer_load_dwordx4 v[138:141], v202, s[12:15], s11 offen offset:2048 sc1
	buffer_load_dwordx4 v[142:145], v202, s[12:15], s11 offen offset:2064 sc1
	s_add_u32 s11, s11, 0x1000
	buffer_load_dwordx4 v[146:149], v202, s[12:15], s11 offen sc1
	buffer_load_dwordx4 v[150:153], v202, s[12:15], s11 offen offset:16 sc1
	buffer_load_dwordx4 v[154:157], v202, s[12:15], s11 offen offset:2048 sc1
	buffer_load_dwordx4 v[158:161], v202, s[12:15], s11 offen offset:2064 sc1
	s_add_u32 s11, s11, 0x1000
	s_waitcnt vmcnt(16)
	v_pk_add_f32 v[80:81], v[80:81], 1.0 op_sel_hi:[1,0]
	v_pk_add_f32 v[82:83], v[82:83], 1.0 op_sel_hi:[1,0]
	v_pk_add_f32 v[84:85], v[84:85], 1.0 op_sel_hi:[1,0]
	v_pk_add_f32 v[86:87], v[86:87], 1.0 op_sel_hi:[1,0]
	v_pk_add_f32 v[88:89], v[88:89], 1.0 op_sel_hi:[1,0]
	v_pk_add_f32 v[90:91], v[90:91], 1.0 op_sel_hi:[1,0]
	v_pk_add_f32 v[92:93], v[92:93], 1.0 op_sel_hi:[1,0]
	v_pk_add_f32 v[94:95], v[94:95], 1.0 op_sel_hi:[1,0]
	v_mul_f32_e32 v178, v0, v0
	v_mul_f32_e32 v179, v16, v16
	v_mul_f32_e32 v180, v32, v32
	v_mul_f32_e32 v181, v48, v48
	v_fma_f32 v178, v1, v1, v178
	v_fma_f32 v179, v17, v17, v179
	v_fma_f32 v180, v33, v33, v180
	v_fma_f32 v181, v49, v49, v181
	v_fma_f32 v178, v2, v2, v178
	v_fma_f32 v179, v18, v18, v179
	v_fma_f32 v180, v34, v34, v180
	v_fma_f32 v181, v50, v50, v181
	v_fma_f32 v178, v3, v3, v178
	v_fma_f32 v179, v19, v19, v179
	v_fma_f32 v180, v35, v35, v180
	v_fma_f32 v181, v51, v51, v181
	v_fma_f32 v178, v4, v4, v178
	v_fma_f32 v179, v20, v20, v179
	v_fma_f32 v180, v36, v36, v180
	v_fma_f32 v181, v52, v52, v181
	v_fma_f32 v178, v5, v5, v178
	v_fma_f32 v179, v21, v21, v179
	v_fma_f32 v180, v37, v37, v180
	v_fma_f32 v181, v53, v53, v181
	v_fma_f32 v178, v6, v6, v178
	v_fma_f32 v179, v22, v22, v179
	v_fma_f32 v180, v38, v38, v180
	v_fma_f32 v181, v54, v54, v181
	v_fma_f32 v178, v7, v7, v178
	v_fma_f32 v179, v23, v23, v179
	v_fma_f32 v180, v39, v39, v180
	v_fma_f32 v181, v55, v55, v181
	v_fma_f32 v178, v8, v8, v178
	v_fma_f32 v179, v24, v24, v179
	v_fma_f32 v180, v40, v40, v180
	v_fma_f32 v181, v56, v56, v181
	v_fma_f32 v178, v9, v9, v178
	v_fma_f32 v179, v25, v25, v179
	v_fma_f32 v180, v41, v41, v180
	v_fma_f32 v181, v57, v57, v181
	v_fma_f32 v178, v10, v10, v178
	v_fma_f32 v179, v26, v26, v179
	v_fma_f32 v180, v42, v42, v180
	v_fma_f32 v181, v58, v58, v181
	v_fma_f32 v178, v11, v11, v178
	v_fma_f32 v179, v27, v27, v179
	v_fma_f32 v180, v43, v43, v180
	v_fma_f32 v181, v59, v59, v181
	v_fma_f32 v178, v12, v12, v178
	v_fma_f32 v179, v28, v28, v179
	v_fma_f32 v180, v44, v44, v180
	v_fma_f32 v181, v60, v60, v181
	v_fma_f32 v178, v13, v13, v178
	v_fma_f32 v179, v29, v29, v179
	v_fma_f32 v180, v45, v45, v180
	v_fma_f32 v181, v61, v61, v181
	v_fma_f32 v178, v14, v14, v178
	v_fma_f32 v179, v30, v30, v179
	v_fma_f32 v180, v46, v46, v180
	v_fma_f32 v181, v62, v62, v181
	v_fma_f32 v178, v15, v15, v178
	v_fma_f32 v179, v31, v31, v179
	v_fma_f32 v180, v47, v47, v180
	v_fma_f32 v181, v63, v63, v181
	v_add_f32_dpp v178, v178, v178 quad_perm:[1,0,3,2] row_mask:0xf bank_mask:0xf
	v_add_f32_dpp v179, v179, v179 quad_perm:[1,0,3,2] row_mask:0xf bank_mask:0xf
	v_add_f32_dpp v180, v180, v180 quad_perm:[1,0,3,2] row_mask:0xf bank_mask:0xf
	v_add_f32_dpp v181, v181, v181 quad_perm:[1,0,3,2] row_mask:0xf bank_mask:0xf
	v_add_f32_dpp v178, v178, v178 quad_perm:[2,3,0,1] row_mask:0xf bank_mask:0xf
	v_add_f32_dpp v179, v179, v179 quad_perm:[2,3,0,1] row_mask:0xf bank_mask:0xf
	v_add_f32_dpp v180, v180, v180 quad_perm:[2,3,0,1] row_mask:0xf bank_mask:0xf
	v_add_f32_dpp v181, v181, v181 quad_perm:[2,3,0,1] row_mask:0xf bank_mask:0xf
	v_add_f32_dpp v178, v178, v178 row_half_mirror row_mask:0xf bank_mask:0xf
	v_add_f32_dpp v179, v179, v179 row_half_mirror row_mask:0xf bank_mask:0xf
	v_add_f32_dpp v180, v180, v180 row_half_mirror row_mask:0xf bank_mask:0xf
	v_add_f32_dpp v181, v181, v181 row_half_mirror row_mask:0xf bank_mask:0xf
	v_add_f32_dpp v178, v178, v178 row_ror:8 row_mask:0xf bank_mask:0xf
	v_add_f32_dpp v179, v179, v179 row_ror:8 row_mask:0xf bank_mask:0xf
	v_add_f32_dpp v180, v180, v180 row_ror:8 row_mask:0xf bank_mask:0xf
	v_add_f32_dpp v181, v181, v181 row_ror:8 row_mask:0xf bank_mask:0xf
	v_mov_b32_e32 v182, v178
	v_mov_b32_e32 v183, v179
	v_mov_b32_e32 v184, v180
	v_mov_b32_e32 v185, v181
	v_permlane16_swap_b32_e32 v182, v178
	v_permlane16_swap_b32_e32 v183, v179
	v_permlane16_swap_b32_e32 v184, v180
	v_permlane16_swap_b32_e32 v185, v181
	v_add_f32_e32 v178, v178, v182
	v_add_f32_e32 v179, v179, v183
	v_add_f32_e32 v180, v180, v184
	v_add_f32_e32 v181, v181, v185
	v_mov_b32_e32 v182, v178
	v_mov_b32_e32 v183, v179
	v_mov_b32_e32 v184, v180
	v_mov_b32_e32 v185, v181
	v_permlane32_swap_b32_e32 v182, v178
	v_permlane32_swap_b32_e32 v183, v179
	v_permlane32_swap_b32_e32 v184, v180
	v_permlane32_swap_b32_e32 v185, v181
	v_add_f32_e32 v178, v178, v182
	v_add_f32_e32 v179, v179, v183
	v_add_f32_e32 v180, v180, v184
	v_add_f32_e32 v181, v181, v185
	v_fmamk_f32 v198, v178, 0x3a800000, v225
	v_fmamk_f32 v199, v179, 0x3a800000, v225
	v_fmamk_f32 v200, v180, 0x3a800000, v225
	v_fmamk_f32 v201, v181, 0x3a800000, v225
	v_mul_f32_e32 v182, 0x4b800000, v198
	v_mul_f32_e32 v183, 0x4b800000, v199
	v_mul_f32_e32 v184, 0x4b800000, v200
	v_mul_f32_e32 v185, 0x4b800000, v201
	v_cmp_gt_f32_e64 s[2:3], s30, v198
	v_cmp_gt_f32_e64 s[50:51], s30, v199
	v_cmp_gt_f32_e64 s[88:89], s30, v200
	v_cmp_gt_f32_e64 s[90:91], s30, v201
	v_cndmask_b32_e64 v198, v198, v182, s[2:3]
	v_cndmask_b32_e64 v199, v199, v183, s[50:51]
	v_cndmask_b32_e64 v200, v200, v184, s[88:89]
	v_cndmask_b32_e64 v201, v201, v185, s[90:91]
	v_rsq_f32_e32 v198, v198
	v_rsq_f32_e32 v199, v199
	v_rsq_f32_e32 v200, v200
	v_rsq_f32_e32 v201, v201
	v_mul_f32_e32 v182, 0x45800000, v198
	v_mul_f32_e32 v183, 0x45800000, v199
	v_mul_f32_e32 v184, 0x45800000, v200
	v_mul_f32_e32 v185, 0x45800000, v201
	v_cndmask_b32_e64 v186, v198, v182, s[2:3]
	v_cndmask_b32_e64 v192, v199, v183, s[50:51]
	v_cndmask_b32_e64 v194, v200, v184, s[88:89]
	v_cndmask_b32_e64 v196, v201, v185, s[90:91]
	v_pk_mul_f32 v[0:1], v[186:187], v[0:1] op_sel_hi:[0,1]
	v_pk_mul_f32 v[2:3], v[186:187], v[2:3] op_sel_hi:[0,1]
	v_pk_mul_f32 v[4:5], v[186:187], v[4:5] op_sel_hi:[0,1]
	v_pk_mul_f32 v[6:7], v[186:187], v[6:7] op_sel_hi:[0,1]
	v_pk_mul_f32 v[8:9], v[186:187], v[8:9] op_sel_hi:[0,1]
	v_pk_mul_f32 v[10:11], v[186:187], v[10:11] op_sel_hi:[0,1]
	v_pk_mul_f32 v[12:13], v[186:187], v[12:13] op_sel_hi:[0,1]
	v_pk_mul_f32 v[14:15], v[186:187], v[14:15] op_sel_hi:[0,1]
	v_pk_mul_f32 v[0:1], v[64:65], v[0:1]
	v_pk_mul_f32 v[2:3], v[66:67], v[2:3]
	v_pk_mul_f32 v[4:5], v[68:69], v[4:5]
	v_pk_mul_f32 v[6:7], v[70:71], v[6:7]
	v_pk_mul_f32 v[8:9], v[72:73], v[8:9]
	v_pk_mul_f32 v[10:11], v[74:75], v[10:11]
	v_pk_mul_f32 v[12:13], v[76:77], v[12:13]
	v_pk_mul_f32 v[14:15], v[78:79], v[14:15]
	v_pk_fma_f32 v[0:1], v[80:81], v[0:1], v[162:163]
	v_pk_fma_f32 v[2:3], v[82:83], v[2:3], v[164:165]
	v_pk_fma_f32 v[4:5], v[84:85], v[4:5], v[166:167]
	v_pk_fma_f32 v[6:7], v[86:87], v[6:7], v[168:169]
	v_pk_fma_f32 v[8:9], v[88:89], v[8:9], v[170:171]
	v_pk_fma_f32 v[10:11], v[90:91], v[10:11], v[172:173]
	v_pk_fma_f32 v[12:13], v[92:93], v[12:13], v[174:175]
	v_pk_fma_f32 v[14:15], v[94:95], v[14:15], v[176:177]
	v_cvt_pk_bf16_f32 v204, v0, v1
	v_cvt_pk_bf16_f32 v205, v2, v3
	v_cvt_pk_bf16_f32 v206, v4, v5
	v_cvt_pk_bf16_f32 v207, v6, v7
	v_cvt_pk_bf16_f32 v208, v8, v9
	v_cvt_pk_bf16_f32 v209, v10, v11
	v_cvt_pk_bf16_f32 v210, v12, v13
	v_cvt_pk_bf16_f32 v211, v14, v15
	global_store_dwordx4 v203, v[204:207], s[48:49] sc1
	global_store_dwordx4 v203, v[208:211], s[48:49] offset:1024 sc1
	s_add_u32 s48, s48, 0x800
	s_addc_u32 s49, s49, 0
	v_pk_mul_f32 v[16:17], v[192:193], v[16:17] op_sel_hi:[0,1]
	v_pk_mul_f32 v[18:19], v[192:193], v[18:19] op_sel_hi:[0,1]
	v_pk_mul_f32 v[20:21], v[192:193], v[20:21] op_sel_hi:[0,1]
	v_pk_mul_f32 v[22:23], v[192:193], v[22:23] op_sel_hi:[0,1]
	v_pk_mul_f32 v[24:25], v[192:193], v[24:25] op_sel_hi:[0,1]
	v_pk_mul_f32 v[26:27], v[192:193], v[26:27] op_sel_hi:[0,1]
	v_pk_mul_f32 v[28:29], v[192:193], v[28:29] op_sel_hi:[0,1]
	v_pk_mul_f32 v[30:31], v[192:193], v[30:31] op_sel_hi:[0,1]
	v_pk_mul_f32 v[16:17], v[64:65], v[16:17]
	v_pk_mul_f32 v[18:19], v[66:67], v[18:19]
	v_pk_mul_f32 v[20:21], v[68:69], v[20:21]
	v_pk_mul_f32 v[22:23], v[70:71], v[22:23]
	v_pk_mul_f32 v[24:25], v[72:73], v[24:25]
	v_pk_mul_f32 v[26:27], v[74:75], v[26:27]
	v_pk_mul_f32 v[28:29], v[76:77], v[28:29]
	v_pk_mul_f32 v[30:31], v[78:79], v[30:31]
	v_pk_fma_f32 v[16:17], v[80:81], v[16:17], v[162:163]
	v_pk_fma_f32 v[18:19], v[82:83], v[18:19], v[164:165]
	v_pk_fma_f32 v[20:21], v[84:85], v[20:21], v[166:167]
	v_pk_fma_f32 v[22:23], v[86:87], v[22:23], v[168:169]
	v_pk_fma_f32 v[24:25], v[88:89], v[24:25], v[170:171]
	v_pk_fma_f32 v[26:27], v[90:91], v[26:27], v[172:173]
	v_pk_fma_f32 v[28:29], v[92:93], v[28:29], v[174:175]
	v_pk_fma_f32 v[30:31], v[94:95], v[30:31], v[176:177]
	v_cvt_pk_bf16_f32 v212, v16, v17
	v_cvt_pk_bf16_f32 v213, v18, v19
	v_cvt_pk_bf16_f32 v214, v20, v21
	v_cvt_pk_bf16_f32 v215, v22, v23
	v_cvt_pk_bf16_f32 v216, v24, v25
	v_cvt_pk_bf16_f32 v217, v26, v27
	v_cvt_pk_bf16_f32 v218, v28, v29
	v_cvt_pk_bf16_f32 v219, v30, v31
	global_store_dwordx4 v203, v[212:215], s[48:49] sc1
	global_store_dwordx4 v203, v[216:219], s[48:49] offset:1024 sc1
	s_add_u32 s48, s48, 0x800
	s_addc_u32 s49, s49, 0
	v_pk_mul_f32 v[32:33], v[194:195], v[32:33] op_sel_hi:[0,1]
	v_pk_mul_f32 v[34:35], v[194:195], v[34:35] op_sel_hi:[0,1]
	v_pk_mul_f32 v[36:37], v[194:195], v[36:37] op_sel_hi:[0,1]
	v_pk_mul_f32 v[38:39], v[194:195], v[38:39] op_sel_hi:[0,1]
	v_pk_mul_f32 v[40:41], v[194:195], v[40:41] op_sel_hi:[0,1]
	v_pk_mul_f32 v[42:43], v[194:195], v[42:43] op_sel_hi:[0,1]
	v_pk_mul_f32 v[44:45], v[194:195], v[44:45] op_sel_hi:[0,1]
	v_pk_mul_f32 v[46:47], v[194:195], v[46:47] op_sel_hi:[0,1]
	v_pk_mul_f32 v[32:33], v[64:65], v[32:33]
	v_pk_mul_f32 v[34:35], v[66:67], v[34:35]
	v_pk_mul_f32 v[36:37], v[68:69], v[36:37]
	v_pk_mul_f32 v[38:39], v[70:71], v[38:39]
	v_pk_mul_f32 v[40:41], v[72:73], v[40:41]
	v_pk_mul_f32 v[42:43], v[74:75], v[42:43]
	v_pk_mul_f32 v[44:45], v[76:77], v[44:45]
	v_pk_mul_f32 v[46:47], v[78:79], v[46:47]
	v_pk_fma_f32 v[32:33], v[80:81], v[32:33], v[162:163]
	v_pk_fma_f32 v[34:35], v[82:83], v[34:35], v[164:165]
	v_pk_fma_f32 v[36:37], v[84:85], v[36:37], v[166:167]
	v_pk_fma_f32 v[38:39], v[86:87], v[38:39], v[168:169]
	v_pk_fma_f32 v[40:41], v[88:89], v[40:41], v[170:171]
	v_pk_fma_f32 v[42:43], v[90:91], v[42:43], v[172:173]
	v_pk_fma_f32 v[44:45], v[92:93], v[44:45], v[174:175]
	v_pk_fma_f32 v[46:47], v[94:95], v[46:47], v[176:177]
	v_cvt_pk_bf16_f32 v204, v32, v33
	v_cvt_pk_bf16_f32 v205, v34, v35
	v_cvt_pk_bf16_f32 v206, v36, v37
	v_cvt_pk_bf16_f32 v207, v38, v39
	v_cvt_pk_bf16_f32 v208, v40, v41
	v_cvt_pk_bf16_f32 v209, v42, v43
	v_cvt_pk_bf16_f32 v210, v44, v45
	v_cvt_pk_bf16_f32 v211, v46, v47
	global_store_dwordx4 v203, v[204:207], s[48:49] sc1
	global_store_dwordx4 v203, v[208:211], s[48:49] offset:1024 sc1
	s_add_u32 s48, s48, 0x800
	s_addc_u32 s49, s49, 0
	v_pk_mul_f32 v[48:49], v[196:197], v[48:49] op_sel_hi:[0,1]
	v_pk_mul_f32 v[50:51], v[196:197], v[50:51] op_sel_hi:[0,1]
	v_pk_mul_f32 v[52:53], v[196:197], v[52:53] op_sel_hi:[0,1]
	v_pk_mul_f32 v[54:55], v[196:197], v[54:55] op_sel_hi:[0,1]
	v_pk_mul_f32 v[56:57], v[196:197], v[56:57] op_sel_hi:[0,1]
	v_pk_mul_f32 v[58:59], v[196:197], v[58:59] op_sel_hi:[0,1]
	v_pk_mul_f32 v[60:61], v[196:197], v[60:61] op_sel_hi:[0,1]
	v_pk_mul_f32 v[62:63], v[196:197], v[62:63] op_sel_hi:[0,1]
	v_pk_mul_f32 v[48:49], v[64:65], v[48:49]
	v_pk_mul_f32 v[50:51], v[66:67], v[50:51]
	v_pk_mul_f32 v[52:53], v[68:69], v[52:53]
	v_pk_mul_f32 v[54:55], v[70:71], v[54:55]
	v_pk_mul_f32 v[56:57], v[72:73], v[56:57]
	v_pk_mul_f32 v[58:59], v[74:75], v[58:59]
	v_pk_mul_f32 v[60:61], v[76:77], v[60:61]
	v_pk_mul_f32 v[62:63], v[78:79], v[62:63]
	v_pk_fma_f32 v[48:49], v[80:81], v[48:49], v[162:163]
	v_pk_fma_f32 v[50:51], v[82:83], v[50:51], v[164:165]
	v_pk_fma_f32 v[52:53], v[84:85], v[52:53], v[166:167]
	v_pk_fma_f32 v[54:55], v[86:87], v[54:55], v[168:169]
	v_pk_fma_f32 v[56:57], v[88:89], v[56:57], v[170:171]
	v_pk_fma_f32 v[58:59], v[90:91], v[58:59], v[172:173]
	v_pk_fma_f32 v[60:61], v[92:93], v[60:61], v[174:175]
	v_pk_fma_f32 v[62:63], v[94:95], v[62:63], v[176:177]
	v_cvt_pk_bf16_f32 v212, v48, v49
	v_cvt_pk_bf16_f32 v213, v50, v51
	v_cvt_pk_bf16_f32 v214, v52, v53
	v_cvt_pk_bf16_f32 v215, v54, v55
	v_cvt_pk_bf16_f32 v216, v56, v57
	v_cvt_pk_bf16_f32 v217, v58, v59
	v_cvt_pk_bf16_f32 v218, v60, v61
	v_cvt_pk_bf16_f32 v219, v62, v63
	global_store_dwordx4 v203, v[212:215], s[48:49] sc1
	global_store_dwordx4 v203, v[216:219], s[48:49] offset:1024 sc1
	s_add_u32 s48, s48, 0x800
	s_addc_u32 s49, s49, 0
	buffer_load_dwordx4 v[0:3], v202, s[12:15], s11 offen sc1
	buffer_load_dwordx4 v[4:7], v202, s[12:15], s11 offen offset:16 sc1
	buffer_load_dwordx4 v[8:11], v202, s[12:15], s11 offen offset:2048 sc1
	buffer_load_dwordx4 v[12:15], v202, s[12:15], s11 offen offset:2064 sc1
	s_add_u32 s11, s11, 0x1000
	buffer_load_dwordx4 v[16:19], v202, s[12:15], s11 offen sc1
	buffer_load_dwordx4 v[20:23], v202, s[12:15], s11 offen offset:16 sc1
	buffer_load_dwordx4 v[24:27], v202, s[12:15], s11 offen offset:2048 sc1
	buffer_load_dwordx4 v[28:31], v202, s[12:15], s11 offen offset:2064 sc1
	s_add_u32 s11, s11, 0x1000
	buffer_load_dwordx4 v[32:35], v202, s[12:15], s11 offen sc1
	buffer_load_dwordx4 v[36:39], v202, s[12:15], s11 offen offset:16 sc1
	buffer_load_dwordx4 v[40:43], v202, s[12:15], s11 offen offset:2048 sc1
	buffer_load_dwordx4 v[44:47], v202, s[12:15], s11 offen offset:2064 sc1
	s_add_u32 s11, s11, 0x1000
	buffer_load_dwordx4 v[48:51], v202, s[12:15], s11 offen sc1
	buffer_load_dwordx4 v[52:55], v202, s[12:15], s11 offen offset:16 sc1
	buffer_load_dwordx4 v[56:59], v202, s[12:15], s11 offen offset:2048 sc1
	buffer_load_dwordx4 v[60:63], v202, s[12:15], s11 offen offset:2064 sc1
	s_add_u32 s11, s11, 0x1000
	s_waitcnt vmcnt(24)
	v_mul_f32_e32 v178, v98, v98
	v_mul_f32_e32 v179, v114, v114
	v_mul_f32_e32 v180, v130, v130
	v_mul_f32_e32 v181, v146, v146
	v_fma_f32 v178, v99, v99, v178
	v_fma_f32 v179, v115, v115, v179
	v_fma_f32 v180, v131, v131, v180
	v_fma_f32 v181, v147, v147, v181
	v_fma_f32 v178, v100, v100, v178
	v_fma_f32 v179, v116, v116, v179
	v_fma_f32 v180, v132, v132, v180
	v_fma_f32 v181, v148, v148, v181
	v_fma_f32 v178, v101, v101, v178
	v_fma_f32 v179, v117, v117, v179
	v_fma_f32 v180, v133, v133, v180
	v_fma_f32 v181, v149, v149, v181
	v_fma_f32 v178, v102, v102, v178
	v_fma_f32 v179, v118, v118, v179
	v_fma_f32 v180, v134, v134, v180
	v_fma_f32 v181, v150, v150, v181
	v_fma_f32 v178, v103, v103, v178
	v_fma_f32 v179, v119, v119, v179
	v_fma_f32 v180, v135, v135, v180
	v_fma_f32 v181, v151, v151, v181
	v_fma_f32 v178, v104, v104, v178
	v_fma_f32 v179, v120, v120, v179
	v_fma_f32 v180, v136, v136, v180
	v_fma_f32 v181, v152, v152, v181
	v_fma_f32 v178, v105, v105, v178
	v_fma_f32 v179, v121, v121, v179
	v_fma_f32 v180, v137, v137, v180
	v_fma_f32 v181, v153, v153, v181
	v_fma_f32 v178, v106, v106, v178
	v_fma_f32 v179, v122, v122, v179
	v_fma_f32 v180, v138, v138, v180
	v_fma_f32 v181, v154, v154, v181
	v_fma_f32 v178, v107, v107, v178
	v_fma_f32 v179, v123, v123, v179
	v_fma_f32 v180, v139, v139, v180
	v_fma_f32 v181, v155, v155, v181
	v_fma_f32 v178, v108, v108, v178
	v_fma_f32 v179, v124, v124, v179
	v_fma_f32 v180, v140, v140, v180
	v_fma_f32 v181, v156, v156, v181
	v_fma_f32 v178, v109, v109, v178
	v_fma_f32 v179, v125, v125, v179
	v_fma_f32 v180, v141, v141, v180
	v_fma_f32 v181, v157, v157, v181
	v_fma_f32 v178, v110, v110, v178
	v_fma_f32 v179, v126, v126, v179
	v_fma_f32 v180, v142, v142, v180
	v_fma_f32 v181, v158, v158, v181
	v_fma_f32 v178, v111, v111, v178
	v_fma_f32 v179, v127, v127, v179
	v_fma_f32 v180, v143, v143, v180
	v_fma_f32 v181, v159, v159, v181
	v_fma_f32 v178, v112, v112, v178
	v_fma_f32 v179, v128, v128, v179
	v_fma_f32 v180, v144, v144, v180
	v_fma_f32 v181, v160, v160, v181
	v_fma_f32 v178, v113, v113, v178
	v_fma_f32 v179, v129, v129, v179
	v_fma_f32 v180, v145, v145, v180
	v_fma_f32 v181, v161, v161, v181
	v_add_f32_dpp v178, v178, v178 quad_perm:[1,0,3,2] row_mask:0xf bank_mask:0xf
	v_add_f32_dpp v179, v179, v179 quad_perm:[1,0,3,2] row_mask:0xf bank_mask:0xf
	v_add_f32_dpp v180, v180, v180 quad_perm:[1,0,3,2] row_mask:0xf bank_mask:0xf
	v_add_f32_dpp v181, v181, v181 quad_perm:[1,0,3,2] row_mask:0xf bank_mask:0xf
	v_add_f32_dpp v178, v178, v178 quad_perm:[2,3,0,1] row_mask:0xf bank_mask:0xf
	v_add_f32_dpp v179, v179, v179 quad_perm:[2,3,0,1] row_mask:0xf bank_mask:0xf
	v_add_f32_dpp v180, v180, v180 quad_perm:[2,3,0,1] row_mask:0xf bank_mask:0xf
	v_add_f32_dpp v181, v181, v181 quad_perm:[2,3,0,1] row_mask:0xf bank_mask:0xf
	v_add_f32_dpp v178, v178, v178 row_half_mirror row_mask:0xf bank_mask:0xf
	v_add_f32_dpp v179, v179, v179 row_half_mirror row_mask:0xf bank_mask:0xf
	v_add_f32_dpp v180, v180, v180 row_half_mirror row_mask:0xf bank_mask:0xf
	v_add_f32_dpp v181, v181, v181 row_half_mirror row_mask:0xf bank_mask:0xf
	v_add_f32_dpp v178, v178, v178 row_ror:8 row_mask:0xf bank_mask:0xf
	v_add_f32_dpp v179, v179, v179 row_ror:8 row_mask:0xf bank_mask:0xf
	v_add_f32_dpp v180, v180, v180 row_ror:8 row_mask:0xf bank_mask:0xf
	v_add_f32_dpp v181, v181, v181 row_ror:8 row_mask:0xf bank_mask:0xf
	v_mov_b32_e32 v182, v178
	v_mov_b32_e32 v183, v179
	v_mov_b32_e32 v184, v180
	v_mov_b32_e32 v185, v181
	v_permlane16_swap_b32_e32 v182, v178
	v_permlane16_swap_b32_e32 v183, v179
	v_permlane16_swap_b32_e32 v184, v180
	v_permlane16_swap_b32_e32 v185, v181
	v_add_f32_e32 v178, v178, v182
	v_add_f32_e32 v179, v179, v183
	v_add_f32_e32 v180, v180, v184
	v_add_f32_e32 v181, v181, v185
	v_mov_b32_e32 v182, v178
	v_mov_b32_e32 v183, v179
	v_mov_b32_e32 v184, v180
	v_mov_b32_e32 v185, v181
	v_permlane32_swap_b32_e32 v182, v178
	v_permlane32_swap_b32_e32 v183, v179
	v_permlane32_swap_b32_e32 v184, v180
	v_permlane32_swap_b32_e32 v185, v181
	v_add_f32_e32 v178, v178, v182
	v_add_f32_e32 v179, v179, v183
	v_add_f32_e32 v180, v180, v184
	v_add_f32_e32 v181, v181, v185
	v_fmamk_f32 v198, v178, 0x3a800000, v225
	v_fmamk_f32 v199, v179, 0x3a800000, v225
	v_fmamk_f32 v200, v180, 0x3a800000, v225
	v_fmamk_f32 v201, v181, 0x3a800000, v225
	v_mul_f32_e32 v182, 0x4b800000, v198
	v_mul_f32_e32 v183, 0x4b800000, v199
	v_mul_f32_e32 v184, 0x4b800000, v200
	v_mul_f32_e32 v185, 0x4b800000, v201
	v_cmp_gt_f32_e64 s[2:3], s30, v198
	v_cmp_gt_f32_e64 s[50:51], s30, v199
	v_cmp_gt_f32_e64 s[88:89], s30, v200
	v_cmp_gt_f32_e64 s[90:91], s30, v201
	v_cndmask_b32_e64 v198, v198, v182, s[2:3]
	v_cndmask_b32_e64 v199, v199, v183, s[50:51]
	v_cndmask_b32_e64 v200, v200, v184, s[88:89]
	v_cndmask_b32_e64 v201, v201, v185, s[90:91]
	v_rsq_f32_e32 v198, v198
	v_rsq_f32_e32 v199, v199
	v_rsq_f32_e32 v200, v200
	v_rsq_f32_e32 v201, v201
	v_mul_f32_e32 v182, 0x45800000, v198
	v_mul_f32_e32 v183, 0x45800000, v199
	v_mul_f32_e32 v184, 0x45800000, v200
	v_mul_f32_e32 v185, 0x45800000, v201
	v_cndmask_b32_e64 v186, v198, v182, s[2:3]
	v_cndmask_b32_e64 v192, v199, v183, s[50:51]
	v_cndmask_b32_e64 v194, v200, v184, s[88:89]
	v_cndmask_b32_e64 v196, v201, v185, s[90:91]
	v_pk_mul_f32 v[98:99], v[186:187], v[98:99] op_sel_hi:[0,1]
	v_pk_mul_f32 v[100:101], v[186:187], v[100:101] op_sel_hi:[0,1]
	v_pk_mul_f32 v[102:103], v[186:187], v[102:103] op_sel_hi:[0,1]
	v_pk_mul_f32 v[104:105], v[186:187], v[104:105] op_sel_hi:[0,1]
	v_pk_mul_f32 v[106:107], v[186:187], v[106:107] op_sel_hi:[0,1]
	v_pk_mul_f32 v[108:109], v[186:187], v[108:109] op_sel_hi:[0,1]
	v_pk_mul_f32 v[110:111], v[186:187], v[110:111] op_sel_hi:[0,1]
	v_pk_mul_f32 v[112:113], v[186:187], v[112:113] op_sel_hi:[0,1]
	v_pk_mul_f32 v[98:99], v[64:65], v[98:99]
	v_pk_mul_f32 v[100:101], v[66:67], v[100:101]
	v_pk_mul_f32 v[102:103], v[68:69], v[102:103]
	v_pk_mul_f32 v[104:105], v[70:71], v[104:105]
	v_pk_mul_f32 v[106:107], v[72:73], v[106:107]
	v_pk_mul_f32 v[108:109], v[74:75], v[108:109]
	v_pk_mul_f32 v[110:111], v[76:77], v[110:111]
	v_pk_mul_f32 v[112:113], v[78:79], v[112:113]
	v_pk_fma_f32 v[98:99], v[80:81], v[98:99], v[162:163]
	v_pk_fma_f32 v[100:101], v[82:83], v[100:101], v[164:165]
	v_pk_fma_f32 v[102:103], v[84:85], v[102:103], v[166:167]
	v_pk_fma_f32 v[104:105], v[86:87], v[104:105], v[168:169]
	v_pk_fma_f32 v[106:107], v[88:89], v[106:107], v[170:171]
	v_pk_fma_f32 v[108:109], v[90:91], v[108:109], v[172:173]
	v_pk_fma_f32 v[110:111], v[92:93], v[110:111], v[174:175]
	v_pk_fma_f32 v[112:113], v[94:95], v[112:113], v[176:177]
	v_cvt_pk_bf16_f32 v204, v98, v99
	v_cvt_pk_bf16_f32 v205, v100, v101
	v_cvt_pk_bf16_f32 v206, v102, v103
	v_cvt_pk_bf16_f32 v207, v104, v105
	v_cvt_pk_bf16_f32 v208, v106, v107
	v_cvt_pk_bf16_f32 v209, v108, v109
	v_cvt_pk_bf16_f32 v210, v110, v111
	v_cvt_pk_bf16_f32 v211, v112, v113
	global_store_dwordx4 v203, v[204:207], s[48:49] sc1
	global_store_dwordx4 v203, v[208:211], s[48:49] offset:1024 sc1
	s_add_u32 s48, s48, 0x800
	s_addc_u32 s49, s49, 0
	v_pk_mul_f32 v[114:115], v[192:193], v[114:115] op_sel_hi:[0,1]
	v_pk_mul_f32 v[116:117], v[192:193], v[116:117] op_sel_hi:[0,1]
	v_pk_mul_f32 v[118:119], v[192:193], v[118:119] op_sel_hi:[0,1]
	v_pk_mul_f32 v[120:121], v[192:193], v[120:121] op_sel_hi:[0,1]
	v_pk_mul_f32 v[122:123], v[192:193], v[122:123] op_sel_hi:[0,1]
	v_pk_mul_f32 v[124:125], v[192:193], v[124:125] op_sel_hi:[0,1]
	v_pk_mul_f32 v[126:127], v[192:193], v[126:127] op_sel_hi:[0,1]
	v_pk_mul_f32 v[128:129], v[192:193], v[128:129] op_sel_hi:[0,1]
	v_pk_mul_f32 v[114:115], v[64:65], v[114:115]
	v_pk_mul_f32 v[116:117], v[66:67], v[116:117]
	v_pk_mul_f32 v[118:119], v[68:69], v[118:119]
	v_pk_mul_f32 v[120:121], v[70:71], v[120:121]
	v_pk_mul_f32 v[122:123], v[72:73], v[122:123]
	v_pk_mul_f32 v[124:125], v[74:75], v[124:125]
	v_pk_mul_f32 v[126:127], v[76:77], v[126:127]
	v_pk_mul_f32 v[128:129], v[78:79], v[128:129]
	v_pk_fma_f32 v[114:115], v[80:81], v[114:115], v[162:163]
	v_pk_fma_f32 v[116:117], v[82:83], v[116:117], v[164:165]
	v_pk_fma_f32 v[118:119], v[84:85], v[118:119], v[166:167]
	v_pk_fma_f32 v[120:121], v[86:87], v[120:121], v[168:169]
	v_pk_fma_f32 v[122:123], v[88:89], v[122:123], v[170:171]
	v_pk_fma_f32 v[124:125], v[90:91], v[124:125], v[172:173]
	v_pk_fma_f32 v[126:127], v[92:93], v[126:127], v[174:175]
	v_pk_fma_f32 v[128:129], v[94:95], v[128:129], v[176:177]
	v_cvt_pk_bf16_f32 v212, v114, v115
	v_cvt_pk_bf16_f32 v213, v116, v117
	v_cvt_pk_bf16_f32 v214, v118, v119
	v_cvt_pk_bf16_f32 v215, v120, v121
	v_cvt_pk_bf16_f32 v216, v122, v123
	v_cvt_pk_bf16_f32 v217, v124, v125
	v_cvt_pk_bf16_f32 v218, v126, v127
	v_cvt_pk_bf16_f32 v219, v128, v129
	global_store_dwordx4 v203, v[212:215], s[48:49] sc1
	global_store_dwordx4 v203, v[216:219], s[48:49] offset:1024 sc1
	s_add_u32 s48, s48, 0x800
	s_addc_u32 s49, s49, 0
	v_pk_mul_f32 v[130:131], v[194:195], v[130:131] op_sel_hi:[0,1]
	v_pk_mul_f32 v[132:133], v[194:195], v[132:133] op_sel_hi:[0,1]
	v_pk_mul_f32 v[134:135], v[194:195], v[134:135] op_sel_hi:[0,1]
	v_pk_mul_f32 v[136:137], v[194:195], v[136:137] op_sel_hi:[0,1]
	v_pk_mul_f32 v[138:139], v[194:195], v[138:139] op_sel_hi:[0,1]
	v_pk_mul_f32 v[140:141], v[194:195], v[140:141] op_sel_hi:[0,1]
	v_pk_mul_f32 v[142:143], v[194:195], v[142:143] op_sel_hi:[0,1]
	v_pk_mul_f32 v[144:145], v[194:195], v[144:145] op_sel_hi:[0,1]
	v_pk_mul_f32 v[130:131], v[64:65], v[130:131]
	v_pk_mul_f32 v[132:133], v[66:67], v[132:133]
	v_pk_mul_f32 v[134:135], v[68:69], v[134:135]
	v_pk_mul_f32 v[136:137], v[70:71], v[136:137]
	v_pk_mul_f32 v[138:139], v[72:73], v[138:139]
	v_pk_mul_f32 v[140:141], v[74:75], v[140:141]
	v_pk_mul_f32 v[142:143], v[76:77], v[142:143]
	v_pk_mul_f32 v[144:145], v[78:79], v[144:145]
	v_pk_fma_f32 v[130:131], v[80:81], v[130:131], v[162:163]
	v_pk_fma_f32 v[132:133], v[82:83], v[132:133], v[164:165]
	v_pk_fma_f32 v[134:135], v[84:85], v[134:135], v[166:167]
	v_pk_fma_f32 v[136:137], v[86:87], v[136:137], v[168:169]
	v_pk_fma_f32 v[138:139], v[88:89], v[138:139], v[170:171]
	v_pk_fma_f32 v[140:141], v[90:91], v[140:141], v[172:173]
	v_pk_fma_f32 v[142:143], v[92:93], v[142:143], v[174:175]
	v_pk_fma_f32 v[144:145], v[94:95], v[144:145], v[176:177]
	v_cvt_pk_bf16_f32 v204, v130, v131
	v_cvt_pk_bf16_f32 v205, v132, v133
	v_cvt_pk_bf16_f32 v206, v134, v135
	v_cvt_pk_bf16_f32 v207, v136, v137
	v_cvt_pk_bf16_f32 v208, v138, v139
	v_cvt_pk_bf16_f32 v209, v140, v141
	v_cvt_pk_bf16_f32 v210, v142, v143
	v_cvt_pk_bf16_f32 v211, v144, v145
	global_store_dwordx4 v203, v[204:207], s[48:49] sc1
	global_store_dwordx4 v203, v[208:211], s[48:49] offset:1024 sc1
	s_add_u32 s48, s48, 0x800
	s_addc_u32 s49, s49, 0
	v_pk_mul_f32 v[146:147], v[196:197], v[146:147] op_sel_hi:[0,1]
	v_pk_mul_f32 v[148:149], v[196:197], v[148:149] op_sel_hi:[0,1]
	v_pk_mul_f32 v[150:151], v[196:197], v[150:151] op_sel_hi:[0,1]
	v_pk_mul_f32 v[152:153], v[196:197], v[152:153] op_sel_hi:[0,1]
	v_pk_mul_f32 v[154:155], v[196:197], v[154:155] op_sel_hi:[0,1]
	v_pk_mul_f32 v[156:157], v[196:197], v[156:157] op_sel_hi:[0,1]
	v_pk_mul_f32 v[158:159], v[196:197], v[158:159] op_sel_hi:[0,1]
	v_pk_mul_f32 v[160:161], v[196:197], v[160:161] op_sel_hi:[0,1]
	v_pk_mul_f32 v[146:147], v[64:65], v[146:147]
	v_pk_mul_f32 v[148:149], v[66:67], v[148:149]
	v_pk_mul_f32 v[150:151], v[68:69], v[150:151]
	v_pk_mul_f32 v[152:153], v[70:71], v[152:153]
	v_pk_mul_f32 v[154:155], v[72:73], v[154:155]
	v_pk_mul_f32 v[156:157], v[74:75], v[156:157]
	v_pk_mul_f32 v[158:159], v[76:77], v[158:159]
	v_pk_mul_f32 v[160:161], v[78:79], v[160:161]
	v_pk_fma_f32 v[146:147], v[80:81], v[146:147], v[162:163]
	v_pk_fma_f32 v[148:149], v[82:83], v[148:149], v[164:165]
	v_pk_fma_f32 v[150:151], v[84:85], v[150:151], v[166:167]
	v_pk_fma_f32 v[152:153], v[86:87], v[152:153], v[168:169]
	v_pk_fma_f32 v[154:155], v[88:89], v[154:155], v[170:171]
	v_pk_fma_f32 v[156:157], v[90:91], v[156:157], v[172:173]
	v_pk_fma_f32 v[158:159], v[92:93], v[158:159], v[174:175]
	v_pk_fma_f32 v[160:161], v[94:95], v[160:161], v[176:177]
	v_cvt_pk_bf16_f32 v212, v146, v147
	v_cvt_pk_bf16_f32 v213, v148, v149
	v_cvt_pk_bf16_f32 v214, v150, v151
	v_cvt_pk_bf16_f32 v215, v152, v153
	v_cvt_pk_bf16_f32 v216, v154, v155
	v_cvt_pk_bf16_f32 v217, v156, v157
	v_cvt_pk_bf16_f32 v218, v158, v159
	v_cvt_pk_bf16_f32 v219, v160, v161
	global_store_dwordx4 v203, v[212:215], s[48:49] sc1
	global_store_dwordx4 v203, v[216:219], s[48:49] offset:1024 sc1
	s_add_u32 s48, s48, 0x800
	s_addc_u32 s49, s49, 0
	buffer_load_dwordx4 v[98:101], v202, s[12:15], s11 offen sc1
	buffer_load_dwordx4 v[102:105], v202, s[12:15], s11 offen offset:16 sc1
	buffer_load_dwordx4 v[106:109], v202, s[12:15], s11 offen offset:2048 sc1
	buffer_load_dwordx4 v[110:113], v202, s[12:15], s11 offen offset:2064 sc1
	s_add_u32 s11, s11, 0x1000
	buffer_load_dwordx4 v[114:117], v202, s[12:15], s11 offen sc1
	buffer_load_dwordx4 v[118:121], v202, s[12:15], s11 offen offset:16 sc1
	buffer_load_dwordx4 v[122:125], v202, s[12:15], s11 offen offset:2048 sc1
	buffer_load_dwordx4 v[126:129], v202, s[12:15], s11 offen offset:2064 sc1
	s_add_u32 s11, s11, 0x1000
	buffer_load_dwordx4 v[130:133], v202, s[12:15], s11 offen sc1
	buffer_load_dwordx4 v[134:137], v202, s[12:15], s11 offen offset:16 sc1
	buffer_load_dwordx4 v[138:141], v202, s[12:15], s11 offen offset:2048 sc1
	buffer_load_dwordx4 v[142:145], v202, s[12:15], s11 offen offset:2064 sc1
	s_add_u32 s11, s11, 0x1000
	buffer_load_dwordx4 v[146:149], v202, s[12:15], s11 offen sc1
	buffer_load_dwordx4 v[150:153], v202, s[12:15], s11 offen offset:16 sc1
	buffer_load_dwordx4 v[154:157], v202, s[12:15], s11 offen offset:2048 sc1
	buffer_load_dwordx4 v[158:161], v202, s[12:15], s11 offen offset:2064 sc1
	s_add_u32 s11, s11, 0x1000
	s_waitcnt vmcnt(24)
	v_mul_f32_e32 v178, v0, v0
	v_mul_f32_e32 v179, v16, v16
	v_mul_f32_e32 v180, v32, v32
	v_mul_f32_e32 v181, v48, v48
	v_fma_f32 v178, v1, v1, v178
	v_fma_f32 v179, v17, v17, v179
	v_fma_f32 v180, v33, v33, v180
	v_fma_f32 v181, v49, v49, v181
	v_fma_f32 v178, v2, v2, v178
	v_fma_f32 v179, v18, v18, v179
	v_fma_f32 v180, v34, v34, v180
	v_fma_f32 v181, v50, v50, v181
	v_fma_f32 v178, v3, v3, v178
	v_fma_f32 v179, v19, v19, v179
	v_fma_f32 v180, v35, v35, v180
	v_fma_f32 v181, v51, v51, v181
	v_fma_f32 v178, v4, v4, v178
	v_fma_f32 v179, v20, v20, v179
	v_fma_f32 v180, v36, v36, v180
	v_fma_f32 v181, v52, v52, v181
	v_fma_f32 v178, v5, v5, v178
	v_fma_f32 v179, v21, v21, v179
	v_fma_f32 v180, v37, v37, v180
	v_fma_f32 v181, v53, v53, v181
	v_fma_f32 v178, v6, v6, v178
	v_fma_f32 v179, v22, v22, v179
	v_fma_f32 v180, v38, v38, v180
	v_fma_f32 v181, v54, v54, v181
	v_fma_f32 v178, v7, v7, v178
	v_fma_f32 v179, v23, v23, v179
	v_fma_f32 v180, v39, v39, v180
	v_fma_f32 v181, v55, v55, v181
	v_fma_f32 v178, v8, v8, v178
	v_fma_f32 v179, v24, v24, v179
	v_fma_f32 v180, v40, v40, v180
	v_fma_f32 v181, v56, v56, v181
	v_fma_f32 v178, v9, v9, v178
	v_fma_f32 v179, v25, v25, v179
	v_fma_f32 v180, v41, v41, v180
	v_fma_f32 v181, v57, v57, v181
	v_fma_f32 v178, v10, v10, v178
	v_fma_f32 v179, v26, v26, v179
	v_fma_f32 v180, v42, v42, v180
	v_fma_f32 v181, v58, v58, v181
	v_fma_f32 v178, v11, v11, v178
	v_fma_f32 v179, v27, v27, v179
	v_fma_f32 v180, v43, v43, v180
	v_fma_f32 v181, v59, v59, v181
	v_fma_f32 v178, v12, v12, v178
	v_fma_f32 v179, v28, v28, v179
	v_fma_f32 v180, v44, v44, v180
	v_fma_f32 v181, v60, v60, v181
	v_fma_f32 v178, v13, v13, v178
	v_fma_f32 v179, v29, v29, v179
	v_fma_f32 v180, v45, v45, v180
	v_fma_f32 v181, v61, v61, v181
	v_fma_f32 v178, v14, v14, v178
	v_fma_f32 v179, v30, v30, v179
	v_fma_f32 v180, v46, v46, v180
	v_fma_f32 v181, v62, v62, v181
	v_fma_f32 v178, v15, v15, v178
	v_fma_f32 v179, v31, v31, v179
	v_fma_f32 v180, v47, v47, v180
	v_fma_f32 v181, v63, v63, v181
	v_add_f32_dpp v178, v178, v178 quad_perm:[1,0,3,2] row_mask:0xf bank_mask:0xf
	v_add_f32_dpp v179, v179, v179 quad_perm:[1,0,3,2] row_mask:0xf bank_mask:0xf
	v_add_f32_dpp v180, v180, v180 quad_perm:[1,0,3,2] row_mask:0xf bank_mask:0xf
	v_add_f32_dpp v181, v181, v181 quad_perm:[1,0,3,2] row_mask:0xf bank_mask:0xf
	v_add_f32_dpp v178, v178, v178 quad_perm:[2,3,0,1] row_mask:0xf bank_mask:0xf
	v_add_f32_dpp v179, v179, v179 quad_perm:[2,3,0,1] row_mask:0xf bank_mask:0xf
	v_add_f32_dpp v180, v180, v180 quad_perm:[2,3,0,1] row_mask:0xf bank_mask:0xf
	v_add_f32_dpp v181, v181, v181 quad_perm:[2,3,0,1] row_mask:0xf bank_mask:0xf
	v_add_f32_dpp v178, v178, v178 row_half_mirror row_mask:0xf bank_mask:0xf
	v_add_f32_dpp v179, v179, v179 row_half_mirror row_mask:0xf bank_mask:0xf
	v_add_f32_dpp v180, v180, v180 row_half_mirror row_mask:0xf bank_mask:0xf
	v_add_f32_dpp v181, v181, v181 row_half_mirror row_mask:0xf bank_mask:0xf
	v_add_f32_dpp v178, v178, v178 row_ror:8 row_mask:0xf bank_mask:0xf
	v_add_f32_dpp v179, v179, v179 row_ror:8 row_mask:0xf bank_mask:0xf
	v_add_f32_dpp v180, v180, v180 row_ror:8 row_mask:0xf bank_mask:0xf
	v_add_f32_dpp v181, v181, v181 row_ror:8 row_mask:0xf bank_mask:0xf
	v_mov_b32_e32 v182, v178
	v_mov_b32_e32 v183, v179
	v_mov_b32_e32 v184, v180
	v_mov_b32_e32 v185, v181
	v_permlane16_swap_b32_e32 v182, v178
	v_permlane16_swap_b32_e32 v183, v179
	v_permlane16_swap_b32_e32 v184, v180
	v_permlane16_swap_b32_e32 v185, v181
	v_add_f32_e32 v178, v178, v182
	v_add_f32_e32 v179, v179, v183
	v_add_f32_e32 v180, v180, v184
	v_add_f32_e32 v181, v181, v185
	v_mov_b32_e32 v182, v178
	v_mov_b32_e32 v183, v179
	v_mov_b32_e32 v184, v180
	v_mov_b32_e32 v185, v181
	v_permlane32_swap_b32_e32 v182, v178
	v_permlane32_swap_b32_e32 v183, v179
	v_permlane32_swap_b32_e32 v184, v180
	v_permlane32_swap_b32_e32 v185, v181
	v_add_f32_e32 v178, v178, v182
	v_add_f32_e32 v179, v179, v183
	v_add_f32_e32 v180, v180, v184
	v_add_f32_e32 v181, v181, v185
	v_fmamk_f32 v198, v178, 0x3a800000, v225
	v_fmamk_f32 v199, v179, 0x3a800000, v225
	v_fmamk_f32 v200, v180, 0x3a800000, v225
	v_fmamk_f32 v201, v181, 0x3a800000, v225
	v_mul_f32_e32 v182, 0x4b800000, v198
	v_mul_f32_e32 v183, 0x4b800000, v199
	v_mul_f32_e32 v184, 0x4b800000, v200
	v_mul_f32_e32 v185, 0x4b800000, v201
	v_cmp_gt_f32_e64 s[2:3], s30, v198
	v_cmp_gt_f32_e64 s[50:51], s30, v199
	v_cmp_gt_f32_e64 s[88:89], s30, v200
	v_cmp_gt_f32_e64 s[90:91], s30, v201
	v_cndmask_b32_e64 v198, v198, v182, s[2:3]
	v_cndmask_b32_e64 v199, v199, v183, s[50:51]
	v_cndmask_b32_e64 v200, v200, v184, s[88:89]
	v_cndmask_b32_e64 v201, v201, v185, s[90:91]
	v_rsq_f32_e32 v198, v198
	v_rsq_f32_e32 v199, v199
	v_rsq_f32_e32 v200, v200
	v_rsq_f32_e32 v201, v201
	v_mul_f32_e32 v182, 0x45800000, v198
	v_mul_f32_e32 v183, 0x45800000, v199
	v_mul_f32_e32 v184, 0x45800000, v200
	v_mul_f32_e32 v185, 0x45800000, v201
	v_cndmask_b32_e64 v186, v198, v182, s[2:3]
	v_cndmask_b32_e64 v192, v199, v183, s[50:51]
	v_cndmask_b32_e64 v194, v200, v184, s[88:89]
	v_cndmask_b32_e64 v196, v201, v185, s[90:91]
	v_pk_mul_f32 v[0:1], v[186:187], v[0:1] op_sel_hi:[0,1]
	v_pk_mul_f32 v[2:3], v[186:187], v[2:3] op_sel_hi:[0,1]
	v_pk_mul_f32 v[4:5], v[186:187], v[4:5] op_sel_hi:[0,1]
	v_pk_mul_f32 v[6:7], v[186:187], v[6:7] op_sel_hi:[0,1]
	v_pk_mul_f32 v[8:9], v[186:187], v[8:9] op_sel_hi:[0,1]
	v_pk_mul_f32 v[10:11], v[186:187], v[10:11] op_sel_hi:[0,1]
	v_pk_mul_f32 v[12:13], v[186:187], v[12:13] op_sel_hi:[0,1]
	v_pk_mul_f32 v[14:15], v[186:187], v[14:15] op_sel_hi:[0,1]
	v_pk_mul_f32 v[0:1], v[64:65], v[0:1]
	v_pk_mul_f32 v[2:3], v[66:67], v[2:3]
	v_pk_mul_f32 v[4:5], v[68:69], v[4:5]
	v_pk_mul_f32 v[6:7], v[70:71], v[6:7]
	v_pk_mul_f32 v[8:9], v[72:73], v[8:9]
	v_pk_mul_f32 v[10:11], v[74:75], v[10:11]
	v_pk_mul_f32 v[12:13], v[76:77], v[12:13]
	v_pk_mul_f32 v[14:15], v[78:79], v[14:15]
	v_pk_fma_f32 v[0:1], v[80:81], v[0:1], v[162:163]
	v_pk_fma_f32 v[2:3], v[82:83], v[2:3], v[164:165]
	v_pk_fma_f32 v[4:5], v[84:85], v[4:5], v[166:167]
	v_pk_fma_f32 v[6:7], v[86:87], v[6:7], v[168:169]
	v_pk_fma_f32 v[8:9], v[88:89], v[8:9], v[170:171]
	v_pk_fma_f32 v[10:11], v[90:91], v[10:11], v[172:173]
	v_pk_fma_f32 v[12:13], v[92:93], v[12:13], v[174:175]
	v_pk_fma_f32 v[14:15], v[94:95], v[14:15], v[176:177]
	v_cvt_pk_bf16_f32 v204, v0, v1
	v_cvt_pk_bf16_f32 v205, v2, v3
	v_cvt_pk_bf16_f32 v206, v4, v5
	v_cvt_pk_bf16_f32 v207, v6, v7
	v_cvt_pk_bf16_f32 v208, v8, v9
	v_cvt_pk_bf16_f32 v209, v10, v11
	v_cvt_pk_bf16_f32 v210, v12, v13
	v_cvt_pk_bf16_f32 v211, v14, v15
	global_store_dwordx4 v203, v[204:207], s[48:49] sc1
	global_store_dwordx4 v203, v[208:211], s[48:49] offset:1024 sc1
	s_add_u32 s48, s48, 0x800
	s_addc_u32 s49, s49, 0
	v_pk_mul_f32 v[16:17], v[192:193], v[16:17] op_sel_hi:[0,1]
	v_pk_mul_f32 v[18:19], v[192:193], v[18:19] op_sel_hi:[0,1]
	v_pk_mul_f32 v[20:21], v[192:193], v[20:21] op_sel_hi:[0,1]
	v_pk_mul_f32 v[22:23], v[192:193], v[22:23] op_sel_hi:[0,1]
	v_pk_mul_f32 v[24:25], v[192:193], v[24:25] op_sel_hi:[0,1]
	v_pk_mul_f32 v[26:27], v[192:193], v[26:27] op_sel_hi:[0,1]
	v_pk_mul_f32 v[28:29], v[192:193], v[28:29] op_sel_hi:[0,1]
	v_pk_mul_f32 v[30:31], v[192:193], v[30:31] op_sel_hi:[0,1]
	v_pk_mul_f32 v[16:17], v[64:65], v[16:17]
	v_pk_mul_f32 v[18:19], v[66:67], v[18:19]
	v_pk_mul_f32 v[20:21], v[68:69], v[20:21]
	v_pk_mul_f32 v[22:23], v[70:71], v[22:23]
	v_pk_mul_f32 v[24:25], v[72:73], v[24:25]
	v_pk_mul_f32 v[26:27], v[74:75], v[26:27]
	v_pk_mul_f32 v[28:29], v[76:77], v[28:29]
	v_pk_mul_f32 v[30:31], v[78:79], v[30:31]
	v_pk_fma_f32 v[16:17], v[80:81], v[16:17], v[162:163]
	v_pk_fma_f32 v[18:19], v[82:83], v[18:19], v[164:165]
	v_pk_fma_f32 v[20:21], v[84:85], v[20:21], v[166:167]
	v_pk_fma_f32 v[22:23], v[86:87], v[22:23], v[168:169]
	v_pk_fma_f32 v[24:25], v[88:89], v[24:25], v[170:171]
	v_pk_fma_f32 v[26:27], v[90:91], v[26:27], v[172:173]
	v_pk_fma_f32 v[28:29], v[92:93], v[28:29], v[174:175]
	v_pk_fma_f32 v[30:31], v[94:95], v[30:31], v[176:177]
	v_cvt_pk_bf16_f32 v212, v16, v17
	v_cvt_pk_bf16_f32 v213, v18, v19
	v_cvt_pk_bf16_f32 v214, v20, v21
	v_cvt_pk_bf16_f32 v215, v22, v23
	v_cvt_pk_bf16_f32 v216, v24, v25
	v_cvt_pk_bf16_f32 v217, v26, v27
	v_cvt_pk_bf16_f32 v218, v28, v29
	v_cvt_pk_bf16_f32 v219, v30, v31
	global_store_dwordx4 v203, v[212:215], s[48:49] sc1
	global_store_dwordx4 v203, v[216:219], s[48:49] offset:1024 sc1
	s_add_u32 s48, s48, 0x800
	s_addc_u32 s49, s49, 0
	v_pk_mul_f32 v[32:33], v[194:195], v[32:33] op_sel_hi:[0,1]
	v_pk_mul_f32 v[34:35], v[194:195], v[34:35] op_sel_hi:[0,1]
	v_pk_mul_f32 v[36:37], v[194:195], v[36:37] op_sel_hi:[0,1]
	v_pk_mul_f32 v[38:39], v[194:195], v[38:39] op_sel_hi:[0,1]
	v_pk_mul_f32 v[40:41], v[194:195], v[40:41] op_sel_hi:[0,1]
	v_pk_mul_f32 v[42:43], v[194:195], v[42:43] op_sel_hi:[0,1]
	v_pk_mul_f32 v[44:45], v[194:195], v[44:45] op_sel_hi:[0,1]
	v_pk_mul_f32 v[46:47], v[194:195], v[46:47] op_sel_hi:[0,1]
	v_pk_mul_f32 v[32:33], v[64:65], v[32:33]
	v_pk_mul_f32 v[34:35], v[66:67], v[34:35]
	v_pk_mul_f32 v[36:37], v[68:69], v[36:37]
	v_pk_mul_f32 v[38:39], v[70:71], v[38:39]
	v_pk_mul_f32 v[40:41], v[72:73], v[40:41]
	v_pk_mul_f32 v[42:43], v[74:75], v[42:43]
	v_pk_mul_f32 v[44:45], v[76:77], v[44:45]
	v_pk_mul_f32 v[46:47], v[78:79], v[46:47]
	v_pk_fma_f32 v[32:33], v[80:81], v[32:33], v[162:163]
	v_pk_fma_f32 v[34:35], v[82:83], v[34:35], v[164:165]
	v_pk_fma_f32 v[36:37], v[84:85], v[36:37], v[166:167]
	v_pk_fma_f32 v[38:39], v[86:87], v[38:39], v[168:169]
	v_pk_fma_f32 v[40:41], v[88:89], v[40:41], v[170:171]
	v_pk_fma_f32 v[42:43], v[90:91], v[42:43], v[172:173]
	v_pk_fma_f32 v[44:45], v[92:93], v[44:45], v[174:175]
	v_pk_fma_f32 v[46:47], v[94:95], v[46:47], v[176:177]
	v_cvt_pk_bf16_f32 v204, v32, v33
	v_cvt_pk_bf16_f32 v205, v34, v35
	v_cvt_pk_bf16_f32 v206, v36, v37
	v_cvt_pk_bf16_f32 v207, v38, v39
	v_cvt_pk_bf16_f32 v208, v40, v41
	v_cvt_pk_bf16_f32 v209, v42, v43
	v_cvt_pk_bf16_f32 v210, v44, v45
	v_cvt_pk_bf16_f32 v211, v46, v47
	global_store_dwordx4 v203, v[204:207], s[48:49] sc1
	global_store_dwordx4 v203, v[208:211], s[48:49] offset:1024 sc1
	s_add_u32 s48, s48, 0x800
	s_addc_u32 s49, s49, 0
	v_pk_mul_f32 v[48:49], v[196:197], v[48:49] op_sel_hi:[0,1]
	v_pk_mul_f32 v[50:51], v[196:197], v[50:51] op_sel_hi:[0,1]
	v_pk_mul_f32 v[52:53], v[196:197], v[52:53] op_sel_hi:[0,1]
	v_pk_mul_f32 v[54:55], v[196:197], v[54:55] op_sel_hi:[0,1]
	v_pk_mul_f32 v[56:57], v[196:197], v[56:57] op_sel_hi:[0,1]
	v_pk_mul_f32 v[58:59], v[196:197], v[58:59] op_sel_hi:[0,1]
	v_pk_mul_f32 v[60:61], v[196:197], v[60:61] op_sel_hi:[0,1]
	v_pk_mul_f32 v[62:63], v[196:197], v[62:63] op_sel_hi:[0,1]
	v_pk_mul_f32 v[48:49], v[64:65], v[48:49]
	v_pk_mul_f32 v[50:51], v[66:67], v[50:51]
	v_pk_mul_f32 v[52:53], v[68:69], v[52:53]
	v_pk_mul_f32 v[54:55], v[70:71], v[54:55]
	v_pk_mul_f32 v[56:57], v[72:73], v[56:57]
	v_pk_mul_f32 v[58:59], v[74:75], v[58:59]
	v_pk_mul_f32 v[60:61], v[76:77], v[60:61]
	v_pk_mul_f32 v[62:63], v[78:79], v[62:63]
	v_pk_fma_f32 v[48:49], v[80:81], v[48:49], v[162:163]
	v_pk_fma_f32 v[50:51], v[82:83], v[50:51], v[164:165]
	v_pk_fma_f32 v[52:53], v[84:85], v[52:53], v[166:167]
	v_pk_fma_f32 v[54:55], v[86:87], v[54:55], v[168:169]
	v_pk_fma_f32 v[56:57], v[88:89], v[56:57], v[170:171]
	v_pk_fma_f32 v[58:59], v[90:91], v[58:59], v[172:173]
	v_pk_fma_f32 v[60:61], v[92:93], v[60:61], v[174:175]
	v_pk_fma_f32 v[62:63], v[94:95], v[62:63], v[176:177]
	v_cvt_pk_bf16_f32 v212, v48, v49
	v_cvt_pk_bf16_f32 v213, v50, v51
	v_cvt_pk_bf16_f32 v214, v52, v53
	v_cvt_pk_bf16_f32 v215, v54, v55
	v_cvt_pk_bf16_f32 v216, v56, v57
	v_cvt_pk_bf16_f32 v217, v58, v59
	v_cvt_pk_bf16_f32 v218, v60, v61
	v_cvt_pk_bf16_f32 v219, v62, v63
	global_store_dwordx4 v203, v[212:215], s[48:49] sc1
	global_store_dwordx4 v203, v[216:219], s[48:49] offset:1024 sc1
	s_add_u32 s48, s48, 0x800
	s_addc_u32 s49, s49, 0
	s_waitcnt vmcnt(8)
	v_mul_f32_e32 v178, v98, v98
	v_mul_f32_e32 v179, v114, v114
	v_mul_f32_e32 v180, v130, v130
	v_mul_f32_e32 v181, v146, v146
	v_fma_f32 v178, v99, v99, v178
	v_fma_f32 v179, v115, v115, v179
	v_fma_f32 v180, v131, v131, v180
	v_fma_f32 v181, v147, v147, v181
	v_fma_f32 v178, v100, v100, v178
	v_fma_f32 v179, v116, v116, v179
	v_fma_f32 v180, v132, v132, v180
	v_fma_f32 v181, v148, v148, v181
	v_fma_f32 v178, v101, v101, v178
	v_fma_f32 v179, v117, v117, v179
	v_fma_f32 v180, v133, v133, v180
	v_fma_f32 v181, v149, v149, v181
	v_fma_f32 v178, v102, v102, v178
	v_fma_f32 v179, v118, v118, v179
	v_fma_f32 v180, v134, v134, v180
	v_fma_f32 v181, v150, v150, v181
	v_fma_f32 v178, v103, v103, v178
	v_fma_f32 v179, v119, v119, v179
	v_fma_f32 v180, v135, v135, v180
	v_fma_f32 v181, v151, v151, v181
	v_fma_f32 v178, v104, v104, v178
	v_fma_f32 v179, v120, v120, v179
	v_fma_f32 v180, v136, v136, v180
	v_fma_f32 v181, v152, v152, v181
	v_fma_f32 v178, v105, v105, v178
	v_fma_f32 v179, v121, v121, v179
	v_fma_f32 v180, v137, v137, v180
	v_fma_f32 v181, v153, v153, v181
	v_fma_f32 v178, v106, v106, v178
	v_fma_f32 v179, v122, v122, v179
	v_fma_f32 v180, v138, v138, v180
	v_fma_f32 v181, v154, v154, v181
	v_fma_f32 v178, v107, v107, v178
	v_fma_f32 v179, v123, v123, v179
	v_fma_f32 v180, v139, v139, v180
	v_fma_f32 v181, v155, v155, v181
	v_fma_f32 v178, v108, v108, v178
	v_fma_f32 v179, v124, v124, v179
	v_fma_f32 v180, v140, v140, v180
	v_fma_f32 v181, v156, v156, v181
	v_fma_f32 v178, v109, v109, v178
	v_fma_f32 v179, v125, v125, v179
	v_fma_f32 v180, v141, v141, v180
	v_fma_f32 v181, v157, v157, v181
	v_fma_f32 v178, v110, v110, v178
	v_fma_f32 v179, v126, v126, v179
	v_fma_f32 v180, v142, v142, v180
	v_fma_f32 v181, v158, v158, v181
	v_fma_f32 v178, v111, v111, v178
	v_fma_f32 v179, v127, v127, v179
	v_fma_f32 v180, v143, v143, v180
	v_fma_f32 v181, v159, v159, v181
	v_fma_f32 v178, v112, v112, v178
	v_fma_f32 v179, v128, v128, v179
	v_fma_f32 v180, v144, v144, v180
	v_fma_f32 v181, v160, v160, v181
	v_fma_f32 v178, v113, v113, v178
	v_fma_f32 v179, v129, v129, v179
	v_fma_f32 v180, v145, v145, v180
	v_fma_f32 v181, v161, v161, v181
	v_add_f32_dpp v178, v178, v178 quad_perm:[1,0,3,2] row_mask:0xf bank_mask:0xf
	v_add_f32_dpp v179, v179, v179 quad_perm:[1,0,3,2] row_mask:0xf bank_mask:0xf
	v_add_f32_dpp v180, v180, v180 quad_perm:[1,0,3,2] row_mask:0xf bank_mask:0xf
	v_add_f32_dpp v181, v181, v181 quad_perm:[1,0,3,2] row_mask:0xf bank_mask:0xf
	v_add_f32_dpp v178, v178, v178 quad_perm:[2,3,0,1] row_mask:0xf bank_mask:0xf
	v_add_f32_dpp v179, v179, v179 quad_perm:[2,3,0,1] row_mask:0xf bank_mask:0xf
	v_add_f32_dpp v180, v180, v180 quad_perm:[2,3,0,1] row_mask:0xf bank_mask:0xf
	v_add_f32_dpp v181, v181, v181 quad_perm:[2,3,0,1] row_mask:0xf bank_mask:0xf
	v_add_f32_dpp v178, v178, v178 row_half_mirror row_mask:0xf bank_mask:0xf
	v_add_f32_dpp v179, v179, v179 row_half_mirror row_mask:0xf bank_mask:0xf
	v_add_f32_dpp v180, v180, v180 row_half_mirror row_mask:0xf bank_mask:0xf
	v_add_f32_dpp v181, v181, v181 row_half_mirror row_mask:0xf bank_mask:0xf
	v_add_f32_dpp v178, v178, v178 row_ror:8 row_mask:0xf bank_mask:0xf
	v_add_f32_dpp v179, v179, v179 row_ror:8 row_mask:0xf bank_mask:0xf
	v_add_f32_dpp v180, v180, v180 row_ror:8 row_mask:0xf bank_mask:0xf
	v_add_f32_dpp v181, v181, v181 row_ror:8 row_mask:0xf bank_mask:0xf
	v_mov_b32_e32 v182, v178
	v_mov_b32_e32 v183, v179
	v_mov_b32_e32 v184, v180
	v_mov_b32_e32 v185, v181
	v_permlane16_swap_b32_e32 v182, v178
	v_permlane16_swap_b32_e32 v183, v179
	v_permlane16_swap_b32_e32 v184, v180
	v_permlane16_swap_b32_e32 v185, v181
	v_add_f32_e32 v178, v178, v182
	v_add_f32_e32 v179, v179, v183
	v_add_f32_e32 v180, v180, v184
	v_add_f32_e32 v181, v181, v185
	v_mov_b32_e32 v182, v178
	v_mov_b32_e32 v183, v179
	v_mov_b32_e32 v184, v180
	v_mov_b32_e32 v185, v181
	v_permlane32_swap_b32_e32 v182, v178
	v_permlane32_swap_b32_e32 v183, v179
	v_permlane32_swap_b32_e32 v184, v180
	v_permlane32_swap_b32_e32 v185, v181
	v_add_f32_e32 v178, v178, v182
	v_add_f32_e32 v179, v179, v183
	v_add_f32_e32 v180, v180, v184
	v_add_f32_e32 v181, v181, v185
	v_fmamk_f32 v198, v178, 0x3a800000, v225
	v_fmamk_f32 v199, v179, 0x3a800000, v225
	v_fmamk_f32 v200, v180, 0x3a800000, v225
	v_fmamk_f32 v201, v181, 0x3a800000, v225
	v_mul_f32_e32 v182, 0x4b800000, v198
	v_mul_f32_e32 v183, 0x4b800000, v199
	v_mul_f32_e32 v184, 0x4b800000, v200
	v_mul_f32_e32 v185, 0x4b800000, v201
	v_cmp_gt_f32_e64 s[2:3], s30, v198
	v_cmp_gt_f32_e64 s[50:51], s30, v199
	v_cmp_gt_f32_e64 s[88:89], s30, v200
	v_cmp_gt_f32_e64 s[90:91], s30, v201
	v_cndmask_b32_e64 v198, v198, v182, s[2:3]
	v_cndmask_b32_e64 v199, v199, v183, s[50:51]
	v_cndmask_b32_e64 v200, v200, v184, s[88:89]
	v_cndmask_b32_e64 v201, v201, v185, s[90:91]
	v_rsq_f32_e32 v198, v198
	v_rsq_f32_e32 v199, v199
	v_rsq_f32_e32 v200, v200
	v_rsq_f32_e32 v201, v201
	v_mul_f32_e32 v182, 0x45800000, v198
	v_mul_f32_e32 v183, 0x45800000, v199
	v_mul_f32_e32 v184, 0x45800000, v200
	v_mul_f32_e32 v185, 0x45800000, v201
	v_cndmask_b32_e64 v186, v198, v182, s[2:3]
	v_cndmask_b32_e64 v192, v199, v183, s[50:51]
	v_cndmask_b32_e64 v194, v200, v184, s[88:89]
	v_cndmask_b32_e64 v196, v201, v185, s[90:91]
	v_pk_mul_f32 v[98:99], v[186:187], v[98:99] op_sel_hi:[0,1]
	v_pk_mul_f32 v[100:101], v[186:187], v[100:101] op_sel_hi:[0,1]
	v_pk_mul_f32 v[102:103], v[186:187], v[102:103] op_sel_hi:[0,1]
	v_pk_mul_f32 v[104:105], v[186:187], v[104:105] op_sel_hi:[0,1]
	v_pk_mul_f32 v[106:107], v[186:187], v[106:107] op_sel_hi:[0,1]
	v_pk_mul_f32 v[108:109], v[186:187], v[108:109] op_sel_hi:[0,1]
	v_pk_mul_f32 v[110:111], v[186:187], v[110:111] op_sel_hi:[0,1]
	v_pk_mul_f32 v[112:113], v[186:187], v[112:113] op_sel_hi:[0,1]
	v_pk_mul_f32 v[98:99], v[64:65], v[98:99]
	v_pk_mul_f32 v[100:101], v[66:67], v[100:101]
	v_pk_mul_f32 v[102:103], v[68:69], v[102:103]
	v_pk_mul_f32 v[104:105], v[70:71], v[104:105]
	v_pk_mul_f32 v[106:107], v[72:73], v[106:107]
	v_pk_mul_f32 v[108:109], v[74:75], v[108:109]
	v_pk_mul_f32 v[110:111], v[76:77], v[110:111]
	v_pk_mul_f32 v[112:113], v[78:79], v[112:113]
	v_pk_fma_f32 v[98:99], v[80:81], v[98:99], v[162:163]
	v_pk_fma_f32 v[100:101], v[82:83], v[100:101], v[164:165]
	v_pk_fma_f32 v[102:103], v[84:85], v[102:103], v[166:167]
	v_pk_fma_f32 v[104:105], v[86:87], v[104:105], v[168:169]
	v_pk_fma_f32 v[106:107], v[88:89], v[106:107], v[170:171]
	v_pk_fma_f32 v[108:109], v[90:91], v[108:109], v[172:173]
	v_pk_fma_f32 v[110:111], v[92:93], v[110:111], v[174:175]
	v_pk_fma_f32 v[112:113], v[94:95], v[112:113], v[176:177]
	v_cvt_pk_bf16_f32 v204, v98, v99
	v_cvt_pk_bf16_f32 v205, v100, v101
	v_cvt_pk_bf16_f32 v206, v102, v103
	v_cvt_pk_bf16_f32 v207, v104, v105
	v_cvt_pk_bf16_f32 v208, v106, v107
	v_cvt_pk_bf16_f32 v209, v108, v109
	v_cvt_pk_bf16_f32 v210, v110, v111
	v_cvt_pk_bf16_f32 v211, v112, v113
	global_store_dwordx4 v203, v[204:207], s[48:49] sc1
	global_store_dwordx4 v203, v[208:211], s[48:49] offset:1024 sc1
	s_add_u32 s48, s48, 0x800
	s_addc_u32 s49, s49, 0
	v_pk_mul_f32 v[114:115], v[192:193], v[114:115] op_sel_hi:[0,1]
	v_pk_mul_f32 v[116:117], v[192:193], v[116:117] op_sel_hi:[0,1]
	v_pk_mul_f32 v[118:119], v[192:193], v[118:119] op_sel_hi:[0,1]
	v_pk_mul_f32 v[120:121], v[192:193], v[120:121] op_sel_hi:[0,1]
	v_pk_mul_f32 v[122:123], v[192:193], v[122:123] op_sel_hi:[0,1]
	v_pk_mul_f32 v[124:125], v[192:193], v[124:125] op_sel_hi:[0,1]
	v_pk_mul_f32 v[126:127], v[192:193], v[126:127] op_sel_hi:[0,1]
	v_pk_mul_f32 v[128:129], v[192:193], v[128:129] op_sel_hi:[0,1]
	v_pk_mul_f32 v[114:115], v[64:65], v[114:115]
	v_pk_mul_f32 v[116:117], v[66:67], v[116:117]
	v_pk_mul_f32 v[118:119], v[68:69], v[118:119]
	v_pk_mul_f32 v[120:121], v[70:71], v[120:121]
	v_pk_mul_f32 v[122:123], v[72:73], v[122:123]
	v_pk_mul_f32 v[124:125], v[74:75], v[124:125]
	v_pk_mul_f32 v[126:127], v[76:77], v[126:127]
	v_pk_mul_f32 v[128:129], v[78:79], v[128:129]
	v_pk_fma_f32 v[114:115], v[80:81], v[114:115], v[162:163]
	v_pk_fma_f32 v[116:117], v[82:83], v[116:117], v[164:165]
	v_pk_fma_f32 v[118:119], v[84:85], v[118:119], v[166:167]
	v_pk_fma_f32 v[120:121], v[86:87], v[120:121], v[168:169]
	v_pk_fma_f32 v[122:123], v[88:89], v[122:123], v[170:171]
	v_pk_fma_f32 v[124:125], v[90:91], v[124:125], v[172:173]
	v_pk_fma_f32 v[126:127], v[92:93], v[126:127], v[174:175]
	v_pk_fma_f32 v[128:129], v[94:95], v[128:129], v[176:177]
	v_cvt_pk_bf16_f32 v212, v114, v115
	v_cvt_pk_bf16_f32 v213, v116, v117
	v_cvt_pk_bf16_f32 v214, v118, v119
	v_cvt_pk_bf16_f32 v215, v120, v121
	v_cvt_pk_bf16_f32 v216, v122, v123
	v_cvt_pk_bf16_f32 v217, v124, v125
	v_cvt_pk_bf16_f32 v218, v126, v127
	v_cvt_pk_bf16_f32 v219, v128, v129
	global_store_dwordx4 v203, v[212:215], s[48:49] sc1
	global_store_dwordx4 v203, v[216:219], s[48:49] offset:1024 sc1
	s_add_u32 s48, s48, 0x800
	s_addc_u32 s49, s49, 0
	v_pk_mul_f32 v[130:131], v[194:195], v[130:131] op_sel_hi:[0,1]
	v_pk_mul_f32 v[132:133], v[194:195], v[132:133] op_sel_hi:[0,1]
	v_pk_mul_f32 v[134:135], v[194:195], v[134:135] op_sel_hi:[0,1]
	v_pk_mul_f32 v[136:137], v[194:195], v[136:137] op_sel_hi:[0,1]
	v_pk_mul_f32 v[138:139], v[194:195], v[138:139] op_sel_hi:[0,1]
	v_pk_mul_f32 v[140:141], v[194:195], v[140:141] op_sel_hi:[0,1]
	v_pk_mul_f32 v[142:143], v[194:195], v[142:143] op_sel_hi:[0,1]
	v_pk_mul_f32 v[144:145], v[194:195], v[144:145] op_sel_hi:[0,1]
	v_pk_mul_f32 v[130:131], v[64:65], v[130:131]
	v_pk_mul_f32 v[132:133], v[66:67], v[132:133]
	v_pk_mul_f32 v[134:135], v[68:69], v[134:135]
	v_pk_mul_f32 v[136:137], v[70:71], v[136:137]
	v_pk_mul_f32 v[138:139], v[72:73], v[138:139]
	v_pk_mul_f32 v[140:141], v[74:75], v[140:141]
	v_pk_mul_f32 v[142:143], v[76:77], v[142:143]
	v_pk_mul_f32 v[144:145], v[78:79], v[144:145]
	v_pk_fma_f32 v[130:131], v[80:81], v[130:131], v[162:163]
	v_pk_fma_f32 v[132:133], v[82:83], v[132:133], v[164:165]
	v_pk_fma_f32 v[134:135], v[84:85], v[134:135], v[166:167]
	v_pk_fma_f32 v[136:137], v[86:87], v[136:137], v[168:169]
	v_pk_fma_f32 v[138:139], v[88:89], v[138:139], v[170:171]
	v_pk_fma_f32 v[140:141], v[90:91], v[140:141], v[172:173]
	v_pk_fma_f32 v[142:143], v[92:93], v[142:143], v[174:175]
	v_pk_fma_f32 v[144:145], v[94:95], v[144:145], v[176:177]
	v_cvt_pk_bf16_f32 v204, v130, v131
	v_cvt_pk_bf16_f32 v205, v132, v133
	v_cvt_pk_bf16_f32 v206, v134, v135
	v_cvt_pk_bf16_f32 v207, v136, v137
	v_cvt_pk_bf16_f32 v208, v138, v139
	v_cvt_pk_bf16_f32 v209, v140, v141
	v_cvt_pk_bf16_f32 v210, v142, v143
	v_cvt_pk_bf16_f32 v211, v144, v145
	global_store_dwordx4 v203, v[204:207], s[48:49] sc1
	global_store_dwordx4 v203, v[208:211], s[48:49] offset:1024 sc1
	s_add_u32 s48, s48, 0x800
	s_addc_u32 s49, s49, 0
	v_pk_mul_f32 v[146:147], v[196:197], v[146:147] op_sel_hi:[0,1]
	v_pk_mul_f32 v[148:149], v[196:197], v[148:149] op_sel_hi:[0,1]
	v_pk_mul_f32 v[150:151], v[196:197], v[150:151] op_sel_hi:[0,1]
	v_pk_mul_f32 v[152:153], v[196:197], v[152:153] op_sel_hi:[0,1]
	v_pk_mul_f32 v[154:155], v[196:197], v[154:155] op_sel_hi:[0,1]
	v_pk_mul_f32 v[156:157], v[196:197], v[156:157] op_sel_hi:[0,1]
	v_pk_mul_f32 v[158:159], v[196:197], v[158:159] op_sel_hi:[0,1]
	v_pk_mul_f32 v[160:161], v[196:197], v[160:161] op_sel_hi:[0,1]
	v_pk_mul_f32 v[146:147], v[64:65], v[146:147]
	v_pk_mul_f32 v[148:149], v[66:67], v[148:149]
	v_pk_mul_f32 v[150:151], v[68:69], v[150:151]
	v_pk_mul_f32 v[152:153], v[70:71], v[152:153]
	v_pk_mul_f32 v[154:155], v[72:73], v[154:155]
	v_pk_mul_f32 v[156:157], v[74:75], v[156:157]
	v_pk_mul_f32 v[158:159], v[76:77], v[158:159]
	v_pk_mul_f32 v[160:161], v[78:79], v[160:161]
	v_pk_fma_f32 v[146:147], v[80:81], v[146:147], v[162:163]
	v_pk_fma_f32 v[148:149], v[82:83], v[148:149], v[164:165]
	v_pk_fma_f32 v[150:151], v[84:85], v[150:151], v[166:167]
	v_pk_fma_f32 v[152:153], v[86:87], v[152:153], v[168:169]
	v_pk_fma_f32 v[154:155], v[88:89], v[154:155], v[170:171]
	v_pk_fma_f32 v[156:157], v[90:91], v[156:157], v[172:173]
	v_pk_fma_f32 v[158:159], v[92:93], v[158:159], v[174:175]
	v_pk_fma_f32 v[160:161], v[94:95], v[160:161], v[176:177]
	v_cvt_pk_bf16_f32 v212, v146, v147
	v_cvt_pk_bf16_f32 v213, v148, v149
	v_cvt_pk_bf16_f32 v214, v150, v151
	v_cvt_pk_bf16_f32 v215, v152, v153
	v_cvt_pk_bf16_f32 v216, v154, v155
	v_cvt_pk_bf16_f32 v217, v156, v157
	v_cvt_pk_bf16_f32 v218, v158, v159
	v_cvt_pk_bf16_f32 v219, v160, v161
	global_store_dwordx4 v203, v[212:215], s[48:49] sc1
	global_store_dwordx4 v203, v[216:219], s[48:49] offset:1024 sc1
	s_add_u32 s48, s48, 0x800
	s_addc_u32 s49, s49, 0
	s_nop 1
	s_branch .LBB0_460
.Lnrm_C_fallback:
	v_and_b32_e32 v0, 64, v227
	v_add_u32_e32 v0, 64, v0
	v_xor_b32_e32 v1, 1, v227
	v_lshlrev_b32_e32 v96, 4, v231
	v_cmp_lt_i32_e32 vcc, v1, v0
	v_lshl_add_u64 v[64:65], s[72:73], 0, v[96:97]
	v_readlane_b32 s2, v250, 2
	v_cndmask_b32_e32 v1, v227, v1, vcc
	v_lshlrev_b32_e32 v65, 2, v1
	v_xor_b32_e32 v1, 2, v227
	v_cmp_lt_i32_e32 vcc, v1, v0
	v_readlane_b32 s3, v250, 3
	s_load_dwordx2 s[2:3], s[2:3], 0x90
	v_cndmask_b32_e32 v1, v227, v1, vcc
	v_lshlrev_b32_e32 v75, 2, v1
	v_xor_b32_e32 v1, 4, v227
	v_cmp_lt_i32_e32 vcc, v1, v0
	s_waitcnt lgkmcnt(0)
	v_lshl_add_u64 v[66:67], s[2:3], 0, v[96:97]
	v_readlane_b32 s2, v250, 56
	v_cndmask_b32_e32 v1, v227, v1, vcc
	v_lshlrev_b32_e32 v80, 2, v1
	v_xor_b32_e32 v1, 8, v227
	v_cmp_lt_i32_e32 vcc, v1, v0
	v_readlane_b32 s3, v250, 57
	s_ashr_i32 s53, s52, 31
	v_cndmask_b32_e32 v1, v227, v1, vcc
	v_lshlrev_b32_e32 v81, 2, v1
	v_xor_b32_e32 v1, 16, v227
	v_lshl_add_u64 v[68:69], s[2:3], 0, v[96:97]
	v_readlane_b32 s2, v250, 58
	v_cmp_lt_i32_e32 vcc, v1, v0
	v_readlane_b32 s3, v250, 59
	s_nop 0
	v_cndmask_b32_e32 v1, v227, v1, vcc
	v_lshl_add_u64 v[70:71], s[2:3], 0, v[96:97]
	s_lshl_b64 s[2:3], s[52:53], 11
	v_lshlrev_b32_e32 v82, 2, v1
	v_xor_b32_e32 v1, 32, v227
	s_add_u32 s12, s40, s2
	v_cmp_lt_i32_e32 vcc, v1, v0
	s_addc_u32 s13, s41, s3
	s_lshl_b64 s[2:3], s[52:53], 12
	v_cndmask_b32_e32 v0, v227, v1, vcc
	s_add_u32 s2, s72, s2
	v_lshlrev_b32_e32 v83, 2, v0
	v_lshlrev_b32_e32 v0, 2, v231
	s_addc_u32 s3, s73, s3
	v_lshl_add_u64 v[72:73], s[2:3], 0, v[96:97]
	v_lshlrev_b32_e32 v96, 1, v0
